# mixer units (kv, ret x2, sgu) wave_mma sections: LDS fragment reads run 10 ahead in renamed registers, counted lgkmcnt waits
# baseline (speedup 1.0000x reference)
; #define LAS __attribute__((address_space(3)))
; __device__ __forceinline__ unsigned pk2(float lo, float hi) { return pg8::cvt_pk_bf16(lo, hi); }
; __device__ __forceinline__ float fexp2(float x) { return __builtin_amdgcn_exp2f(x); }
; __device__ __forceinline__ float ret_log2gamma(int h) { return log2f(1.f - exp2f(-5.f - (float)h)); }
; template <bool SC> __device__ __forceinline__ void stage_tr(LAS bfu* dst, const bfu* src, int pitch, int tid, float lg) {
; #pragma unroll
;     for (int i = 0; i < 4; ++i) { const int id = tid + NTHR * i, c = id & 127, ch = id >> 7; const v4u v = *(const v4u*)(src + (size_t)c * pitch + ch * 8);
;         const float sc = SC ? fexp2(lg * (float)(127 - c)) : 1.f;
; #pragma unroll
;         for (int j = 0; j < 4; ++j) { unsigned w = v[j];
;             if (SC) w = pk2(bflo(w) * sc, bfhi(w) * sc);
;             dst[(ch * 8 + 2 * j) * TS + c] = (bfu)(w & 0xffffu); dst[(ch * 8 + 2 * j + 1) * TS + c] = (bfu)(w >> 16); } }
; }
; __device__ __forceinline__ void kv_unit(LAS unsigned char* lds, const bfu* PROJ, float* KVT, int u) {
;     ...
;     const int bh = u >> 6, i = u & 63, b = bh / 6, h = bh % 6; const size_t row0 = (size_t)b * SEQ + (size_t)i * 128; const float lg = ret_log2gamma(h);
;     LAS bfu* Vt = (LAS bfu*)lds; LAS bfu* Kt = (LAS bfu*)(lds + TILE_B);
;     stage_tr<false>(Vt, PROJ + row0 * INW + C_RV + h * 128, INW, tid, 0.f);
;     stage_tr<true>(Kt, PROJ + row0 * INW + C_RK + h * 128, INW, tid, lg);
.LBB0_272:
	s_mov_b32 s22, 21
	s_ashr_i32 s23, s22, 31
	s_lshl_b64 s[22:23], s[22:23], 3
	s_add_u32 s22, s0, s22
	s_addc_u32 s23, s1, s23
	s_load_dwordx2 s[34:35], s[22:23], 0x0
	s_mov_b32 s22, 21
	s_ashr_i32 s23, s22, 31
	s_lshl_b64 s[22:23], s[22:23], 3
	s_add_u32 s22, s0, s22
	s_addc_u32 s23, s1, s23
	s_ashr_i32 s44, s40, 6
	s_load_dwordx2 s[46:47], s[22:23], 0x0
	s_mul_hi_i32 s22, s44, 0x2aaaaaab
	s_lshr_b32 s23, s22, 31
	s_add_i32 s22, s22, s23
	s_mul_i32 s23, s22, 6
	s_sub_i32 s41, s44, s23
	v_cvt_f32_i32_e32 v0, s41
	s_ashr_i32 s23, s22, 31
	s_lshl_b32 s45, s40, 7
	s_lshl_b64 s[22:23], s[22:23], 13
	v_sub_f32_e32 v0, 0xc0a00000, v0
	v_cmp_gt_f32_e32 vcc, s64, v0
	s_and_b32 s45, s45, 0x1f80
	s_or_b32 s22, s22, s45
	v_cndmask_b32_e32 v2, 0, v241, vcc
	v_add_f32_e32 v0, v0, v2
	v_exp_f32_e32 v0, v0
	s_and_b64 s[48:49], vcc, exec
	s_cselect_b32 s45, 0xffffffc0, 0
	s_mulk_i32 s23, 0x3200
	v_ldexp_f32 v0, v0, s45
	v_sub_f32_e32 v0, 1.0, v0
	v_cmp_gt_f32_e32 vcc, s52, v0
	s_and_b64 s[48:49], vcc, exec
	s_cselect_b32 s45, 32, 0
	v_ldexp_f32 v0, v0, s45
	s_mul_hi_u32 s45, s22, 0x3200
	s_add_i32 s45, s45, s23
	s_mulk_i32 s22, 0x3200
	v_log_f32_e32 v0, v0
	s_waitcnt lgkmcnt(0)
	s_add_u32 s34, s34, s22
	s_addc_u32 s35, s35, s45
	s_lshl_b32 s22, s41, 7
	v_mov_b32_e32 v8, v232
	s_ashr_i32 s23, s22, 31
	v_cndmask_b32_e32 v2, 0, v242, vcc
	s_lshl_b64 s[22:23], s[22:23], 1
	v_and_b32_e32 v4, 0x7f, v8
	v_sub_f32_e32 v17, v0, v2
	s_add_u32 s22, s34, s22
	v_mul_u32_u24_e32 v0, 0x1900, v4
	s_addc_u32 s23, s35, s23
	v_lshlrev_b32_e32 v0, 1, v0
	v_lshl_add_u64 v[2:3], s[22:23], 0, v[0:1]
	s_mov_b64 s[22:23], 0x1ce00000
	v_ashrrev_i32_e32 v0, 4, v8
	v_lshl_add_u64 v[14:15], v[2:3], 0, s[22:23]
	v_and_b32_e32 v2, -8, v0
	v_ashrrev_i32_e32 v3, 31, v2
	v_lshl_add_u64 v[18:19], v[2:3], 1, v[14:15]
	v_mul_lo_u32 v0, v2, s65
	v_lshlrev_b32_e32 v9, 1, v4
	global_load_dwordx4 v[50:53], v[18:19], off offset:3072
	v_add3_u32 v20, 0, v0, v9
	v_add_u32_e32 v0, 0x200, v8
	v_ashrrev_i32_e32 v0, 4, v0
	s_movk_i32 s22, 0x7f
	v_readfirstlane_b32 s20, v8
	s_ashr_i32 s20, s20, 2
	s_ashr_i32 s41, s40, 31
	v_and_b32_e32 v2, -8, v0
	v_ashrrev_i32_e32 v3, 31, v2
	v_lshl_add_u64 v[6:7], v[2:3], 1, v[14:15]
	v_mul_lo_u32 v0, v2, s65
	global_load_dwordx4 v[54:57], v[6:7], off offset:3072
	v_add3_u32 v21, 0, v0, v9
	v_add_u32_e32 v0, 0x400, v8
	v_ashrrev_i32_e32 v0, 4, v0
	v_and_b32_e32 v2, -8, v0
	v_ashrrev_i32_e32 v3, 31, v2
	v_lshl_add_u64 v[4:5], v[2:3], 1, v[14:15]
	global_load_dwordx4 v[58:61], v[4:5], off offset:3072
	v_mul_lo_u32 v0, v2, s65
	v_add3_u32 v22, 0, v0, v9
	v_add_u32_e32 v0, 0x600, v8
	v_ashrrev_i32_e32 v0, 4, v0
	v_and_b32_e32 v10, -8, v0
	v_ashrrev_i32_e32 v11, 31, v10
	v_lshl_add_u64 v[2:3], v[10:11], 1, v[14:15]
	v_mul_lo_u32 v0, v10, s65
	global_load_dwordx4 v[62:65], v[2:3], off offset:3072
	v_add3_u32 v9, 0, v0, v9
	v_bitop3_b32 v0, v8, s22, v8 bitop3:0xc
	v_cvt_f32_ubyte0_e32 v0, v0
	v_mul_f32_e32 v0, v17, v0
	v_exp_f32_e32 v0, v0
	v_bfi_b32 v17, -16, s20, v8
	s_mov_b32 s20, 0x30600000
	global_load_dwordx4 v[66:69], v[18:19], off offset:1536
	v_mov_b32_e32 v70, v0
	v_mov_b32_e32 v71, v1
	global_load_dwordx4 v[92:95], v[6:7], off offset:1536
	global_load_dwordx4 v[120:123], v[4:5], off offset:1536
	global_load_dwordx4 v[146:149], v[2:3], off offset:1536
	s_waitcnt vmcnt(7)
	ds_write_b16 v20, v50
	ds_write_b16_d16_hi v20, v50 offset:272
	ds_write_b16 v20, v51 offset:544
	ds_write_b16_d16_hi v20, v51 offset:816
	ds_write_b16 v20, v52 offset:1088
	ds_write_b16_d16_hi v20, v52 offset:1360
	ds_write_b16 v20, v53 offset:1632
	ds_write_b16_d16_hi v20, v53 offset:1904
	s_waitcnt vmcnt(6)
	ds_write_b16 v21, v54
	ds_write_b16_d16_hi v21, v54 offset:272
	ds_write_b16 v21, v55 offset:544
	ds_write_b16_d16_hi v21, v55 offset:816
	ds_write_b16 v21, v56 offset:1088
	ds_write_b16_d16_hi v21, v56 offset:1360
	ds_write_b16 v21, v57 offset:1632
	ds_write_b16_d16_hi v21, v57 offset:1904
	s_waitcnt vmcnt(5)
	ds_write_b16 v22, v58
	ds_write_b16_d16_hi v22, v58 offset:272
	ds_write_b16 v22, v59 offset:544
	ds_write_b16_d16_hi v22, v59 offset:816
	ds_write_b16 v22, v60 offset:1088
	ds_write_b16_d16_hi v22, v60 offset:1360
	ds_write_b16 v22, v61 offset:1632
	ds_write_b16_d16_hi v22, v61 offset:1904
	s_waitcnt vmcnt(4)
	ds_write_b16 v9, v62
	ds_write_b16_d16_hi v9, v62 offset:272
	ds_write_b16 v9, v63 offset:544
	ds_write_b16_d16_hi v9, v63 offset:816
	ds_write_b16 v9, v64 offset:1088
	ds_write_b16_d16_hi v9, v64 offset:1360
	ds_write_b16 v9, v65 offset:1632
	ds_write_b16_d16_hi v9, v65 offset:1904
	s_waitcnt vmcnt(3)
	v_lshlrev_b32_e32 v46, 16, v66
	v_and_b32_e32 v47, 0xffff0000, v66
	v_pk_mul_f32 v[72:73], v[70:71], v[46:47] op_sel_hi:[0,1]
	v_cvt_pk_bf16_f32 v49, v72, v73
	ds_write_b16 v20, v49 offset:34816
	ds_write_b16_d16_hi v20, v49 offset:35088
	v_lshlrev_b32_e32 v74, 16, v67
	v_and_b32_e32 v75, 0xffff0000, v67
	v_pk_mul_f32 v[76:77], v[70:71], v[74:75] op_sel_hi:[0,1]
	v_cvt_pk_bf16_f32 v78, v76, v77
	ds_write_b16 v20, v78 offset:35360
	ds_write_b16_d16_hi v20, v78 offset:35632
	v_lshlrev_b32_e32 v80, 16, v68
	v_and_b32_e32 v81, 0xffff0000, v68
	v_pk_mul_f32 v[82:83], v[70:71], v[80:81] op_sel_hi:[0,1]
	v_cvt_pk_bf16_f32 v79, v82, v83
	ds_write_b16 v20, v79 offset:35904
	ds_write_b16_d16_hi v20, v79 offset:36176
	v_lshlrev_b32_e32 v84, 16, v69
	v_and_b32_e32 v85, 0xffff0000, v69
	v_pk_mul_f32 v[86:87], v[70:71], v[84:85] op_sel_hi:[0,1]
	v_cvt_pk_bf16_f32 v88, v86, v87
	ds_write_b16 v20, v88 offset:36448
	ds_write_b16_d16_hi v20, v88 offset:36720
	s_waitcnt vmcnt(2)
; #define LAS __attribute__((address_space(3)))
; __device__ __forceinline__ unsigned pk2(float lo, float hi) { return pg8::cvt_pk_bf16(lo, hi); }
; __device__ __forceinline__ float fexp2(float x) { return __builtin_amdgcn_exp2f(x); }
; #define ZERO8(a) do { _Pragma("unroll") for (int t_ = 0; t_ < 8; ++t_) a[t_] = (f32x4){0.f, 0.f, 0.f, 0.f}; } while (0)
; template <bool SC> __device__ __forceinline__ void stage_tr(LAS bfu* dst, const bfu* src, int pitch, int tid, float lg) {
; #pragma unroll
;     for (int i = 0; i < 4; ++i) { const int id = tid + NTHR * i, c = id & 127, ch = id >> 7; const v4u v = *(const v4u*)(src + (size_t)c * pitch + ch * 8);
;         const float sc = SC ? fexp2(lg * (float)(127 - c)) : 1.f;
; #pragma unroll
;         for (int j = 0; j < 4; ++j) { unsigned w = v[j];
;             if (SC) w = pk2(bflo(w) * sc, bfhi(w) * sc);
;             dst[(ch * 8 + 2 * j) * TS + c] = (bfu)(w & 0xffffu); dst[(ch * 8 + 2 * j + 1) * TS + c] = (bfu)(w >> 16); } }
; }
; __device__ __forceinline__ void kv_unit(LAS unsigned char* lds, const bfu* PROJ, float* KVT, int u) {
;     ...
;     __syncthreads();
;     const int fr = lane & 15, fq = lane >> 4, m0 = wid * 16; f32x4 acc[8]; ZERO8(acc);
	v_lshlrev_b32_e32 v96, 16, v92
	v_and_b32_e32 v97, 0xffff0000, v92
	v_pk_mul_f32 v[98:99], v[70:71], v[96:97] op_sel_hi:[0,1]
	v_cvt_pk_bf16_f32 v100, v98, v99
	ds_write_b16 v21, v100 offset:34816
	ds_write_b16_d16_hi v21, v100 offset:35088
	v_lshlrev_b32_e32 v102, 16, v93
	v_and_b32_e32 v103, 0xffff0000, v93
	v_pk_mul_f32 v[104:105], v[70:71], v[102:103] op_sel_hi:[0,1]
	v_cvt_pk_bf16_f32 v101, v104, v105
	ds_write_b16 v21, v101 offset:35360
	ds_write_b16_d16_hi v21, v101 offset:35632
	v_lshlrev_b32_e32 v106, 16, v94
	v_and_b32_e32 v107, 0xffff0000, v94
	v_pk_mul_f32 v[108:109], v[70:71], v[106:107] op_sel_hi:[0,1]
	v_cvt_pk_bf16_f32 v110, v108, v109
	ds_write_b16 v21, v110 offset:35904
	ds_write_b16_d16_hi v21, v110 offset:36176
	v_lshlrev_b32_e32 v112, 16, v95
	v_and_b32_e32 v113, 0xffff0000, v95
	v_pk_mul_f32 v[114:115], v[70:71], v[112:113] op_sel_hi:[0,1]
	v_cvt_pk_bf16_f32 v118, v114, v115
	ds_write_b16 v21, v118 offset:36448
	ds_write_b16_d16_hi v21, v118 offset:36720
	s_waitcnt vmcnt(1)
	v_lshlrev_b32_e32 v124, 16, v120
	v_and_b32_e32 v125, 0xffff0000, v120
	v_pk_mul_f32 v[126:127], v[70:71], v[124:125] op_sel_hi:[0,1]
	v_cvt_pk_bf16_f32 v116, v126, v127
	ds_write_b16 v22, v116 offset:34816
	ds_write_b16_d16_hi v22, v116 offset:35088
	v_lshlrev_b32_e32 v128, 16, v121
	v_and_b32_e32 v129, 0xffff0000, v121
	v_pk_mul_f32 v[130:131], v[70:71], v[128:129] op_sel_hi:[0,1]
	v_cvt_pk_bf16_f32 v111, v130, v131
	ds_write_b16 v22, v111 offset:35360
	ds_write_b16_d16_hi v22, v111 offset:35632
	v_lshlrev_b32_e32 v132, 16, v122
	v_and_b32_e32 v133, 0xffff0000, v122
	v_pk_mul_f32 v[134:135], v[70:71], v[132:133] op_sel_hi:[0,1]
	v_cvt_pk_bf16_f32 v136, v134, v135
	ds_write_b16 v22, v136 offset:35904
	ds_write_b16_d16_hi v22, v136 offset:36176
	v_lshlrev_b32_e32 v138, 16, v123
	v_and_b32_e32 v139, 0xffff0000, v123
	v_pk_mul_f32 v[140:141], v[70:71], v[138:139] op_sel_hi:[0,1]
	v_cvt_pk_bf16_f32 v144, v140, v141
	ds_write_b16 v22, v144 offset:36448
	ds_write_b16_d16_hi v22, v144 offset:36720
	s_waitcnt vmcnt(0)
	v_lshlrev_b32_e32 v150, 16, v146
	v_and_b32_e32 v151, 0xffff0000, v146
	v_pk_mul_f32 v[152:153], v[70:71], v[150:151] op_sel_hi:[0,1]
	v_cvt_pk_bf16_f32 v142, v152, v153
	ds_write_b16 v9, v142 offset:34816
	ds_write_b16_d16_hi v9, v142 offset:35088
	v_lshlrev_b32_e32 v154, 16, v147
	v_and_b32_e32 v155, 0xffff0000, v147
	v_pk_mul_f32 v[156:157], v[70:71], v[154:155] op_sel_hi:[0,1]
	v_cvt_pk_bf16_f32 v137, v156, v157
	ds_write_b16 v9, v137 offset:35360
	ds_write_b16_d16_hi v9, v137 offset:35632
	v_lshlrev_b32_e32 v158, 16, v148
	v_and_b32_e32 v159, 0xffff0000, v148
	v_pk_mul_f32 v[160:161], v[70:71], v[158:159] op_sel_hi:[0,1]
	v_cvt_pk_bf16_f32 v162, v160, v161
	ds_write_b16 v9, v162 offset:35904
	ds_write_b16_d16_hi v9, v162 offset:36176
	v_lshlrev_b32_e32 v164, 16, v149
	v_and_b32_e32 v165, 0xffff0000, v149
	v_pk_mul_f32 v[166:167], v[70:71], v[164:165] op_sel_hi:[0,1]
	v_cvt_pk_bf16_f32 v163, v166, v167
	ds_write_b16 v9, v163 offset:36448
	ds_write_b16_d16_hi v9, v163 offset:36720
	v_and_b32_e32 v0, 48, v8
	v_and_b32_e32 v9, 15, v8
	v_add_u32_e32 v8, 0, v0
	v_mad_u64_u32 v[2:3], s[22:23], v17, s65, v[8:9]
	v_mad_u32_u24 v3, v9, s65, v8
	s_waitcnt lgkmcnt(0)
	s_barrier
; #define LAS __attribute__((address_space(3)))
; #define ZERO8(a) do { _Pragma("unroll") for (int t_ = 0; t_ < 8; ++t_) a[t_] = (f32x4){0.f, 0.f, 0.f, 0.f}; } while (0)
; __device__ __forceinline__ void st_sc1_x4(float* p, f32x4 v) { st_sc1_u2(p, __float_as_uint(v[0]), __float_as_uint(v[1])); st_sc1_u2(p + 2, __float_as_uint(v[2]), __float_as_uint(v[3])); }
; __device__ __forceinline__ void wave_mma(f32x4 (&acc)[8], const LAS bfu* As, const LAS bfu* Bs, int m0, int fr, int fq) {
; #pragma unroll
;     for (int ks = 0; ks < 4; ++ks) { const bf16x8 a = *(const LAS bf16x8*)(As + (m0 + fr) * TS + ks * 32 + fq * 8);
; #pragma unroll
;         for (int t = 0; t < 8; ++t) { const bf16x8 b = *(const LAS bf16x8*)(Bs + (t * 16 + fr) * TS + ks * 32 + fq * 8); acc[t] = __builtin_amdgcn_mfma_f32_16x16x32_bf16(b, a, acc[t], 0, 0, 0); } }
; }
; __device__ __forceinline__ void kv_unit(LAS unsigned char* lds, const bfu* PROJ, float* KVT, int u) {
;     ...
;     const int fr = lane & 15, fq = lane >> 4, m0 = wid * 16; f32x4 acc[8]; ZERO8(acc);
;     wave_mma(acc, Vt, Kt, m0, fr, fq);
;     float* o = KVT + (size_t)u * 16384 + (m0 + fr) * 128 + 4 * fq;
; #pragma unroll
;     for (int t = 0; t < 8; ++t) st_sc1_x4(o + 16 * t, acc[t]);
	s_waitcnt lgkmcnt(0)
	ds_read_b128 v[52:55], v2
	ds_read_b128 v[56:59], v3 offset:34816
	ds_read_b128 v[60:63], v3 offset:39168
	ds_read_b128 v[64:67], v3 offset:43520
	ds_read_b128 v[68:71], v3 offset:47872
	ds_read_b128 v[72:75], v3 offset:52224
	ds_read_b128 v[76:79], v3 offset:56576
	ds_read_b128 v[80:83], v3 offset:60928
	ds_read_b128 v[84:87], v3 offset:65280
	ds_read_b128 v[88:91], v2 offset:64
	ds_read_b128 v[92:95], v3 offset:34880
	ds_read_b128 v[96:99], v3 offset:39232
	s_waitcnt lgkmcnt(10)
	v_mfma_f32_16x16x32_bf16 v[8:11], v[56:59], v[52:55], 0
	s_lshl_b64 s[22:23], s[40:41], 16
	s_add_u32 s22, s46, s22
	s_addc_u32 s23, s47, s23
	ds_read_b128 v[56:59], v3 offset:43584
	s_waitcnt lgkmcnt(10)
	v_mfma_f32_16x16x32_bf16 v[12:15], v[60:63], v[52:55], 0
	ds_read_b128 v[60:63], v3 offset:47936
	s_waitcnt lgkmcnt(10)
	v_mfma_f32_16x16x32_bf16 v[18:21], v[64:67], v[52:55], 0
	ds_read_b128 v[64:67], v3 offset:52288
	s_waitcnt lgkmcnt(10)
	v_mfma_f32_16x16x32_bf16 v[22:25], v[68:71], v[52:55], 0
	ds_read_b128 v[68:71], v3 offset:56640
	s_waitcnt lgkmcnt(10)
	v_mfma_f32_16x16x32_bf16 v[26:29], v[72:75], v[52:55], 0
	ds_read_b128 v[72:75], v3 offset:60992
	s_waitcnt lgkmcnt(10)
	v_mfma_f32_16x16x32_bf16 v[30:33], v[76:79], v[52:55], 0
	ds_read_b128 v[76:79], v3 offset:65344
	s_waitcnt lgkmcnt(10)
	v_mfma_f32_16x16x32_bf16 v[34:37], v[80:83], v[52:55], 0
	ds_read_b128 v[80:83], v2 offset:128
	s_waitcnt lgkmcnt(10)
	v_mfma_f32_16x16x32_bf16 v[4:7], v[84:87], v[52:55], 0
	ds_read_b128 v[52:55], v3 offset:34944
	ds_read_b128 v[84:87], v3 offset:39296
	s_waitcnt lgkmcnt(10)
	v_mfma_f32_16x16x32_bf16 v[8:11], v[92:95], v[88:91], v[8:11]
	ds_read_b128 v[92:95], v3 offset:43648
	s_waitcnt lgkmcnt(10)
	v_mfma_f32_16x16x32_bf16 v[12:15], v[96:99], v[88:91], v[12:15]
	ds_read_b128 v[96:99], v3 offset:48000
	s_waitcnt lgkmcnt(10)
	v_mfma_f32_16x16x32_bf16 v[18:21], v[56:59], v[88:91], v[18:21]
	ds_read_b128 v[56:59], v3 offset:52352
	s_waitcnt lgkmcnt(10)
	v_mfma_f32_16x16x32_bf16 v[22:25], v[60:63], v[88:91], v[22:25]
	ds_read_b128 v[60:63], v3 offset:56704
	s_waitcnt lgkmcnt(10)
	v_mfma_f32_16x16x32_bf16 v[26:29], v[64:67], v[88:91], v[26:29]
	ds_read_b128 v[64:67], v3 offset:61056
	s_waitcnt lgkmcnt(10)
	v_mfma_f32_16x16x32_bf16 v[30:33], v[68:71], v[88:91], v[30:33]
	ds_read_b128 v[68:71], v3 offset:65408
	s_waitcnt lgkmcnt(10)
	v_mfma_f32_16x16x32_bf16 v[34:37], v[72:75], v[88:91], v[34:37]
	ds_read_b128 v[72:75], v2 offset:192
	s_waitcnt lgkmcnt(10)
	v_mfma_f32_16x16x32_bf16 v[4:7], v[76:79], v[88:91], v[4:7]
	ds_read_b128 v[76:79], v3 offset:35008
	ds_read_b128 v[88:91], v3 offset:39360
	s_waitcnt lgkmcnt(10)
	v_mfma_f32_16x16x32_bf16 v[8:11], v[52:55], v[80:83], v[8:11]
	ds_read_b128 v[52:55], v3 offset:43712
	s_waitcnt lgkmcnt(10)
	v_mfma_f32_16x16x32_bf16 v[12:15], v[84:87], v[80:83], v[12:15]
	ds_read_b128 v[84:87], v3 offset:48064
	s_waitcnt lgkmcnt(10)
	v_mfma_f32_16x16x32_bf16 v[18:21], v[92:95], v[80:83], v[18:21]
	ds_read_b128 v[92:95], v3 offset:52416
	s_waitcnt lgkmcnt(10)
	v_mfma_f32_16x16x32_bf16 v[22:25], v[96:99], v[80:83], v[22:25]
	ds_read_b128 v[96:99], v3 offset:56768
	s_waitcnt lgkmcnt(10)
	v_mfma_f32_16x16x32_bf16 v[26:29], v[56:59], v[80:83], v[26:29]
	ds_read_b128 v[56:59], v3 offset:61120
	s_waitcnt lgkmcnt(10)
	v_mfma_f32_16x16x32_bf16 v[30:33], v[60:63], v[80:83], v[30:33]
	ds_read_b128 v[60:63], v3 offset:65472
	s_waitcnt lgkmcnt(10)
	v_mfma_f32_16x16x32_bf16 v[34:37], v[64:67], v[80:83], v[34:37]
	s_waitcnt lgkmcnt(9)
	v_mfma_f32_16x16x32_bf16 v[4:7], v[68:71], v[80:83], v[4:7]
	s_waitcnt lgkmcnt(7)
	v_mfma_f32_16x16x32_bf16 v[8:11], v[76:79], v[72:75], v[8:11]
	s_waitcnt lgkmcnt(6)
	v_mfma_f32_16x16x32_bf16 v[12:15], v[88:91], v[72:75], v[12:15]
	s_waitcnt lgkmcnt(5)
	v_mfma_f32_16x16x32_bf16 v[18:21], v[52:55], v[72:75], v[18:21]
	s_waitcnt lgkmcnt(4)
	v_mfma_f32_16x16x32_bf16 v[22:25], v[84:87], v[72:75], v[22:25]
	s_waitcnt lgkmcnt(3)
	v_mfma_f32_16x16x32_bf16 v[26:29], v[92:95], v[72:75], v[26:29]
	s_waitcnt lgkmcnt(2)
	v_mfma_f32_16x16x32_bf16 v[30:33], v[96:99], v[72:75], v[30:33]
	s_waitcnt lgkmcnt(1)
	v_mfma_f32_16x16x32_bf16 v[34:37], v[56:59], v[72:75], v[34:37]
	s_waitcnt lgkmcnt(0)
	v_mfma_f32_16x16x32_bf16 v[2:5], v[60:63], v[72:75], v[4:7]
	s_nop 2
	s_waitcnt lgkmcnt(0)
	v_lshlrev_b32_e32 v6, 7, v17
	v_ashrrev_i32_e32 v7, 31, v6
	v_lshl_add_u64 v[6:7], v[6:7], 2, s[22:23]
	v_lshl_add_u64 v[6:7], v[6:7], 0, v[0:1]
	s_mov_b64 s[22:23], 0x30600000
	v_lshl_add_u64 v[38:39], v[6:7], 0, s[22:23]
	v_add_co_u32_e32 v6, vcc, s20, v6
	s_nop 1
	v_addc_co_u32_e32 v7, vcc, 0, v7, vcc
	global_store_dwordx4 v[38:39], v[8:11], off sc1
	global_store_dwordx4 v[38:39], v[12:15], off offset:64 sc1
	global_store_dwordx4 v[38:39], v[18:21], off offset:128 sc1
	global_store_dwordx4 v[38:39], v[22:25], off offset:192 sc1
	global_store_dwordx4 v[38:39], v[26:29], off offset:256 sc1
	global_store_dwordx4 v[38:39], v[30:33], off offset:320 sc1
	global_store_dwordx4 v[38:39], v[34:37], off offset:384 sc1
	global_store_dwordx4 v[38:39], v[2:5], off offset:448 sc1
	s_waitcnt vmcnt(0)
	s_barrier
	s_and_saveexec_b64 s[40:41], s[74:75]
	s_ashr_i32 s45, s44, 31
	s_lshl_b64 s[22:23], s[44:45], 2
	s_add_u32 s20, s4, s22
	s_addc_u32 s22, s5, s23
	s_add_u32 s34, s20, 0x200
	s_addc_u32 s35, s22, 0
	s_or_b64 s[42:43], s[42:43], exec
	s_or_b64 exec, exec, s[40:41]

; #define LAS __attribute__((address_space(3)))
; __device__ __forceinline__ float ret_log2gamma(int h) { return log2f(1.f - exp2f(-5.f - (float)h)); }
; __device__ __forceinline__ void ret_unit(LAS unsigned char* lds, const bfu* PROJ, const bfu* RT, const float* gn_g, bfu* CAT, int u) {
;     int tid = threadIdx.x; asm volatile("" : "+v"(tid)); const int lane = tid & 63, wid = __builtin_amdgcn_readfirstlane(tid >> 6); (void)lane; (void)wid;
;     const int bh = u >> 6, i = u & 63, b = bh / 6, h = bh % 6; const size_t row0 = (size_t)b * SEQ + (size_t)i * 128; const float lg = ret_log2gamma(h);
;     LAS bfu* Qs = (LAS bfu*)lds; LAS bfu* Ks = (LAS bfu*)(lds + TILE_B); LAS bfu* Vt = (LAS bfu*)(lds + 2 * TILE_B); LAS bfu* Rt = (LAS bfu*)(lds + 3 * TILE_B);
;     const bfu* P0 = PROJ + row0 * INW + h * 128;
;     stage_nat(Qs, P0 + C_RQ, INW, tid); stage_nat(Ks, P0 + C_RK, INW, tid); stage_tr<false>(Vt, P0 + C_RV, INW, tid, 0.f); stage_nat(Rt, RT + (size_t)u * 16384, 128, tid);
.LBB0_410:
	s_or_b64 exec, exec, s[40:41]
	s_mov_b32 s22, 21
	s_barrier
	s_ashr_i32 s23, s22, 31
	s_lshl_b64 s[22:23], s[22:23], 3
	s_add_u32 s22, s0, s22
	s_addc_u32 s23, s1, s23
	s_load_dwordx2 s[48:49], s[22:23], 0x0
	s_mov_b32 s22, 21
	s_ashr_i32 s23, s22, 31
	s_lshl_b64 s[22:23], s[22:23], 3
	s_add_u32 s22, s0, s22
	s_addc_u32 s23, s1, s23
	s_load_dwordx2 s[40:41], s[22:23], 0x0
	s_mov_b32 s22, 3
	s_ashr_i32 s23, s22, 31
	s_lshl_b64 s[22:23], s[22:23], 3
	s_add_u32 s22, s0, s22
	s_addc_u32 s23, s1, s23
	s_load_dwordx2 s[22:23], s[22:23], 0x0
	v_mov_b32_e32 v10, v232
	v_readlane_b32 s91, v255, 54
	s_waitcnt lgkmcnt(0)
	s_add_u32 s20, s22, s36
	s_mov_b32 s22, 21
	s_addc_u32 s35, s23, s37
	s_ashr_i32 s23, s22, 31
	s_lshl_b64 s[22:23], s[22:23], 3
	s_add_u32 s22, s0, s22
	s_addc_u32 s23, s1, s23
	s_load_dwordx2 s[44:45], s[22:23], 0x0
	s_mul_hi_i32 s23, s34, 0x2aaaaaab
	s_lshr_b32 s46, s23, 31
	s_add_i32 s46, s23, s46
	s_mul_i32 s23, s46, 6
	s_sub_i32 s23, s34, s23
	v_cvt_f32_i32_e32 v0, s23
	s_ashr_i32 s47, s46, 31
	s_lshl_b32 s34, s92, 7
	s_lshl_b64 s[46:47], s[46:47], 13
	v_sub_f32_e32 v0, 0xc0a00000, v0
	v_cmp_gt_f32_e32 vcc, s64, v0
	s_and_b32 s34, s34, 0x1f80
	s_or_b32 s46, s46, s34
	v_cndmask_b32_e32 v2, 0, v241, vcc
	v_add_f32_e32 v0, v0, v2
	v_exp_f32_e32 v0, v0
	s_and_b64 s[50:51], vcc, exec
	s_cselect_b32 s34, 0xffffffc0, 0
	s_mul_hi_u32 s50, s46, 0x3200
	v_ldexp_f32 v0, v0, s34
	s_mul_i32 s34, s47, 0x3200
	s_add_i32 s50, s50, s34
	s_mul_i32 s34, s46, 0x3200
	s_add_u32 s34, s48, s34
	s_addc_u32 s48, s49, s50
	s_lshl_b32 s50, s23, 7
	s_ashr_i32 s51, s50, 31
	s_lshl_b64 s[52:53], s[50:51], 1
	s_add_u32 s23, s34, s52
	s_addc_u32 s34, s48, s53
	v_sub_f32_e32 v11, 1.0, v0
	s_add_u32 s56, s23, 0x1ce00000
	v_lshlrev_b32_e32 v0, 4, v10
	s_addc_u32 s57, s34, 0
	v_and_b32_e32 v0, 0xf0, v0
	v_lshl_add_u64 v[16:17], s[56:57], 0, v[0:1]
	v_ashrrev_i32_e32 v2, 4, v10
	v_mad_i64_i32 v[18:19], s[48:49], v2, s61, v[16:17]
	global_load_dwordx4 v[120:123], v[18:19], off
	v_add_u32_e32 v26, 0, v0
	v_mul_lo_u32 v27, v2, s65
	v_add_u32_e32 v28, v26, v27
	s_ashr_i32 s93, s92, 31
	v_ashrrev_i32_e32 v3, 31, v2
	v_readfirstlane_b32 s22, v10
	v_bfe_u32 v71, v10, 4, 2
	v_lshlrev_b32_e32 v69, 4, v71
	v_add_u32_e32 v4, 0x200, v10
	v_ashrrev_i32_e32 v4, 4, v4
	v_mad_i64_i32 v[20:21], s[48:49], v4, s61, v[16:17]
	global_load_dwordx4 v[124:127], v[20:21], off
	v_mul_lo_u32 v29, v4, s65
	v_add_u32_e32 v30, v26, v29
	v_ashrrev_i32_e32 v5, 31, v4
	v_add_u32_e32 v6, 0x400, v10
	v_ashrrev_i32_e32 v6, 4, v6
	v_mad_i64_i32 v[22:23], s[48:49], v6, s61, v[16:17]
	global_load_dwordx4 v[128:131], v[22:23], off
	v_add_u32_e32 v8, 0x600, v10
	v_mul_lo_u32 v31, v6, s65
	v_ashrrev_i32_e32 v8, 4, v8
	v_add_u32_e32 v32, v26, v31
	v_mad_i64_i32 v[24:25], s[48:49], v8, s61, v[16:17]
	s_lshl_b64 s[48:49], s[92:93], 15
	s_add_u32 s40, s40, s48
	s_addc_u32 s41, s41, s49
	v_ashrrev_i32_e32 v7, 31, v6
	v_ashrrev_i32_e32 v9, 31, v8
	s_ashr_i32 s34, s22, 2
	s_mov_b32 s22, 0x800000
	v_cmp_gt_f32_e32 vcc, s22, v11
	s_and_b64 s[22:23], vcc, exec
	s_cselect_b32 s22, 32, 0
	v_bfi_b32 v66, -16, s34, v10
	global_load_dwordx4 v[132:135], v[24:25], off
	v_mul_lo_u32 v12, v8, s65
	v_add_u32_e32 v13, v26, v12
	v_mov_b32_e32 v119, v13
	global_load_dwordx4 v[136:139], v[18:19], off offset:1536
	global_load_dwordx4 v[140:143], v[20:21], off offset:1536
	global_load_dwordx4 v[144:147], v[22:23], off offset:1536
	global_load_dwordx4 v[148:151], v[24:25], off offset:1536
	v_and_b32_e32 v13, 0x7f, v10
	v_mul_u32_u24_e32 v14, 0x1900, v13
	v_lshlrev_b32_e32 v14, 1, v14
	v_mov_b32_e32 v15, v1
	v_lshl_add_u64 v[18:19], s[56:57], 0, v[14:15]
	v_and_b32_e32 v14, -8, v2
	v_ashrrev_i32_e32 v15, 31, v14
	v_lshl_add_u64 v[16:17], v[14:15], 1, v[18:19]
	v_mul_lo_u32 v14, v14, s65
	v_lshlrev_b32_e32 v13, 1, v13
	v_add3_u32 v20, s70, v14, v13
	global_load_dwordx4 v[152:155], v[16:17], off offset:3072
	v_lshlrev_b64 v[2:3], 8, v[2:3]
	v_mov_b32_e32 v156, v20
	v_and_b32_e32 v14, -8, v4
	v_ashrrev_i32_e32 v15, 31, v14
	v_lshl_add_u64 v[16:17], v[14:15], 1, v[18:19]
	v_mul_lo_u32 v14, v14, s65
	v_add3_u32 v20, s70, v14, v13
	global_load_dwordx4 v[158:161], v[16:17], off offset:3072
	v_mov_b32_e32 v157, v20
	v_and_b32_e32 v14, -8, v6
	v_ashrrev_i32_e32 v15, 31, v14
	v_lshl_add_u64 v[16:17], v[14:15], 1, v[18:19]
	v_mul_lo_u32 v14, v14, s65
	v_add3_u32 v20, s70, v14, v13
	global_load_dwordx4 v[162:165], v[16:17], off offset:3072
	v_and_b32_e32 v14, -8, v8
	v_ashrrev_i32_e32 v15, 31, v14
	v_lshl_add_u64 v[16:17], v[14:15], 1, v[18:19]
	v_mul_lo_u32 v14, v14, s65
	v_add3_u32 v13, s70, v14, v13
	global_load_dwordx4 v[166:169], v[16:17], off offset:3072
	v_mov_b32_e32 v170, v13
	v_lshl_add_u64 v[14:15], s[40:41], 0, v[0:1]
	s_mov_b64 s[40:41], 0x33600000
	v_lshl_add_u64 v[18:19], v[14:15], 0, s[40:41]
	v_lshl_add_u64 v[2:3], v[18:19], 0, v[2:3]
	global_load_dwordx4 v[172:175], v[2:3], off
	v_readlane_b32 s40, v255, 29
	s_nop 1
	v_add_u32_e32 v0, s40, v0
	v_add_u32_e32 v2, v0, v27
	v_add_u32_e32 v13, v0, v29
	v_mov_b32_e32 v171, v2
	v_lshlrev_b64 v[2:3], 8, v[4:5]
	v_lshl_add_u64 v[2:3], v[18:19], 0, v[2:3]
	global_load_dwordx4 v[176:179], v[2:3], off
	v_lshlrev_b64 v[2:3], 8, v[6:7]
	v_lshl_add_u64 v[2:3], v[18:19], 0, v[2:3]
	global_load_dwordx4 v[180:183], v[2:3], off
	v_add_u32_e32 v6, v0, v31
	v_add_u32_e32 v0, v0, v12
	v_lshlrev_b64 v[2:3], 8, v[8:9]
	v_lshl_add_u64 v[2:3], v[18:19], 0, v[2:3]
	global_load_dwordx4 v[184:187], v[2:3], off
	s_waitcnt vmcnt(15)
	ds_write_b128 v28, v[120:123]
	s_waitcnt vmcnt(14)
	ds_write_b128 v30, v[124:127]
	s_waitcnt vmcnt(13)
	ds_write_b128 v32, v[128:131]
	s_waitcnt vmcnt(12)
; #define ZERO8(a) do { _Pragma("unroll") for (int t_ = 0; t_ < 8; ++t_) a[t_] = (f32x4){0.f, 0.f, 0.f, 0.f}; } while (0)
; __device__ __forceinline__ void ret_unit(LAS unsigned char* lds, const bfu* PROJ, const bfu* RT, const float* gn_g, bfu* CAT, int u) {
;     ...
;     stage_nat(Qs, P0 + C_RQ, INW, tid); stage_nat(Ks, P0 + C_RK, INW, tid); stage_tr<false>(Vt, P0 + C_RV, INW, tid, 0.f); stage_nat(Rt, RT + (size_t)u * 16384, 128, tid);
;     __syncthreads();
;     const int fr = lane & 15, fq = lane >> 4, m0 = wid * 16, c = m0 + fr;
;     f32x4 acc[8], cr[8]; ZERO8(acc); ZERO8(cr);
;     wave_mma(cr, Qs, Rt, m0, fr, fq);
;     wave_mma(acc, Qs, Ks, m0, fr, fq);
	ds_write_b128 v119, v[132:135]
	s_waitcnt vmcnt(11)
	ds_write_b128 v28, v[136:139] offset:34816
	s_waitcnt vmcnt(10)
	ds_write_b128 v30, v[140:143] offset:34816
	s_waitcnt vmcnt(9)
	ds_write_b128 v32, v[144:147] offset:34816
	s_waitcnt vmcnt(8)
	ds_write_b128 v119, v[148:151] offset:34816
	s_waitcnt vmcnt(7)
	ds_write_b16 v156, v152
	ds_write_b16_d16_hi v156, v152 offset:272
	ds_write_b16 v156, v153 offset:544
	ds_write_b16_d16_hi v156, v153 offset:816
	ds_write_b16 v156, v154 offset:1088
	ds_write_b16_d16_hi v156, v154 offset:1360
	ds_write_b16 v156, v155 offset:1632
	ds_write_b16_d16_hi v156, v155 offset:1904
	s_waitcnt vmcnt(6)
	ds_write_b16 v157, v158
	ds_write_b16_d16_hi v157, v158 offset:272
	ds_write_b16 v157, v159 offset:544
	ds_write_b16_d16_hi v157, v159 offset:816
	ds_write_b16 v157, v160 offset:1088
	ds_write_b16_d16_hi v157, v160 offset:1360
	ds_write_b16 v157, v161 offset:1632
	ds_write_b16_d16_hi v157, v161 offset:1904
	s_waitcnt vmcnt(5)
	ds_write_b16 v20, v162
	ds_write_b16_d16_hi v20, v162 offset:272
	ds_write_b16 v20, v163 offset:544
	ds_write_b16_d16_hi v20, v163 offset:816
	ds_write_b16 v20, v164 offset:1088
	ds_write_b16_d16_hi v20, v164 offset:1360
	ds_write_b16 v20, v165 offset:1632
	ds_write_b16_d16_hi v20, v165 offset:1904
	s_waitcnt vmcnt(4)
	ds_write_b16 v170, v166
	ds_write_b16_d16_hi v170, v166 offset:272
	ds_write_b16 v170, v167 offset:544
	ds_write_b16_d16_hi v170, v167 offset:816
	ds_write_b16 v170, v168 offset:1088
	ds_write_b16_d16_hi v170, v168 offset:1360
	ds_write_b16 v170, v169 offset:1632
	ds_write_b16_d16_hi v170, v169 offset:1904
	s_waitcnt vmcnt(3)
	ds_write_b128 v171, v[172:175]
	s_waitcnt vmcnt(2)
	ds_write_b128 v13, v[176:179]
	s_waitcnt vmcnt(1)
	ds_write_b128 v6, v[180:183]
	s_waitcnt vmcnt(0)
	ds_write_b128 v0, v[184:187]
	v_ldexp_f32 v0, v11, s22
	v_log_f32_e32 v0, v0
	v_cndmask_b32_e32 v2, 0, v242, vcc
	s_waitcnt lgkmcnt(0)
	s_barrier
	s_waitcnt lgkmcnt(0)
	v_sub_f32_e32 v67, v0, v2
	v_and_b32_e32 v2, 15, v10
	v_mul_lo_u32 v0, v66, s65
	v_add_u32_e32 v73, 0, v0
	v_mul_u32_u24_e32 v70, 0x110, v2
	v_add_u32_e32 v62, v73, v69
	ds_read_b128 v[96:99], v62
	v_add3_u32 v63, s40, v69, v70
	ds_read_b128 v[100:103], v63
	ds_read_b128 v[104:107], v63 offset:4352
	ds_read_b128 v[108:111], v63 offset:8704
	ds_read_b128 v[112:115], v63 offset:13056
	ds_read_b128 v[116:119], v63 offset:17408
	ds_read_b128 v[120:123], v63 offset:21760
	ds_read_b128 v[124:127], v63 offset:26112
	ds_read_b128 v[128:131], v63 offset:30464
	ds_read_b128 v[132:135], v62 offset:64
	ds_read_b128 v[136:139], v63 offset:64
	ds_read_b128 v[140:143], v63 offset:4416
	s_waitcnt lgkmcnt(10)
	v_mfma_f32_16x16x32_bf16 v[2:5], v[100:103], v[96:99], 0
	v_add3_u32 v72, 0, v69, v70
	v_lshlrev_b32_e32 v0, 3, v71
	ds_read_b128 v[100:103], v63 offset:8768
	ds_read_b128 v[144:147], v63 offset:13120
	ds_read_b128 v[148:151], v63 offset:17472
	s_waitcnt lgkmcnt(4)
	v_mfma_f32_16x16x32_bf16 v[2:5], v[136:139], v[132:135], v[2:5]
	ds_read_b128 v[136:139], v63 offset:21824
	v_mfma_f32_16x16x32_bf16 v[6:9], v[104:107], v[96:99], 0
	ds_read_b128 v[104:107], v63 offset:26176
	s_waitcnt lgkmcnt(5)
	v_mfma_f32_16x16x32_bf16 v[6:9], v[140:143], v[132:135], v[6:9]
	ds_read_b128 v[140:143], v63 offset:30528
	v_mfma_f32_16x16x32_bf16 v[10:13], v[108:111], v[96:99], 0
	ds_read_b128 v[108:111], v62 offset:128
	s_waitcnt lgkmcnt(6)
	v_mfma_f32_16x16x32_bf16 v[10:13], v[100:103], v[132:135], v[10:13]
	ds_read_b128 v[100:103], v63 offset:128
	v_mfma_f32_16x16x32_bf16 v[14:17], v[112:115], v[96:99], 0
	ds_read_b128 v[112:115], v63 offset:4480
	s_waitcnt lgkmcnt(7)
	v_mfma_f32_16x16x32_bf16 v[14:17], v[144:147], v[132:135], v[14:17]
	ds_read_b128 v[144:147], v63 offset:8832
	v_mfma_f32_16x16x32_bf16 v[18:21], v[116:119], v[96:99], 0
	ds_read_b128 v[116:119], v63 offset:13184
	s_waitcnt lgkmcnt(8)
	v_mfma_f32_16x16x32_bf16 v[18:21], v[148:151], v[132:135], v[18:21]
	ds_read_b128 v[148:151], v63 offset:17536
	v_mfma_f32_16x16x32_bf16 v[22:25], v[120:123], v[96:99], 0
	ds_read_b128 v[120:123], v63 offset:21888
	s_waitcnt lgkmcnt(9)
	v_mfma_f32_16x16x32_bf16 v[22:25], v[136:139], v[132:135], v[22:25]
	ds_read_b128 v[136:139], v63 offset:26240
	v_mfma_f32_16x16x32_bf16 v[26:29], v[124:127], v[96:99], 0
	ds_read_b128 v[124:127], v63 offset:30592
	s_waitcnt lgkmcnt(10)
	v_mfma_f32_16x16x32_bf16 v[26:29], v[104:107], v[132:135], v[26:29]
	v_mfma_f32_16x16x32_bf16 v[30:33], v[128:131], v[96:99], 0
	ds_read_b128 v[104:107], v62 offset:192
	s_waitcnt lgkmcnt(10)
	v_mfma_f32_16x16x32_bf16 v[30:33], v[140:143], v[132:135], v[30:33]
	ds_read_b128 v[128:131], v63 offset:192
	ds_read_b128 v[140:143], v72 offset:52224
	s_waitcnt lgkmcnt(10)
	v_mfma_f32_16x16x32_bf16 v[2:5], v[100:103], v[108:111], v[2:5]
	ds_read_b128 v[100:103], v72 offset:56576
	s_waitcnt lgkmcnt(10)
	v_mfma_f32_16x16x32_bf16 v[6:9], v[112:115], v[108:111], v[6:9]
	ds_read_b128 v[112:115], v72 offset:60928
	s_waitcnt lgkmcnt(10)
	v_mfma_f32_16x16x32_bf16 v[50:53], v[144:147], v[108:111], v[10:13]
	s_nop 2
	ds_read_b128 v[144:147], v72 offset:65280
	s_waitcnt lgkmcnt(10)
	v_mfma_f32_16x16x32_bf16 v[14:17], v[116:119], v[108:111], v[14:17]
	ds_read_b128 v[116:119], v63 offset:4544
	s_waitcnt lgkmcnt(10)
	v_mfma_f32_16x16x32_bf16 v[18:21], v[148:151], v[108:111], v[18:21]
	ds_read_b128 v[148:151], v63 offset:8896
	s_waitcnt lgkmcnt(10)
	v_mfma_f32_16x16x32_bf16 v[22:25], v[120:123], v[108:111], v[22:25]
	ds_read_b128 v[120:123], v63 offset:13248
	s_waitcnt lgkmcnt(10)
	v_mfma_f32_16x16x32_bf16 v[54:57], v[136:139], v[108:111], v[26:29]
	ds_read_b128 v[136:139], v63 offset:17600
	s_waitcnt lgkmcnt(10)
; #define LAS __attribute__((address_space(3)))
; __device__ __forceinline__ unsigned pk2(float lo, float hi) { return pg8::cvt_pk_bf16(lo, hi); }
; __device__ __forceinline__ float fexp2(float x) { return __builtin_amdgcn_exp2f(x); }
; __device__ __forceinline__ void wave_mma(f32x4 (&acc)[8], const LAS bfu* As, const LAS bfu* Bs, int m0, int fr, int fq) {
;     ...
;     for (int ks = 0; ks < 4; ++ks) { const bf16x8 a = *(const LAS bf16x8*)(As + (m0 + fr) * TS + ks * 32 + fq * 8);
; #pragma unroll
;         for (int t = 0; t < 8; ++t) { const bf16x8 b = *(const LAS bf16x8*)(Bs + (t * 16 + fr) * TS + ks * 32 + fq * 8); acc[t] = __builtin_amdgcn_mfma_f32_16x16x32_bf16(b, a, acc[t], 0, 0, 0); } }
; __device__ __forceinline__ void ret_unit(LAS unsigned char* lds, const bfu* PROJ, const bfu* RT, const float* gn_g, bfu* CAT, int u) {
;     ...
;     for (int t = 0; t < 8; ++t) { float p[4];
; #pragma unroll
;         for (int j = 0; j < 4; ++j) { const int e = 16 * t + 4 * fq + j; p[j] = (c >= e) ? acc[t][j] * fexp2(lg * (float)(c - e)) : 0.f; }
;         v2u w; w.x = pk2(p[0], p[1]); w.y = pk2(p[2], p[3]); *(LAS v2u*)(Ks + c * TS + 16 * t + 4 * fq) = w; }
	v_mfma_f32_16x16x32_bf16 v[58:61], v[124:127], v[108:111], v[30:33]
	ds_read_b128 v[124:127], v72 offset:34816
	s_waitcnt lgkmcnt(9)
	v_mfma_f32_16x16x32_bf16 v[10:13], v[128:131], v[104:107], v[2:5]
	ds_read_b128 v[128:131], v63 offset:21952
	s_nop 1
	s_waitcnt lgkmcnt(5)
	v_mfma_f32_16x16x32_bf16 v[30:33], v[116:119], v[104:107], v[6:9]
	ds_read_b128 v[116:119], v63 offset:26304
	s_nop 1
	s_waitcnt lgkmcnt(4)
	v_mfma_f32_16x16x32_bf16 v[14:17], v[120:123], v[104:107], v[14:17]
	ds_read_b128 v[120:123], v63 offset:30656
	v_mfma_f32_16x16x32_bf16 v[2:5], v[148:151], v[104:107], v[50:53]
	ds_read_b128 v[148:151], v72 offset:39168
	s_nop 2
	s_waitcnt lgkmcnt(5)
	v_mfma_f32_16x16x32_bf16 v[26:29], v[136:139], v[104:107], v[18:21]
	ds_read_b128 v[136:139], v72 offset:47872
	s_nop 1
	s_waitcnt lgkmcnt(4)
	v_mfma_f32_16x16x32_bf16 v[6:9], v[128:131], v[104:107], v[22:25]
	ds_read_b128 v[128:131], v72 offset:43520
	s_nop 2
	s_waitcnt lgkmcnt(4)
	v_mfma_f32_16x16x32_bf16 v[18:21], v[116:119], v[104:107], v[54:57]
	ds_read_b128 v[116:119], v72 offset:34880
	s_nop 2
	s_waitcnt lgkmcnt(4)
	v_mfma_f32_16x16x32_bf16 v[22:25], v[120:123], v[104:107], v[58:61]
	ds_read_b128 v[120:123], v72 offset:39232
	s_nop 1
	v_mfma_f32_16x16x32_bf16 v[50:53], v[124:127], v[96:99], 0
	ds_read_b128 v[124:127], v72 offset:43584
	s_waitcnt lgkmcnt(5)
	v_mfma_f32_16x16x32_bf16 v[54:57], v[148:151], v[96:99], 0
	ds_read_b128 v[148:151], v72 offset:47936
	s_waitcnt lgkmcnt(4)
	v_mfma_f32_16x16x32_bf16 v[58:61], v[128:131], v[96:99], 0
	ds_read_b128 v[128:131], v72 offset:52288
	v_mfma_f32_16x16x32_bf16 v[62:65], v[136:139], v[96:99], 0
	ds_read_b128 v[136:139], v72 offset:56640
	v_mfma_f32_16x16x32_bf16 v[74:77], v[140:143], v[96:99], 0
	ds_read_b128 v[140:143], v72 offset:60992
	v_mfma_f32_16x16x32_bf16 v[78:81], v[100:103], v[96:99], 0
	ds_read_b128 v[100:103], v72 offset:65344
	v_mfma_f32_16x16x32_bf16 v[82:85], v[112:115], v[96:99], 0
	ds_read_b128 v[112:115], v72 offset:34944
	v_mfma_f32_16x16x32_bf16 v[46:49], v[144:147], v[96:99], 0
	ds_read_b128 v[96:99], v72 offset:39296
	ds_read_b128 v[144:147], v72 offset:43648
	s_waitcnt lgkmcnt(10)
	v_mfma_f32_16x16x32_bf16 v[50:53], v[116:119], v[132:135], v[50:53]
	ds_read_b128 v[116:119], v72 offset:48000
	s_waitcnt lgkmcnt(10)
	v_mfma_f32_16x16x32_bf16 v[54:57], v[120:123], v[132:135], v[54:57]
	ds_read_b128 v[120:123], v72 offset:52352
	s_waitcnt lgkmcnt(10)
	v_mfma_f32_16x16x32_bf16 v[58:61], v[124:127], v[132:135], v[58:61]
	ds_read_b128 v[124:127], v72 offset:56704
	s_waitcnt lgkmcnt(10)
	v_mfma_f32_16x16x32_bf16 v[62:65], v[148:151], v[132:135], v[62:65]
	ds_read_b128 v[148:151], v72 offset:61056
	s_waitcnt lgkmcnt(10)
	v_mfma_f32_16x16x32_bf16 v[74:77], v[128:131], v[132:135], v[74:77]
	ds_read_b128 v[128:131], v72 offset:65408
	s_waitcnt lgkmcnt(10)
	v_mfma_f32_16x16x32_bf16 v[78:81], v[136:139], v[132:135], v[78:81]
	ds_read_b128 v[136:139], v72 offset:35008
	s_waitcnt lgkmcnt(10)
	v_mfma_f32_16x16x32_bf16 v[82:85], v[140:143], v[132:135], v[82:85]
	ds_read_b128 v[140:143], v72 offset:39360
	s_waitcnt lgkmcnt(10)
	v_mfma_f32_16x16x32_bf16 v[38:41], v[100:103], v[132:135], v[46:49]
	s_nop 2
	ds_read_b128 v[100:103], v72 offset:43712
	s_waitcnt lgkmcnt(10)
	v_mfma_f32_16x16x32_bf16 v[46:49], v[112:115], v[108:111], v[50:53]
	s_nop 2
	ds_read_b128 v[112:115], v72 offset:48064
	s_waitcnt lgkmcnt(10)
	v_mfma_f32_16x16x32_bf16 v[50:53], v[96:99], v[108:111], v[54:57]
	s_nop 2
	ds_read_b128 v[96:99], v72 offset:52416
	s_waitcnt lgkmcnt(10)
	v_mfma_f32_16x16x32_bf16 v[54:57], v[144:147], v[108:111], v[58:61]
	s_nop 2
	ds_read_b128 v[132:135], v72 offset:56768
	s_waitcnt lgkmcnt(10)
	v_mfma_f32_16x16x32_bf16 v[86:89], v[116:119], v[108:111], v[62:65]
	ds_read_b128 v[116:119], v72 offset:65472
	s_waitcnt lgkmcnt(10)
	v_mfma_f32_16x16x32_bf16 v[74:77], v[120:123], v[108:111], v[74:77]
	ds_read_b128 v[120:123], v72 offset:61120
	s_waitcnt lgkmcnt(10)
	v_mfma_f32_16x16x32_bf16 v[78:81], v[124:127], v[108:111], v[78:81]
	s_waitcnt lgkmcnt(9)
	v_mfma_f32_16x16x32_bf16 v[82:85], v[148:151], v[108:111], v[82:85]
	s_waitcnt lgkmcnt(8)
	v_mfma_f32_16x16x32_bf16 v[90:93], v[128:131], v[108:111], v[38:41]
	s_nop 2
	s_waitcnt lgkmcnt(7)
	v_mfma_f32_16x16x32_bf16 v[62:65], v[136:139], v[104:107], v[46:49]
	s_waitcnt lgkmcnt(6)
	v_mfma_f32_16x16x32_bf16 v[58:61], v[140:143], v[104:107], v[50:53]
	s_waitcnt lgkmcnt(5)
	v_mfma_f32_16x16x32_bf16 v[54:57], v[100:103], v[104:107], v[54:57]
	s_waitcnt lgkmcnt(4)
	v_mfma_f32_16x16x32_bf16 v[50:53], v[112:115], v[104:107], v[86:89]
	s_waitcnt lgkmcnt(3)
	v_mfma_f32_16x16x32_bf16 v[46:49], v[96:99], v[104:107], v[74:77]
	s_nop 1
	s_waitcnt lgkmcnt(2)
	v_mfma_f32_16x16x32_bf16 v[42:45], v[132:135], v[104:107], v[78:81]
	v_lshlrev_b32_e32 v72, 2, v71
	v_add_u32_e32 v71, v73, v0
	v_sub_u32_e32 v73, v66, v72
	v_cvt_f32_i32_e32 v73, v73
	v_cmp_ge_i32_e32 vcc, v66, v72
	s_waitcnt lgkmcnt(0)
	v_mfma_f32_16x16x32_bf16 v[38:41], v[120:123], v[104:107], v[82:85]
	v_mul_f32_e32 v73, v67, v73
	v_exp_f32_e32 v73, v73
	v_mfma_f32_16x16x32_bf16 v[34:37], v[116:119], v[104:107], v[90:93]
	v_or_b32_e32 v75, 3, v72
	v_mul_f32_e32 v62, v73, v62
	v_cndmask_b32_e32 v73, 0, v62, vcc
	v_xad_u32 v62, v72, -1, v66
	v_cvt_f32_i32_e32 v62, v62
	v_cmp_gt_i32_e32 vcc, v66, v72
	v_or_b32_e32 v76, 2, v72
	s_waitcnt lgkmcnt(0)
	s_barrier
; #define LAS __attribute__((address_space(3)))
; __device__ __forceinline__ unsigned pk2(float lo, float hi) { return pg8::cvt_pk_bf16(lo, hi); }
; __device__ __forceinline__ float fexp2(float x) { return __builtin_amdgcn_exp2f(x); }
; __device__ __forceinline__ void ret_unit(LAS unsigned char* lds, const bfu* PROJ, const bfu* RT, const float* gn_g, bfu* CAT, int u) {
;     ...
;     for (int t = 0; t < 8; ++t) { float p[4];
; #pragma unroll
;         for (int j = 0; j < 4; ++j) { const int e = 16 * t + 4 * fq + j; p[j] = (c >= e) ? acc[t][j] * fexp2(lg * (float)(c - e)) : 0.f; }
;         v2u w; w.x = pk2(p[0], p[1]); w.y = pk2(p[2], p[3]); *(LAS v2u*)(Ks + c * TS + 16 * t + 4 * fq) = w; }
	v_mul_f32_e32 v62, v67, v62
	v_exp_f32_e32 v62, v62
	v_add_u32_e32 v78, v71, v0
	v_add3_u32 v82, s70, v69, v70
	v_mul_f32_e32 v62, v62, v63
	v_cndmask_b32_e32 v74, 0, v62, vcc
	v_sub_u32_e32 v62, v66, v76
	v_sub_u32_e32 v63, v66, v75
	v_cvt_f32_i32_e32 v62, v62
	v_cvt_f32_i32_e32 v63, v63
	v_cmp_ge_i32_e32 vcc, v66, v76
	v_or_b32_e32 v76, 18, v72
	v_mul_f32_e32 v62, v67, v62
	v_mul_f32_e32 v63, v67, v63
	v_exp_f32_e32 v62, v62
	v_exp_f32_e32 v63, v63
	s_nop 0
	v_pk_mul_f32 v[62:63], v[62:63], v[64:65]
	s_nop 0
	v_cvt_pk_bf16_f32 v62, v62, v63
	v_cndmask_b32_e32 v63, 0, v62, vcc
	v_lshrrev_b32_e32 v62, 16, v62
	v_cmp_ge_i32_e32 vcc, v66, v75
	v_cvt_pk_bf16_f32 v64, v73, v74
	v_or_b32_e32 v73, 17, v72
	v_cndmask_b32_e32 v62, 0, v62, vcc
	v_or_b32_e32 v74, 16, v72
	v_perm_b32 v65, v62, v63, s72
	v_sub_u32_e32 v62, v66, v74
	v_sub_u32_e32 v63, v66, v73
	v_cvt_f32_i32_e32 v62, v62
	v_cvt_f32_i32_e32 v63, v63
	v_or_b32_e32 v75, 19, v72
	v_cmp_ge_i32_e32 vcc, v66, v74
	v_mul_f32_e32 v62, v67, v62
	v_mul_f32_e32 v63, v67, v63
	v_exp_f32_e32 v62, v62
	v_exp_f32_e32 v63, v63
	s_nop 0
	v_pk_mul_f32 v[58:59], v[62:63], v[58:59]
	v_sub_u32_e32 v62, v66, v76
	v_sub_u32_e32 v63, v66, v75
	v_cvt_f32_i32_e32 v62, v62
	v_cvt_f32_i32_e32 v63, v63
	v_cvt_pk_bf16_f32 v58, v58, v59
	v_cndmask_b32_e32 v59, 0, v58, vcc
	v_mul_f32_e32 v62, v67, v62
	v_mul_f32_e32 v63, v67, v63
	v_exp_f32_e32 v62, v62
	v_exp_f32_e32 v63, v63
	v_lshrrev_b32_e32 v58, 16, v58
	v_cmp_ge_i32_e32 vcc, v66, v73
	v_pk_mul_f32 v[60:61], v[62:63], v[60:61]
	s_nop 0
	v_cndmask_b32_e32 v58, 0, v58, vcc
	v_perm_b32 v62, v58, v59, s72
	v_cvt_pk_bf16_f32 v58, v60, v61
	v_cmp_ge_i32_e32 vcc, v66, v76
	s_nop 1
	v_cndmask_b32_e32 v59, 0, v58, vcc
	v_lshrrev_b32_e32 v58, 16, v58
	v_cmp_ge_i32_e32 vcc, v66, v75
	s_nop 1
	v_cndmask_b32_e32 v58, 0, v58, vcc
	v_perm_b32 v63, v58, v59, s72
	v_add_u32_e32 v58, 0x8800, v71
	ds_write2_b64 v58, v[64:65], v[62:63] offset1:4
	v_or_b32_e32 v59, 33, v72
	v_or_b32_e32 v62, 32, v72
	v_sub_u32_e32 v60, v66, v62
	v_sub_u32_e32 v61, v66, v59
	v_cvt_f32_i32_e32 v60, v60
	v_cvt_f32_i32_e32 v61, v61
	v_or_b32_e32 v63, 35, v72
	v_or_b32_e32 v64, 34, v72
	v_mul_f32_e32 v60, v67, v60
	v_mul_f32_e32 v61, v67, v61
	v_exp_f32_e32 v60, v60
	v_exp_f32_e32 v61, v61
	v_cmp_ge_i32_e32 vcc, v66, v62
	v_or_b32_e32 v62, 50, v72
	v_pk_mul_f32 v[54:55], v[60:61], v[54:55]
	v_sub_u32_e32 v60, v66, v64
	v_sub_u32_e32 v61, v66, v63
	v_cvt_f32_i32_e32 v60, v60
	v_cvt_f32_i32_e32 v61, v61
	v_cvt_pk_bf16_f32 v54, v54, v55
	v_cndmask_b32_e32 v55, 0, v54, vcc
	v_mul_f32_e32 v60, v67, v60
	v_mul_f32_e32 v61, v67, v61
	v_exp_f32_e32 v60, v60
	v_exp_f32_e32 v61, v61
	v_lshrrev_b32_e32 v54, 16, v54
	v_cmp_ge_i32_e32 vcc, v66, v59
	v_or_b32_e32 v59, 49, v72
	v_pk_mul_f32 v[56:57], v[60:61], v[56:57]
	v_cndmask_b32_e32 v54, 0, v54, vcc
	v_perm_b32 v54, v54, v55, s72
	v_cvt_pk_bf16_f32 v55, v56, v57
	v_cmp_ge_i32_e32 vcc, v66, v64
	v_or_b32_e32 v60, 48, v72
	v_sub_u32_e32 v57, v66, v59
	v_cndmask_b32_e32 v56, 0, v55, vcc
	v_lshrrev_b32_e32 v55, 16, v55
	v_cmp_ge_i32_e32 vcc, v66, v63
	v_cvt_f32_i32_e32 v57, v57
	v_or_b32_e32 v61, 51, v72
	v_cndmask_b32_e32 v55, 0, v55, vcc
	v_perm_b32 v55, v55, v56, s72
	v_sub_u32_e32 v56, v66, v60
	v_cvt_f32_i32_e32 v56, v56
	v_mul_f32_e32 v57, v67, v57
	v_exp_f32_e32 v57, v57
	v_cmp_ge_i32_e32 vcc, v66, v60
	v_mul_f32_e32 v56, v67, v56
	v_exp_f32_e32 v56, v56
	s_nop 0
	v_pk_mul_f32 v[50:51], v[56:57], v[50:51]
	v_sub_u32_e32 v56, v66, v62
	v_sub_u32_e32 v57, v66, v61
	v_cvt_f32_i32_e32 v56, v56
	v_cvt_f32_i32_e32 v57, v57
	v_cvt_pk_bf16_f32 v50, v50, v51
	v_cndmask_b32_e32 v51, 0, v50, vcc
	v_mul_f32_e32 v56, v67, v56
	v_mul_f32_e32 v57, v67, v57
	v_exp_f32_e32 v56, v56
	v_exp_f32_e32 v57, v57
	v_lshrrev_b32_e32 v50, 16, v50
	v_cmp_ge_i32_e32 vcc, v66, v59
	v_pk_mul_f32 v[52:53], v[56:57], v[52:53]
	s_nop 0
	v_cndmask_b32_e32 v50, 0, v50, vcc
	v_perm_b32 v50, v50, v51, s72
	v_cvt_pk_bf16_f32 v51, v52, v53
	v_cmp_ge_i32_e32 vcc, v66, v62
	v_or_b32_e32 v53, 64, v72
	s_nop 0
	v_cndmask_b32_e32 v52, 0, v51, vcc
	v_lshrrev_b32_e32 v51, 16, v51
	v_cmp_ge_i32_e32 vcc, v66, v61
	s_nop 1
	v_cndmask_b32_e32 v51, 0, v51, vcc
	v_perm_b32 v51, v51, v52, s72
	v_or_b32_e32 v52, 0x41, v72
	ds_write2_b64 v58, v[54:55], v[50:51] offset0:8 offset1:12
	v_sub_u32_e32 v50, v66, v53
	v_sub_u32_e32 v51, v66, v52
	v_cvt_f32_i32_e32 v50, v50
	v_cvt_f32_i32_e32 v51, v51
	v_or_b32_e32 v54, 0x43, v72
	v_or_b32_e32 v55, 0x42, v72
	v_mul_f32_e32 v50, v67, v50
	v_mul_f32_e32 v51, v67, v51
	v_exp_f32_e32 v50, v50
	v_exp_f32_e32 v51, v51
	v_cmp_ge_i32_e32 vcc, v66, v53
	v_or_b32_e32 v53, 0x52, v72
	v_pk_mul_f32 v[46:47], v[50:51], v[46:47]
	v_sub_u32_e32 v50, v66, v55
	v_sub_u32_e32 v51, v66, v54
	v_cvt_f32_i32_e32 v50, v50
	v_cvt_f32_i32_e32 v51, v51
	v_cvt_pk_bf16_f32 v46, v46, v47
	v_cndmask_b32_e32 v47, 0, v46, vcc
	v_mul_f32_e32 v50, v67, v50
	v_mul_f32_e32 v51, v67, v51
	v_exp_f32_e32 v50, v50
	v_exp_f32_e32 v51, v51
	v_lshrrev_b32_e32 v46, 16, v46
	v_cmp_ge_i32_e32 vcc, v66, v52
	v_or_b32_e32 v52, 0x53, v72
	v_pk_mul_f32 v[48:49], v[50:51], v[48:49]
	v_cndmask_b32_e32 v46, 0, v46, vcc
	v_perm_b32 v46, v46, v47, s72
	v_cvt_pk_bf16_f32 v47, v48, v49
	v_cmp_ge_i32_e32 vcc, v66, v55
	v_or_b32_e32 v50, 0x51, v72
	v_or_b32_e32 v51, 0x50, v72
	v_cndmask_b32_e32 v48, 0, v47, vcc
	v_lshrrev_b32_e32 v47, 16, v47
	v_cmp_ge_i32_e32 vcc, v66, v54
	v_sub_u32_e32 v49, v66, v50
	v_cvt_f32_i32_e32 v49, v49
	v_cndmask_b32_e32 v47, 0, v47, vcc
	v_perm_b32 v47, v47, v48, s72
	v_sub_u32_e32 v48, v66, v51
	v_cvt_f32_i32_e32 v48, v48
	v_mul_f32_e32 v49, v67, v49
	v_exp_f32_e32 v49, v49
	v_cmp_ge_i32_e32 vcc, v66, v51
; #define LAS __attribute__((address_space(3)))
; #define LDS_WAIT() asm volatile("s_waitcnt lgkmcnt(0)" ::: "memory")
; __device__ __forceinline__ unsigned pk2(float lo, float hi) { return pg8::cvt_pk_bf16(lo, hi); }
; __device__ __forceinline__ float fexp2(float x) { return __builtin_amdgcn_exp2f(x); }
; #define ZERO8(a) do { _Pragma("unroll") for (int t_ = 0; t_ < 8; ++t_) a[t_] = (f32x4){0.f, 0.f, 0.f, 0.f}; } while (0)
; __device__ __forceinline__ void ret_unit(LAS unsigned char* lds, const bfu* PROJ, const bfu* RT, const float* gn_g, bfu* CAT, int u) {
;     ...
;     for (int t = 0; t < 8; ++t) { float p[4];
; #pragma unroll
;         for (int j = 0; j < 4; ++j) { const int e = 16 * t + 4 * fq + j; p[j] = (c >= e) ? acc[t][j] * fexp2(lg * (float)(c - e)) : 0.f; }
;         v2u w; w.x = pk2(p[0], p[1]); w.y = pk2(p[2], p[3]); *(LAS v2u*)(Ks + c * TS + 16 * t + 4 * fq) = w; }
;     LDS_WAIT(); asm volatile("" ::: "memory");
;     ZERO8(acc);
;     wave_mma(acc, Ks, Vt, m0, fr, fq);
	v_mul_f32_e32 v48, v67, v48
	v_exp_f32_e32 v48, v48
	s_nop 0
	v_pk_mul_f32 v[42:43], v[48:49], v[42:43]
	v_sub_u32_e32 v48, v66, v53
	v_sub_u32_e32 v49, v66, v52
	v_cvt_f32_i32_e32 v48, v48
	v_cvt_f32_i32_e32 v49, v49
	v_cvt_pk_bf16_f32 v42, v42, v43
	v_cndmask_b32_e32 v43, 0, v42, vcc
	v_mul_f32_e32 v48, v67, v48
	v_mul_f32_e32 v49, v67, v49
	v_exp_f32_e32 v48, v48
	v_exp_f32_e32 v49, v49
	v_lshrrev_b32_e32 v42, 16, v42
	v_cmp_ge_i32_e32 vcc, v66, v50
	v_pk_mul_f32 v[44:45], v[48:49], v[44:45]
	s_nop 0
	v_cndmask_b32_e32 v42, 0, v42, vcc
	v_perm_b32 v42, v42, v43, s72
	v_cvt_pk_bf16_f32 v43, v44, v45
	v_cmp_ge_i32_e32 vcc, v66, v53
	v_or_b32_e32 v45, 0x60, v72
	s_nop 0
	v_cndmask_b32_e32 v44, 0, v43, vcc
	v_lshrrev_b32_e32 v43, 16, v43
	v_cmp_ge_i32_e32 vcc, v66, v52
	s_nop 1
	v_cndmask_b32_e32 v43, 0, v43, vcc
	v_perm_b32 v43, v43, v44, s72
	v_or_b32_e32 v44, 0x61, v72
	ds_write2_b64 v58, v[46:47], v[42:43] offset0:16 offset1:20
	v_sub_u32_e32 v42, v66, v45
	v_sub_u32_e32 v43, v66, v44
	v_cvt_f32_i32_e32 v42, v42
	v_cvt_f32_i32_e32 v43, v43
	v_or_b32_e32 v46, 0x63, v72
	v_or_b32_e32 v47, 0x62, v72
	v_mul_f32_e32 v42, v67, v42
	v_mul_f32_e32 v43, v67, v43
	v_exp_f32_e32 v42, v42
	v_exp_f32_e32 v43, v43
	v_cmp_ge_i32_e32 vcc, v66, v45
	v_or_b32_e32 v45, 0x72, v72
	v_pk_mul_f32 v[38:39], v[42:43], v[38:39]
	v_sub_u32_e32 v42, v66, v47
	v_sub_u32_e32 v43, v66, v46
	v_cvt_f32_i32_e32 v42, v42
	v_cvt_f32_i32_e32 v43, v43
	v_cvt_pk_bf16_f32 v38, v38, v39
	v_cndmask_b32_e32 v39, 0, v38, vcc
	v_mul_f32_e32 v42, v67, v42
	v_mul_f32_e32 v43, v67, v43
	v_exp_f32_e32 v42, v42
	v_exp_f32_e32 v43, v43
	v_lshrrev_b32_e32 v38, 16, v38
	v_cmp_ge_i32_e32 vcc, v66, v44
	v_or_b32_e32 v44, 0x73, v72
	v_pk_mul_f32 v[40:41], v[42:43], v[40:41]
	v_cndmask_b32_e32 v38, 0, v38, vcc
	v_perm_b32 v38, v38, v39, s72
	v_cvt_pk_bf16_f32 v39, v40, v41
	v_cmp_ge_i32_e32 vcc, v66, v47
	v_or_b32_e32 v42, 0x71, v72
	v_or_b32_e32 v43, 0x70, v72
	v_cndmask_b32_e32 v40, 0, v39, vcc
	v_lshrrev_b32_e32 v39, 16, v39
	v_cmp_ge_i32_e32 vcc, v66, v46
	v_sub_u32_e32 v41, v66, v42
	v_cvt_f32_i32_e32 v41, v41
	v_cndmask_b32_e32 v39, 0, v39, vcc
	v_perm_b32 v39, v39, v40, s72
	v_sub_u32_e32 v40, v66, v43
	v_cvt_f32_i32_e32 v40, v40
	v_mul_f32_e32 v41, v67, v41
	v_exp_f32_e32 v41, v41
	v_cmp_ge_i32_e32 vcc, v66, v43
	v_mul_f32_e32 v40, v67, v40
	v_exp_f32_e32 v40, v40
	s_nop 0
	v_pk_mul_f32 v[34:35], v[40:41], v[34:35]
	v_sub_u32_e32 v40, v66, v45
	v_sub_u32_e32 v41, v66, v44
	v_cvt_f32_i32_e32 v40, v40
	v_cvt_f32_i32_e32 v41, v41
	v_cvt_pk_bf16_f32 v34, v34, v35
	v_cndmask_b32_e32 v35, 0, v34, vcc
	v_mul_f32_e32 v40, v67, v40
	v_mul_f32_e32 v41, v67, v41
	v_exp_f32_e32 v40, v40
	v_exp_f32_e32 v41, v41
	v_lshrrev_b32_e32 v34, 16, v34
	v_cmp_ge_i32_e32 vcc, v66, v42
	v_pk_mul_f32 v[36:37], v[40:41], v[36:37]
	s_nop 0
	v_cndmask_b32_e32 v34, 0, v34, vcc
	v_perm_b32 v34, v34, v35, s72
	v_cvt_pk_bf16_f32 v35, v36, v37
	v_cmp_ge_i32_e32 vcc, v66, v45
	s_nop 1
	v_cndmask_b32_e32 v36, 0, v35, vcc
	v_lshrrev_b32_e32 v35, 16, v35
	v_cmp_ge_i32_e32 vcc, v66, v44
	s_nop 1
	v_cndmask_b32_e32 v35, 0, v35, vcc
	v_perm_b32 v35, v35, v36, s72
	ds_write2_b64 v58, v[38:39], v[34:35] offset0:24 offset1:28
	s_waitcnt lgkmcnt(0)
	s_waitcnt lgkmcnt(0)
	ds_read_b128 v[84:87], v78 offset:34816
	ds_read_b128 v[88:91], v82
	ds_read_b128 v[92:95], v82 offset:4352
	ds_read_b128 v[96:99], v82 offset:8704
	ds_read_b128 v[100:103], v82 offset:13056
	ds_read_b128 v[104:107], v82 offset:17408
	ds_read_b128 v[108:111], v82 offset:21760
	ds_read_b128 v[112:115], v82 offset:26112
	ds_read_b128 v[116:119], v82 offset:30464
	ds_read_b128 v[120:123], v78 offset:34880
	ds_read_b128 v[124:127], v82 offset:64
	ds_read_b128 v[128:131], v82 offset:4416
	s_waitcnt lgkmcnt(10)
	v_mfma_f32_16x16x32_bf16 v[38:41], v[88:91], v[84:87], 0
	ds_read_b128 v[88:91], v82 offset:8768
	s_waitcnt lgkmcnt(10)
	v_mfma_f32_16x16x32_bf16 v[42:45], v[92:95], v[84:87], 0
	ds_read_b128 v[92:95], v82 offset:13120
	s_waitcnt lgkmcnt(10)
	v_mfma_f32_16x16x32_bf16 v[46:49], v[96:99], v[84:87], 0
	ds_read_b128 v[96:99], v82 offset:17472
	s_waitcnt lgkmcnt(10)
	v_mfma_f32_16x16x32_bf16 v[50:53], v[100:103], v[84:87], 0
	ds_read_b128 v[100:103], v82 offset:21824
	s_waitcnt lgkmcnt(10)
	v_mfma_f32_16x16x32_bf16 v[54:57], v[104:107], v[84:87], 0
	ds_read_b128 v[104:107], v82 offset:26176
	s_waitcnt lgkmcnt(10)
	v_mfma_f32_16x16x32_bf16 v[58:61], v[108:111], v[84:87], 0
	ds_read_b128 v[108:111], v82 offset:30528
	s_waitcnt lgkmcnt(10)
	v_mfma_f32_16x16x32_bf16 v[62:65], v[112:115], v[84:87], 0
	ds_read_b128 v[112:115], v78 offset:34944
	s_waitcnt lgkmcnt(10)
	v_mfma_f32_16x16x32_bf16 v[34:37], v[116:119], v[84:87], 0
	ds_read_b128 v[84:87], v82 offset:128
	ds_read_b128 v[116:119], v82 offset:4480
	s_waitcnt lgkmcnt(10)
	v_mfma_f32_16x16x32_bf16 v[38:41], v[124:127], v[120:123], v[38:41]
	ds_read_b128 v[124:127], v82 offset:8832
	s_waitcnt lgkmcnt(10)
	v_mfma_f32_16x16x32_bf16 v[42:45], v[128:131], v[120:123], v[42:45]
	ds_read_b128 v[128:131], v82 offset:13184
	s_waitcnt lgkmcnt(10)
	v_mfma_f32_16x16x32_bf16 v[46:49], v[88:91], v[120:123], v[46:49]
	ds_read_b128 v[88:91], v82 offset:17536
	s_waitcnt lgkmcnt(10)
	v_mfma_f32_16x16x32_bf16 v[50:53], v[92:95], v[120:123], v[50:53]
	ds_read_b128 v[92:95], v82 offset:21888
	s_waitcnt lgkmcnt(10)
	v_mfma_f32_16x16x32_bf16 v[54:57], v[96:99], v[120:123], v[54:57]
	ds_read_b128 v[96:99], v82 offset:26240
	s_waitcnt lgkmcnt(10)
	v_mfma_f32_16x16x32_bf16 v[58:61], v[100:103], v[120:123], v[58:61]
	ds_read_b128 v[100:103], v82 offset:30592
	s_waitcnt lgkmcnt(10)
; #define LAS __attribute__((address_space(3)))
; __device__ __forceinline__ float fexp2(float x) { return __builtin_amdgcn_exp2f(x); }
; __device__ __forceinline__ void wave_mma(f32x4 (&acc)[8], const LAS bfu* As, const LAS bfu* Bs, int m0, int fr, int fq) {
;     ...
;     for (int ks = 0; ks < 4; ++ks) { const bf16x8 a = *(const LAS bf16x8*)(As + (m0 + fr) * TS + ks * 32 + fq * 8);
; #pragma unroll
;         for (int t = 0; t < 8; ++t) { const bf16x8 b = *(const LAS bf16x8*)(Bs + (t * 16 + fr) * TS + ks * 32 + fq * 8); acc[t] = __builtin_amdgcn_mfma_f32_16x16x32_bf16(b, a, acc[t], 0, 0, 0); } }
; __device__ __forceinline__ void ret_unit(LAS unsigned char* lds, const bfu* PROJ, const bfu* RT, const float* gn_g, bfu* CAT, int u) {
;     ...
;     wave_mma(acc, Ks, Vt, m0, fr, fq);
;     const float xi = fexp2(lg * (float)(c + 1)); float s = 0.f;
; #pragma unroll
;     for (int t = 0; t < 8; ++t) { acc[t] = acc[t] + cr[t] * xi; s += (acc[t][0] + acc[t][1]) + (acc[t][2] + acc[t][3]); }
;     s += __shfl_xor(s, 16); s += __shfl_xor(s, 32); const float mu = s * (1.f / 128.f); float q = 0.f;
	v_mfma_f32_16x16x32_bf16 v[62:65], v[104:107], v[120:123], v[62:65]
	ds_read_b128 v[104:107], v78 offset:35008
	s_waitcnt lgkmcnt(10)
	v_mfma_f32_16x16x32_bf16 v[34:37], v[108:111], v[120:123], v[34:37]
	ds_read_b128 v[108:111], v82 offset:192
	ds_read_b128 v[120:123], v82 offset:4544
	s_waitcnt lgkmcnt(10)
	v_mfma_f32_16x16x32_bf16 v[38:41], v[84:87], v[112:115], v[38:41]
	ds_read_b128 v[84:87], v82 offset:8896
	s_waitcnt lgkmcnt(10)
	v_mfma_f32_16x16x32_bf16 v[42:45], v[116:119], v[112:115], v[42:45]
	ds_read_b128 v[116:119], v82 offset:13248
	s_waitcnt lgkmcnt(10)
	v_mfma_f32_16x16x32_bf16 v[46:49], v[124:127], v[112:115], v[46:49]
	ds_read_b128 v[124:127], v82 offset:17600
	s_waitcnt lgkmcnt(10)
	v_mfma_f32_16x16x32_bf16 v[50:53], v[128:131], v[112:115], v[50:53]
	ds_read_b128 v[128:131], v82 offset:21952
	s_waitcnt lgkmcnt(10)
	v_mfma_f32_16x16x32_bf16 v[54:57], v[88:91], v[112:115], v[54:57]
	ds_read_b128 v[88:91], v82 offset:26304
	s_waitcnt lgkmcnt(10)
	v_mfma_f32_16x16x32_bf16 v[58:61], v[92:95], v[112:115], v[58:61]
	ds_read_b128 v[92:95], v82 offset:30656
	s_waitcnt lgkmcnt(10)
	v_mfma_f32_16x16x32_bf16 v[62:65], v[96:99], v[112:115], v[62:65]
	s_waitcnt lgkmcnt(9)
	v_mfma_f32_16x16x32_bf16 v[34:37], v[100:103], v[112:115], v[34:37]
	s_waitcnt lgkmcnt(7)
	v_mfma_f32_16x16x32_bf16 v[38:41], v[108:111], v[104:107], v[38:41]
	s_waitcnt lgkmcnt(6)
	v_mfma_f32_16x16x32_bf16 v[74:77], v[120:123], v[104:107], v[42:45]
	s_nop 2
	s_waitcnt lgkmcnt(5)
	v_mfma_f32_16x16x32_bf16 v[78:81], v[84:87], v[104:107], v[46:49]
	s_waitcnt lgkmcnt(4)
	v_mfma_f32_16x16x32_bf16 v[48:51], v[116:119], v[104:107], v[50:53]
	s_waitcnt lgkmcnt(3)
	v_mfma_f32_16x16x32_bf16 v[52:55], v[124:127], v[104:107], v[54:57]
	s_waitcnt lgkmcnt(2)
	v_mfma_f32_16x16x32_bf16 v[56:59], v[128:131], v[104:107], v[58:61]
	s_waitcnt lgkmcnt(1)
	v_mfma_f32_16x16x32_bf16 v[60:63], v[88:91], v[104:107], v[62:65]
	s_waitcnt lgkmcnt(0)
	v_mfma_f32_16x16x32_bf16 v[70:73], v[92:95], v[104:107], v[34:37]
	s_nop 2
	s_waitcnt lgkmcnt(0)
	v_add_u32_e32 v34, 1, v66
	v_cvt_f32_i32_e32 v34, v34
	v_mul_f32_e32 v34, v67, v34
	v_exp_f32_e32 v64, v34
	v_ashrrev_i32_e32 v67, 31, v66
	v_pk_fma_f32 v[46:47], v[64:65], v[10:11], v[38:39] op_sel_hi:[0,1,1]
	v_pk_fma_f32 v[42:43], v[64:65], v[30:31], v[74:75] op_sel_hi:[0,1,1]
	v_pk_fma_f32 v[44:45], v[64:65], v[12:13], v[40:41] op_sel_hi:[0,1,1]
	v_pk_fma_f32 v[40:41], v[64:65], v[32:33], v[76:77] op_sel_hi:[0,1,1]
	v_mov_b32_e32 v10, v46
	v_mov_b32_e32 v11, v42
	v_mov_b32_e32 v12, v47
	v_mov_b32_e32 v13, v43
	v_pk_add_f32 v[10:11], v[10:11], v[12:13]
	v_mov_b32_e32 v12, v44
	v_mov_b32_e32 v13, v40
	v_mov_b32_e32 v30, v45
	v_mov_b32_e32 v31, v41
	v_pk_fma_f32 v[38:39], v[64:65], v[2:3], v[78:79] op_sel_hi:[0,1,1]
	v_pk_fma_f32 v[36:37], v[64:65], v[4:5], v[80:81] op_sel_hi:[0,1,1]
	v_pk_add_f32 v[12:13], v[12:13], v[30:31]
	v_pk_mov_b32 v[2:3], v[38:39], v[36:37] op_sel:[1,0]
	v_mov_b32_e32 v4, v38
	v_mov_b32_e32 v5, v37
	v_pk_add_f32 v[10:11], v[10:11], v[12:13]
	v_pk_add_f32 v[2:3], v[2:3], v[4:5]
	v_add_f32_e32 v10, 0, v10
	v_pk_add_f32 v[2:3], v[2:3], v[2:3] op_sel:[0,1] op_sel_hi:[1,0]
	v_pk_fma_f32 v[32:33], v[64:65], v[16:17], v[50:51] op_sel_hi:[0,1,1]
	v_pk_fma_f32 v[34:35], v[64:65], v[14:15], v[48:49] op_sel_hi:[0,1,1]
	v_pk_fma_f32 v[28:29], v[64:65], v[28:29], v[54:55] op_sel_hi:[0,1,1]
	v_pk_fma_f32 v[30:31], v[64:65], v[26:27], v[52:53] op_sel_hi:[0,1,1]
	v_add_f32_e32 v10, v10, v11
	v_add_f32_e32 v4, v34, v35
	v_add_f32_e32 v12, v32, v33
	v_mov_b32_e32 v11, v30
	v_mov_b32_e32 v3, v31
	v_mov_b32_e32 v5, v28
	v_mov_b32_e32 v13, v29
	v_pk_add_f32 v[2:3], v[10:11], v[2:3]
	v_pk_add_f32 v[4:5], v[4:5], v[12:13]
	v_pk_fma_f32 v[26:27], v[64:65], v[6:7], v[56:57] op_sel_hi:[0,1,1]
	v_pk_fma_f32 v[16:17], v[64:65], v[8:9], v[58:59] op_sel_hi:[0,1,1]
	v_pk_add_f32 v[2:3], v[2:3], v[4:5]
	v_pk_mov_b32 v[4:5], v[26:27], v[16:17] op_sel:[1,0]
	v_mov_b32_e32 v6, v26
	v_mov_b32_e32 v7, v17
	v_pk_add_f32 v[4:5], v[4:5], v[6:7]
	v_pk_add_f32 v[2:3], v[2:3], v[2:3] op_sel:[0,1] op_sel_hi:[1,0]
	v_pk_add_f32 v[4:5], v[4:5], v[4:5] op_sel:[0,1] op_sel_hi:[1,0]
	v_pk_fma_f32 v[10:11], v[64:65], v[20:21], v[62:63] op_sel_hi:[0,1,1]
	v_pk_fma_f32 v[12:13], v[64:65], v[18:19], v[60:61] op_sel_hi:[0,1,1]
	v_pk_fma_f32 v[6:7], v[64:65], v[24:25], v[72:73] op_sel_hi:[0,1,1]
	v_pk_fma_f32 v[8:9], v[64:65], v[22:23], v[70:71] op_sel_hi:[0,1,1]
	v_add_f32_e32 v14, v12, v13
	v_add_f32_e32 v18, v10, v11
	v_mov_b32_e32 v3, v8
	v_mov_b32_e32 v5, v9
	v_mov_b32_e32 v15, v6
	v_mov_b32_e32 v19, v7
	v_pk_add_f32 v[2:3], v[2:3], v[4:5]
	v_pk_add_f32 v[4:5], v[14:15], v[18:19]
	s_nop 0
	v_pk_add_f32 v[2:3], v[2:3], v[4:5]
	v_and_b32_e32 v4, 64, v240
	v_add_f32_e32 v2, v2, v3
	v_xor_b32_e32 v3, 16, v240
	v_add_u32_e32 v4, 64, v4
	v_cmp_lt_i32_e32 vcc, v3, v4
	s_nop 1
	v_cndmask_b32_e32 v3, v240, v3, vcc
	v_lshlrev_b32_e32 v20, 2, v3
	s_waitcnt lgkmcnt(0)
	v_mov_b32_e32 v3, v2
	s_nop 1
	v_permlane16_swap_b32_e32 v2, v3
	v_add_f32_e32 v2, v2, v3
	v_xor_b32_e32 v3, 32, v240
	v_cmp_lt_i32_e32 vcc, v3, v4
	s_nop 1
	v_cndmask_b32_e32 v3, v240, v3, vcc
	v_lshlrev_b32_e32 v21, 2, v3
	s_waitcnt lgkmcnt(0)
; __device__ __forceinline__ void ret_unit(LAS unsigned char* lds, const bfu* PROJ, const bfu* RT, const float* gn_g, bfu* CAT, int u) {
;     ...
;     s += __shfl_xor(s, 16); s += __shfl_xor(s, 32); const float mu = s * (1.f / 128.f); float q = 0.f;
; #pragma unroll
;     for (int t = 0; t < 8; ++t) { acc[t] = acc[t] - mu; q += (acc[t][0] * acc[t][0] + acc[t][1] * acc[t][1]) + (acc[t][2] * acc[t][2] + acc[t][3] * acc[t][3]); }
;     q += __shfl_xor(q, 16); q += __shfl_xor(q, 32); const float rstd = 1.f / sqrtf(q * (1.f / 128.f) + EPS);
;     const bfu* gp = P0 + (size_t)c * INW + C_RG + 4 * fq; bfu* op = CAT + (row0 + c) * DM + h * 128 + 4 * fq; const float* gg = gn_g + h * 128 + 4 * fq;
; #pragma unroll
;     for (int t = 0; t < 8; ++t) { const v2u gw = *(const v2u*)(gp + 16 * t); const f32x4 g4 = *(const f32x4*)(gg + 16 * t);
	v_mov_b32_e32 v3, v2
	v_mov_b32_e32 v22, v2
	s_nop 1
	v_permlane32_swap_b32_e32 v22, v3
	v_add_f32_e32 v22, v22, v3
	v_fmamk_f32 v47, v22, 0xbc000000, v47
	v_fmamk_f32 v43, v22, 0xbc000000, v43
	v_fmamk_f32 v45, v22, 0xbc000000, v45
	v_fmac_f32_e32 v46, 0xbc000000, v22
	v_fmamk_f32 v41, v22, 0xbc000000, v41
	v_fmac_f32_e32 v42, 0xbc000000, v22
	v_mov_b32_e32 v4, v47
	v_mov_b32_e32 v5, v43
	v_fmac_f32_e32 v44, 0xbc000000, v22
	v_fmac_f32_e32 v40, 0xbc000000, v22
	v_mov_b32_e32 v2, v46
	v_mov_b32_e32 v3, v42
	v_pk_mul_f32 v[4:5], v[4:5], v[4:5]
	v_mov_b32_e32 v14, v45
	v_mov_b32_e32 v15, v41
	v_pk_fma_f32 v[2:3], v[2:3], v[2:3], v[4:5]
	v_mov_b32_e32 v4, v44
	v_mov_b32_e32 v5, v40
	v_pk_mul_f32 v[14:15], v[14:15], v[14:15]
	v_fmamk_f32 v39, v22, 0xbc000000, v39
	v_pk_fma_f32 v[4:5], v[4:5], v[4:5], v[14:15]
	v_fmac_f32_e32 v38, 0xbc000000, v22
	v_pk_add_f32 v[2:3], v[2:3], v[4:5]
	v_fmamk_f32 v37, v22, 0xbc000000, v37
	v_fmac_f32_e32 v36, 0xbc000000, v22
	v_pk_add_f32 v[2:3], v[2:3], v[2:3] op_sel_hi:[0,1]
	v_pk_mul_f32 v[4:5], v[36:37], v[36:37]
	v_pk_mul_f32 v[14:15], v[38:39], v[38:39]
	v_fmac_f32_e32 v34, 0xbc000000, v22
	v_pk_mov_b32 v[18:19], v[14:15], v[4:5] op_sel:[1,0]
	v_mov_b32_e32 v15, v5
	v_fmac_f32_e32 v32, 0xbc000000, v22
	v_fmamk_f32 v35, v22, 0xbc000000, v35
	v_mul_f32_e32 v2, v34, v34
	v_pk_add_f32 v[4:5], v[18:19], v[14:15]
	v_fmamk_f32 v33, v22, 0xbc000000, v33
	v_pk_fma_f32 v[14:15], v[34:35], v[34:35], v[2:3] op_sel_hi:[1,1,0]
	v_mul_f32_e32 v2, v32, v32
	v_pk_add_f32 v[4:5], v[4:5], v[4:5] op_sel_hi:[0,1]
	v_pk_fma_f32 v[18:19], v[32:33], v[32:33], v[2:3] op_sel_hi:[1,1,0]
	v_fmamk_f32 v29, v22, 0xbc000000, v29
	v_fmac_f32_e32 v28, 0xbc000000, v22
	v_fmamk_f32 v31, v22, 0xbc000000, v31
	v_fmac_f32_e32 v30, 0xbc000000, v22
	v_mul_f32_e32 v14, v30, v30
	v_mul_f32_e32 v18, v31, v31
	v_mul_f32_e32 v4, v28, v28
	v_mul_f32_e32 v2, v29, v29
	v_pk_add_f32 v[14:15], v[14:15], v[18:19]
	v_pk_add_f32 v[2:3], v[4:5], v[2:3]
	v_fmamk_f32 v27, v22, 0xbc000000, v27
	v_pk_add_f32 v[2:3], v[14:15], v[2:3]
	v_fmac_f32_e32 v26, 0xbc000000, v22
	v_fmamk_f32 v17, v22, 0xbc000000, v17
	v_fmac_f32_e32 v16, 0xbc000000, v22
	v_pk_add_f32 v[2:3], v[2:3], v[2:3] op_sel_hi:[0,1]
	v_pk_mul_f32 v[4:5], v[16:17], v[16:17]
	v_pk_mul_f32 v[14:15], v[26:27], v[26:27]
	v_fmac_f32_e32 v12, 0xbc000000, v22
	v_pk_mov_b32 v[18:19], v[14:15], v[4:5] op_sel:[1,0]
	v_mov_b32_e32 v15, v5
	v_fmac_f32_e32 v10, 0xbc000000, v22
	v_fmamk_f32 v13, v22, 0xbc000000, v13
	v_mul_f32_e32 v2, v12, v12
	v_pk_add_f32 v[4:5], v[18:19], v[14:15]
	v_fmamk_f32 v11, v22, 0xbc000000, v11
	v_pk_fma_f32 v[14:15], v[12:13], v[12:13], v[2:3] op_sel_hi:[1,1,0]
	v_mul_f32_e32 v2, v10, v10
	v_pk_add_f32 v[4:5], v[4:5], v[4:5] op_sel_hi:[0,1]
	v_pk_fma_f32 v[18:19], v[10:11], v[10:11], v[2:3] op_sel_hi:[1,1,0]
	v_fmamk_f32 v7, v22, 0xbc000000, v7
	v_fmac_f32_e32 v6, 0xbc000000, v22
	v_fmamk_f32 v9, v22, 0xbc000000, v9
	v_fmac_f32_e32 v8, 0xbc000000, v22
	v_mul_f32_e32 v14, v8, v8
	v_mul_f32_e32 v18, v9, v9
	v_mul_f32_e32 v4, v6, v6
	v_mul_f32_e32 v2, v7, v7
	v_pk_add_f32 v[14:15], v[14:15], v[18:19]
	v_pk_add_f32 v[2:3], v[4:5], v[2:3]
	s_nop 0
	v_pk_add_f32 v[2:3], v[14:15], v[2:3]
	s_nop 0
	v_add_f32_e32 v2, v2, v3
	s_waitcnt lgkmcnt(0)
	v_mov_b32_e32 v3, v2
	s_nop 1
	v_permlane16_swap_b32_e32 v2, v3
	v_add_f32_e32 v2, v2, v3
	v_mov_b32_e32 v3, v2
	s_nop 1
	v_permlane32_swap_b32_e32 v2, v3
	v_add_f32_e32 v2, v2, v3
	v_fmamk_f32 v2, v2, 0x3c000000, v236
	v_cmp_gt_f32_e32 vcc, s68, v2
	v_mul_f32_e32 v3, 0x4f800000, v2
	s_nop 0
	v_cndmask_b32_e32 v2, v2, v3, vcc
	v_sqrt_f32_e32 v3, v2
	s_nop 0
	v_add_u32_e32 v4, -1, v3
	v_fma_f32 v5, -v4, v3, v2
	v_cmp_ge_f32_e64 s[40:41], 0, v5
	v_add_u32_e32 v5, 1, v3
	s_nop 0
	v_cndmask_b32_e64 v4, v3, v4, s[40:41]
	v_fma_f32 v3, -v5, v3, v2
	v_cmp_lt_f32_e64 s[40:41], 0, v3
	s_nop 1
	v_cndmask_b32_e64 v3, v4, v5, s[40:41]
	v_mul_f32_e32 v4, 0x37800000, v3
	v_cndmask_b32_e32 v3, v3, v4, vcc
	v_cmp_class_f32_e32 vcc, v2, v234
	s_nop 1
	v_cndmask_b32_e32 v2, v3, v2, vcc
	v_div_scale_f32 v3, s[22:23], v2, v2, 1.0
	v_rcp_f32_e32 v4, v3
	s_nop 0
	v_fma_f32 v5, -v3, v4, 1.0
	v_fmac_f32_e32 v4, v5, v4
	v_div_scale_f32 v5, vcc, 1.0, v2, 1.0
	v_mul_f32_e32 v14, v5, v4
	v_fma_f32 v15, -v3, v14, v5
	v_fmac_f32_e32 v14, v15, v4
	v_fma_f32 v3, -v3, v14, v5
	v_div_fmas_f32 v3, v3, v4, v14
	v_lshl_add_u64 v[4:5], s[46:47], 0, v[66:67]
	v_div_fixup_f32 v14, v3, v2, 1.0
	v_mov_b64_e32 v[2:3], s[56:57]
	v_lshlrev_b64 v[4:5], 12, v[4:5]
	v_mad_i64_i32 v[2:3], s[22:23], v66, s61, v[2:3]
	v_lshl_add_u64 v[4:5], s[44:45], 0, v[4:5]
	v_lshl_add_u64 v[2:3], v[2:3], 0, v[0:1]
	s_mov_b64 s[22:23], 0x1200
	v_lshl_add_u64 v[4:5], v[4:5], 0, s[52:53]
	v_lshl_add_u64 v[20:21], v[2:3], 0, s[22:23]
	v_lshl_add_u64 v[22:23], v[4:5], 0, v[0:1]
	s_mov_b64 s[22:23], 0x29600000
	v_lshl_add_u64 v[18:19], v[22:23], 0, s[22:23]
	s_lshl_b64 s[22:23], s[50:51], 2
	v_add_co_u32_e32 v2, vcc, s62, v2
	s_add_u32 s40, s20, s22
	s_nop 0
	v_addc_co_u32_e32 v3, vcc, 0, v3, vcc
	s_addc_u32 s41, s35, s23
	global_load_dwordx2 v[120:121], v[2:3], off offset:512
	global_load_dwordx4 v[122:125], v69, s[40:41]
	global_load_dwordx2 v[126:127], v[20:21], off offset:32
	global_load_dwordx4 v[128:131], v69, s[40:41] offset:64
	global_load_dwordx2 v[132:133], v[20:21], off offset:64
	global_load_dwordx4 v[134:137], v69, s[40:41] offset:128
	global_load_dwordx2 v[138:139], v[20:21], off offset:96
	global_load_dwordx4 v[140:143], v69, s[40:41] offset:192
	global_load_dwordx2 v[144:145], v[20:21], off offset:128
	global_load_dwordx4 v[146:149], v69, s[40:41] offset:256
	global_load_dwordx2 v[150:151], v[20:21], off offset:160
	global_load_dwordx4 v[152:155], v69, s[40:41] offset:320
	global_load_dwordx2 v[156:157], v[20:21], off offset:192
	global_load_dwordx4 v[158:161], v69, s[40:41] offset:384
	global_load_dwordx2 v[162:163], v[20:21], off offset:224
	global_load_dwordx4 v[164:167], v69, s[40:41] offset:448
	s_nop 0
	s_mov_b32 s20, 0x29600000
	s_waitcnt vmcnt(0)
; __device__ __forceinline__ unsigned pk2(float lo, float hi) { return pg8::cvt_pk_bf16(lo, hi); }
; __device__ __forceinline__ float silu_f(float g) { return g * frcp(1.f + fexp2(-LOG2E * g)); }
; __device__ __forceinline__ void ret_unit(LAS unsigned char* lds, const bfu* PROJ, const bfu* RT, const float* gn_g, bfu* CAT, int u) {
;     ...
;     for (int t = 0; t < 8; ++t) { const v2u gw = *(const v2u*)(gp + 16 * t); const f32x4 g4 = *(const f32x4*)(gg + 16 * t);
;         const float o0 = silu_f(bflo(gw.x)) * acc[t][0] * rstd * g4.x, o1 = silu_f(bfhi(gw.x)) * acc[t][1] * rstd * g4.y, o2 = silu_f(bflo(gw.y)) * acc[t][2] * rstd * g4.z, o3 = silu_f(bfhi(gw.y)) * acc[t][3] * rstd * g4.w;
;         v2u w; w.x = pk2(o0, o1); w.y = pk2(o2, o3); *(v2u*)(op + 16 * t) = w; }
	v_lshlrev_b32_e32 v48, 16, v120
	v_mul_f32_e32 v0, 0xbfb8aa3b, v48
	v_exp_f32_e32 v0, v0
	v_and_b32_e32 v49, 0xffff0000, v120
	v_lshlrev_b32_e32 v24, 16, v121
	v_and_b32_e32 v25, 0xffff0000, v121
	v_add_f32_e32 v0, 1.0, v0
	v_rcp_f32_e32 v50, v0
	v_mul_f32_e32 v0, 0xbfb8aa3b, v49
	v_exp_f32_e32 v0, v0
	s_nop 0
	v_add_f32_e32 v0, 1.0, v0
	v_rcp_f32_e32 v51, v0
	v_mul_f32_e32 v0, 0xbfb8aa3b, v24
	v_exp_f32_e32 v0, v0
	v_pk_mul_f32 v[48:49], v[50:51], v[48:49]
	s_nop 0
	v_pk_mul_f32 v[46:47], v[46:47], v[48:49]
	v_add_f32_e32 v0, 1.0, v0
	v_pk_mul_f32 v[46:47], v[46:47], v[14:15] op_sel_hi:[1,0]
	v_pk_mul_f32 v[2:3], v[122:123], v[46:47]
	v_rcp_f32_e32 v46, v0
	v_mul_f32_e32 v0, 0xbfb8aa3b, v25
	v_exp_f32_e32 v0, v0
	v_cvt_pk_bf16_f32 v2, v2, v3
	v_add_f32_e32 v0, 1.0, v0
	v_rcp_f32_e32 v47, v0
	s_nop 0
	v_pk_mul_f32 v[24:25], v[46:47], v[24:25]
	s_nop 0
	v_pk_mul_f32 v[24:25], v[44:45], v[24:25]
	s_nop 0
	v_pk_mul_f32 v[24:25], v[24:25], v[14:15] op_sel_hi:[1,0]
	s_nop 0
	v_pk_mul_f32 v[4:5], v[124:125], v[24:25]
	s_nop 0
	v_cvt_pk_bf16_f32 v3, v4, v5
	v_add_co_u32_e32 v4, vcc, s20, v22
	s_nop 1
	v_addc_co_u32_e32 v5, vcc, 0, v23, vcc
	global_store_dwordx2 v[4:5], v[2:3], off
	s_nop 0
	v_lshlrev_b32_e32 v24, 16, v126
	v_mul_f32_e32 v0, 0xbfb8aa3b, v24
	v_exp_f32_e32 v0, v0
	v_and_b32_e32 v25, 0xffff0000, v126
	v_lshlrev_b32_e32 v22, 16, v127
	v_and_b32_e32 v23, 0xffff0000, v127
	v_add_f32_e32 v0, 1.0, v0
	v_rcp_f32_e32 v44, v0
	v_mul_f32_e32 v0, 0xbfb8aa3b, v25
	v_exp_f32_e32 v0, v0
	s_nop 0
	v_add_f32_e32 v0, 1.0, v0
	v_rcp_f32_e32 v45, v0
	v_mul_f32_e32 v0, 0xbfb8aa3b, v22
	v_exp_f32_e32 v0, v0
	v_pk_mul_f32 v[24:25], v[44:45], v[24:25]
	s_nop 0
	v_pk_mul_f32 v[24:25], v[42:43], v[24:25]
	v_add_f32_e32 v0, 1.0, v0
	v_pk_mul_f32 v[24:25], v[24:25], v[14:15] op_sel_hi:[1,0]
	v_pk_mul_f32 v[2:3], v[128:129], v[24:25]
	v_rcp_f32_e32 v24, v0
	v_mul_f32_e32 v0, 0xbfb8aa3b, v23
	v_exp_f32_e32 v0, v0
	v_cvt_pk_bf16_f32 v2, v2, v3
	v_add_f32_e32 v0, 1.0, v0
	v_rcp_f32_e32 v25, v0
	s_nop 0
	v_pk_mul_f32 v[22:23], v[24:25], v[22:23]
	s_nop 0
	v_pk_mul_f32 v[22:23], v[40:41], v[22:23]
	s_nop 0
	v_pk_mul_f32 v[22:23], v[22:23], v[14:15] op_sel_hi:[1,0]
	s_nop 0
	v_pk_mul_f32 v[4:5], v[130:131], v[22:23]
	s_nop 0
	v_cvt_pk_bf16_f32 v3, v4, v5
	global_store_dwordx2 v[18:19], v[2:3], off offset:32
	s_nop 0
	v_lshlrev_b32_e32 v24, 16, v132
	v_mul_f32_e32 v0, 0xbfb8aa3b, v24
	v_exp_f32_e32 v0, v0
	v_and_b32_e32 v25, 0xffff0000, v132
	v_lshlrev_b32_e32 v22, 16, v133
	v_and_b32_e32 v23, 0xffff0000, v133
	v_add_f32_e32 v0, 1.0, v0
	v_rcp_f32_e32 v40, v0
	v_mul_f32_e32 v0, 0xbfb8aa3b, v25
	v_exp_f32_e32 v0, v0
	s_nop 0
	v_add_f32_e32 v0, 1.0, v0
	v_rcp_f32_e32 v41, v0
	v_mul_f32_e32 v0, 0xbfb8aa3b, v22
	v_exp_f32_e32 v0, v0
	v_pk_mul_f32 v[24:25], v[40:41], v[24:25]
	s_nop 0
	v_pk_mul_f32 v[24:25], v[38:39], v[24:25]
	v_add_f32_e32 v0, 1.0, v0
	v_pk_mul_f32 v[24:25], v[24:25], v[14:15] op_sel_hi:[1,0]
	v_pk_mul_f32 v[2:3], v[134:135], v[24:25]
	v_rcp_f32_e32 v24, v0
	v_mul_f32_e32 v0, 0xbfb8aa3b, v23
	v_exp_f32_e32 v0, v0
	v_cvt_pk_bf16_f32 v2, v2, v3
	v_add_f32_e32 v0, 1.0, v0
	v_rcp_f32_e32 v25, v0
	s_nop 0
	v_pk_mul_f32 v[22:23], v[24:25], v[22:23]
	s_nop 0
	v_pk_mul_f32 v[22:23], v[36:37], v[22:23]
	s_nop 0
	v_pk_mul_f32 v[22:23], v[22:23], v[14:15] op_sel_hi:[1,0]
	s_nop 0
	v_pk_mul_f32 v[4:5], v[136:137], v[22:23]
	s_nop 0
	v_cvt_pk_bf16_f32 v3, v4, v5
	global_store_dwordx2 v[18:19], v[2:3], off offset:64
	s_nop 0
	v_lshlrev_b32_e32 v24, 16, v138
	v_mul_f32_e32 v0, 0xbfb8aa3b, v24
	v_exp_f32_e32 v0, v0
	v_and_b32_e32 v25, 0xffff0000, v138
	v_lshlrev_b32_e32 v22, 16, v139
	v_and_b32_e32 v23, 0xffff0000, v139
	v_add_f32_e32 v0, 1.0, v0
	v_rcp_f32_e32 v36, v0
	v_mul_f32_e32 v0, 0xbfb8aa3b, v25
	v_exp_f32_e32 v0, v0
	s_nop 0
	v_add_f32_e32 v0, 1.0, v0
	v_rcp_f32_e32 v37, v0
	v_mul_f32_e32 v0, 0xbfb8aa3b, v22
	v_exp_f32_e32 v0, v0
	v_pk_mul_f32 v[24:25], v[36:37], v[24:25]
	s_nop 0
	v_pk_mul_f32 v[24:25], v[34:35], v[24:25]
	v_add_f32_e32 v0, 1.0, v0
	v_pk_mul_f32 v[24:25], v[24:25], v[14:15] op_sel_hi:[1,0]
	v_pk_mul_f32 v[2:3], v[140:141], v[24:25]
	v_rcp_f32_e32 v24, v0
	v_mul_f32_e32 v0, 0xbfb8aa3b, v23
	v_exp_f32_e32 v0, v0
	v_cvt_pk_bf16_f32 v2, v2, v3
	v_add_f32_e32 v0, 1.0, v0
	v_rcp_f32_e32 v25, v0
	s_nop 0
	v_pk_mul_f32 v[22:23], v[24:25], v[22:23]
	s_nop 0
	v_pk_mul_f32 v[22:23], v[32:33], v[22:23]
	s_nop 0
	v_pk_mul_f32 v[22:23], v[22:23], v[14:15] op_sel_hi:[1,0]
	s_nop 0
	v_pk_mul_f32 v[4:5], v[142:143], v[22:23]
	s_nop 0
	v_cvt_pk_bf16_f32 v3, v4, v5
	global_store_dwordx2 v[18:19], v[2:3], off offset:96
; __device__ __forceinline__ unsigned pk2(float lo, float hi) { return pg8::cvt_pk_bf16(lo, hi); }
; __device__ __forceinline__ float silu_f(float g) { return g * frcp(1.f + fexp2(-LOG2E * g)); }
; __device__ __forceinline__ void ret_unit(LAS unsigned char* lds, const bfu* PROJ, const bfu* RT, const float* gn_g, bfu* CAT, int u) {
;     ...
;     for (int t = 0; t < 8; ++t) { const v2u gw = *(const v2u*)(gp + 16 * t); const f32x4 g4 = *(const f32x4*)(gg + 16 * t);
;         const float o0 = silu_f(bflo(gw.x)) * acc[t][0] * rstd * g4.x, o1 = silu_f(bfhi(gw.x)) * acc[t][1] * rstd * g4.y, o2 = silu_f(bflo(gw.y)) * acc[t][2] * rstd * g4.z, o3 = silu_f(bfhi(gw.y)) * acc[t][3] * rstd * g4.w;
;         v2u w; w.x = pk2(o0, o1); w.y = pk2(o2, o3); *(v2u*)(op + 16 * t) = w; }
;     __syncthreads();
	s_nop 0
	v_lshlrev_b32_e32 v24, 16, v144
	v_mul_f32_e32 v0, 0xbfb8aa3b, v24
	v_exp_f32_e32 v0, v0
	v_and_b32_e32 v25, 0xffff0000, v144
	v_lshlrev_b32_e32 v22, 16, v145
	v_and_b32_e32 v23, 0xffff0000, v145
	v_add_f32_e32 v0, 1.0, v0
	v_rcp_f32_e32 v32, v0
	v_mul_f32_e32 v0, 0xbfb8aa3b, v25
	v_exp_f32_e32 v0, v0
	s_nop 0
	v_add_f32_e32 v0, 1.0, v0
	v_rcp_f32_e32 v33, v0
	v_mul_f32_e32 v0, 0xbfb8aa3b, v22
	v_exp_f32_e32 v0, v0
	v_pk_mul_f32 v[24:25], v[32:33], v[24:25]
	s_nop 0
	v_pk_mul_f32 v[24:25], v[30:31], v[24:25]
	v_add_f32_e32 v0, 1.0, v0
	v_pk_mul_f32 v[24:25], v[24:25], v[14:15] op_sel_hi:[1,0]
	v_pk_mul_f32 v[2:3], v[146:147], v[24:25]
	v_rcp_f32_e32 v24, v0
	v_mul_f32_e32 v0, 0xbfb8aa3b, v23
	v_exp_f32_e32 v0, v0
	v_cvt_pk_bf16_f32 v2, v2, v3
	v_add_f32_e32 v0, 1.0, v0
	v_rcp_f32_e32 v25, v0
	s_nop 0
	v_pk_mul_f32 v[22:23], v[24:25], v[22:23]
	s_nop 0
	v_pk_mul_f32 v[22:23], v[28:29], v[22:23]
	s_nop 0
	v_pk_mul_f32 v[22:23], v[22:23], v[14:15] op_sel_hi:[1,0]
	s_nop 0
	v_pk_mul_f32 v[4:5], v[148:149], v[22:23]
	s_nop 0
	v_cvt_pk_bf16_f32 v3, v4, v5
	global_store_dwordx2 v[18:19], v[2:3], off offset:128
	s_nop 0
	v_lshlrev_b32_e32 v24, 16, v150
	v_mul_f32_e32 v0, 0xbfb8aa3b, v24
	v_exp_f32_e32 v0, v0
	v_and_b32_e32 v25, 0xffff0000, v150
	v_lshlrev_b32_e32 v22, 16, v151
	v_and_b32_e32 v23, 0xffff0000, v151
	v_add_f32_e32 v0, 1.0, v0
	v_rcp_f32_e32 v28, v0
	v_mul_f32_e32 v0, 0xbfb8aa3b, v25
	v_exp_f32_e32 v0, v0
	s_nop 0
	v_add_f32_e32 v0, 1.0, v0
	v_rcp_f32_e32 v29, v0
	v_mul_f32_e32 v0, 0xbfb8aa3b, v22
	v_exp_f32_e32 v0, v0
	v_pk_mul_f32 v[24:25], v[28:29], v[24:25]
	s_nop 0
	v_pk_mul_f32 v[24:25], v[26:27], v[24:25]
	v_add_f32_e32 v0, 1.0, v0
	v_pk_mul_f32 v[24:25], v[14:15], v[24:25] op_sel_hi:[0,1]
	v_pk_mul_f32 v[2:3], v[152:153], v[24:25]
	v_rcp_f32_e32 v24, v0
	v_mul_f32_e32 v0, 0xbfb8aa3b, v23
	v_exp_f32_e32 v0, v0
	v_cvt_pk_bf16_f32 v2, v2, v3
	v_add_f32_e32 v0, 1.0, v0
	v_rcp_f32_e32 v25, v0
	s_nop 0
	v_pk_mul_f32 v[22:23], v[24:25], v[22:23]
	s_nop 0
	v_pk_mul_f32 v[16:17], v[16:17], v[22:23]
	s_nop 0
	v_pk_mul_f32 v[16:17], v[14:15], v[16:17] op_sel_hi:[0,1]
	v_pk_mul_f32 v[4:5], v[154:155], v[16:17]
	s_nop 0
	v_cvt_pk_bf16_f32 v3, v4, v5
	global_store_dwordx2 v[18:19], v[2:3], off offset:160
	s_nop 0
	v_lshlrev_b32_e32 v22, 16, v156
	v_mul_f32_e32 v0, 0xbfb8aa3b, v22
	v_exp_f32_e32 v0, v0
	v_and_b32_e32 v23, 0xffff0000, v156
	v_add_f32_e32 v0, 1.0, v0
	v_rcp_f32_e32 v24, v0
	v_mul_f32_e32 v0, 0xbfb8aa3b, v23
	v_exp_f32_e32 v0, v0
	s_nop 0
	v_add_f32_e32 v0, 1.0, v0
	v_rcp_f32_e32 v25, v0
	s_nop 0
	v_pk_mul_f32 v[22:23], v[24:25], v[22:23]
	s_nop 0
	v_pk_mul_f32 v[12:13], v[12:13], v[22:23]
	s_nop 0
	v_pk_mul_f32 v[12:13], v[14:15], v[12:13] op_sel_hi:[0,1]
	v_pk_mul_f32 v[2:3], v[158:159], v[12:13]
	v_lshlrev_b32_e32 v12, 16, v157
	v_mul_f32_e32 v0, 0xbfb8aa3b, v12
	v_exp_f32_e32 v0, v0
	v_and_b32_e32 v13, 0xffff0000, v157
	v_cvt_pk_bf16_f32 v2, v2, v3
	v_add_f32_e32 v0, 1.0, v0
	v_rcp_f32_e32 v16, v0
	v_mul_f32_e32 v0, 0xbfb8aa3b, v13
	v_exp_f32_e32 v0, v0
	s_nop 0
	v_add_f32_e32 v0, 1.0, v0
	v_rcp_f32_e32 v17, v0
	s_nop 0
	v_pk_mul_f32 v[12:13], v[16:17], v[12:13]
	s_nop 0
	v_pk_mul_f32 v[10:11], v[10:11], v[12:13]
	s_nop 0
	v_pk_mul_f32 v[10:11], v[14:15], v[10:11] op_sel_hi:[0,1]
	v_pk_mul_f32 v[4:5], v[160:161], v[10:11]
	s_nop 0
	v_cvt_pk_bf16_f32 v3, v4, v5
	global_store_dwordx2 v[18:19], v[2:3], off offset:192
	s_nop 0
	v_lshlrev_b32_e32 v12, 16, v162
	v_mul_f32_e32 v0, 0xbfb8aa3b, v12
	v_exp_f32_e32 v0, v0
	v_and_b32_e32 v13, 0xffff0000, v162
	v_add_f32_e32 v0, 1.0, v0
	v_rcp_f32_e32 v16, v0
	v_mul_f32_e32 v0, 0xbfb8aa3b, v13
	v_exp_f32_e32 v0, v0
	s_nop 0
	v_add_f32_e32 v0, 1.0, v0
	v_rcp_f32_e32 v17, v0
	s_nop 0
	v_pk_mul_f32 v[12:13], v[16:17], v[12:13]
	s_nop 0
	v_pk_mul_f32 v[8:9], v[8:9], v[12:13]
	s_nop 0
	v_pk_mul_f32 v[8:9], v[14:15], v[8:9] op_sel_hi:[0,1]
	v_pk_mul_f32 v[2:3], v[164:165], v[8:9]
	v_lshlrev_b32_e32 v8, 16, v163
	v_mul_f32_e32 v0, 0xbfb8aa3b, v8
	v_exp_f32_e32 v0, v0
	v_and_b32_e32 v9, 0xffff0000, v163
	v_cvt_pk_bf16_f32 v2, v2, v3
	v_add_f32_e32 v0, 1.0, v0
	v_rcp_f32_e32 v10, v0
	v_mul_f32_e32 v0, 0xbfb8aa3b, v9
	v_exp_f32_e32 v0, v0
	s_nop 0
	v_add_f32_e32 v0, 1.0, v0
	v_rcp_f32_e32 v11, v0
	s_nop 0
	v_pk_mul_f32 v[8:9], v[10:11], v[8:9]
	s_nop 0
	v_pk_mul_f32 v[6:7], v[6:7], v[8:9]
	s_nop 0
	v_pk_mul_f32 v[6:7], v[14:15], v[6:7] op_sel_hi:[0,1]
	v_pk_mul_f32 v[4:5], v[166:167], v[6:7]
	s_nop 0
	v_cvt_pk_bf16_f32 v3, v4, v5
	global_store_dwordx2 v[18:19], v[2:3], off offset:224
	s_barrier

; #define LAS __attribute__((address_space(3)))
; __device__ __forceinline__ float gelu_tanh(float x) { const float z = 0.7978845608028654f * (x + 0.044715f * x * x * x); return x * frcp(1.f + fexp2(-2.f * LOG2E * z)); }
; __device__ __forceinline__ void stage_nat(LAS bfu* dst, const bfu* src, int pitch, int tid) {
; #pragma unroll
;     for (int i = 0; i < 4; ++i) { const int id = tid + NTHR * i, r = id >> 4, ch = id & 15; const v4u v = *(const v4u*)(src + (size_t)r * pitch + ch * 8); *(LAS v4u*)(dst + r * TS + ch * 8) = v; }
; }
; __device__ __forceinline__ void sgu_unit(LAS unsigned char* lds, const bfu* PROJ, const bfu* SW  , const float* ln_g, const float* ln_b, const float* sb, bfu* CAT, int s) {
;     ...
;     stage_nat(Ws, SW + (size_t)g * 16384, 128, tid);
;     const int sr = tid & 127, qd = tid >> 7;
;     const bfu* vp = PROJ + (row0 + sr) * INW + C_SV + g * 128 + qd * 32; float v[32]; float a = 0.f, a2 = 0.f;
; #pragma unroll
;     for (int k = 0; k < 4; ++k) { const v4u w = *(const v4u*)(vp + 8 * k);
; #pragma unroll
;         for (int j = 0; j < 4; ++j) { const float x0 = gelu_tanh(bflo(w[j])), x1 = gelu_tanh(bfhi(w[j])); v[8 * k + 2 * j] = x0; v[8 * k + 2 * j + 1] = x1; a += x0 + x1; a2 += x0 * x0 + x1 * x1; } }
.LBB0_422:
	s_mov_b32 s22, 21
	s_ashr_i32 s23, s22, 31
	s_lshl_b64 s[22:23], s[22:23], 3
	s_add_u32 s22, s0, s22
	s_addc_u32 s23, s1, s23
	s_load_dwordx2 s[22:23], s[22:23], 0x0
	s_mov_b32 s34, 21
	s_mov_b32 s46, 12
	s_mov_b32 s48, 21
	s_waitcnt lgkmcnt(0)
	s_add_u32 s44, s22, 0x1ce00000
	s_addc_u32 s45, s23, 0
	s_ashr_i32 s35, s34, 31
	s_lshl_b64 s[22:23], s[34:35], 3
	s_add_u32 s22, s0, s22
	s_addc_u32 s23, s1, s23
	s_load_dwordx2 s[22:23], s[22:23], 0x0
	s_mov_b32 s34, 9
	v_mov_b32_e32 v16, v232
	s_movk_i32 s56, 0x2000
	s_waitcnt lgkmcnt(0)
	s_add_u32 s20, s22, s55
	s_addc_u32 s53, s23, 0
	s_ashr_i32 s35, s34, 31
	s_lshl_b64 s[22:23], s[34:35], 3
	s_add_u32 s22, s0, s22
	s_addc_u32 s23, s1, s23
	s_load_dwordx2 s[22:23], s[22:23], 0x0
	s_mov_b32 s34, 10
	s_waitcnt lgkmcnt(0)
	s_add_u32 s22, s22, s26
	s_addc_u32 s23, s23, s27
	s_ashr_i32 s35, s34, 31
	s_lshl_b64 s[34:35], s[34:35], 3
	s_add_u32 s34, s0, s34
	s_addc_u32 s35, s1, s35
	s_load_dwordx2 s[40:41], s[34:35], 0x0
	s_waitcnt lgkmcnt(0)
	s_add_u32 s35, s40, s26
	s_addc_u32 s40, s41, s27
	s_ashr_i32 s47, s46, 31
	s_lshl_b64 s[46:47], s[46:47], 3
	s_add_u32 s46, s0, s46
	s_addc_u32 s47, s1, s47
	s_load_dwordx2 s[46:47], s[46:47], 0x0
	s_waitcnt lgkmcnt(0)
	s_add_u32 s50, s46, s26
	s_addc_u32 s51, s47, s27
	s_ashr_i32 s49, s48, 31
	s_lshl_b64 s[46:47], s[48:49], 3
	s_add_u32 s46, s0, s46
	s_addc_u32 s47, s1, s47
	s_lshl_b32 s41, s92, 5
	s_and_b32 s34, s92, 3
	s_and_b32 s41, s41, 0x3f80
	s_xor_b32 s52, s41, 0x2000
	s_lshl_b32 s41, s34, 15
	s_load_dwordx2 s[46:47], s[46:47], 0x0
	s_add_u32 s48, s20, s41
	v_lshlrev_b32_e32 v0, 4, v16
	s_addc_u32 s49, s53, 0
	v_and_b32_e32 v0, 0xf0, v0
	v_lshl_add_u64 v[2:3], s[48:49], 0, v[0:1]
	v_add_u32_e32 v4, 0, v0
	v_ashrrev_i32_e32 v6, 4, v16
	v_add_u32_e32 v0, 0x200, v16
	s_mov_b64 s[48:49], 0x100000
	v_ashrrev_i32_e32 v7, 31, v6
	v_ashrrev_i32_e32 v10, 4, v0
	v_lshl_add_u64 v[2:3], v[2:3], 0, s[48:49]
	v_lshlrev_b64 v[8:9], 8, v[6:7]
	v_ashrrev_i32_e32 v11, 31, v10
	v_lshl_add_u64 v[8:9], v[2:3], 0, v[8:9]
	v_lshlrev_b64 v[12:13], 8, v[10:11]
	v_add_u32_e32 v0, 0x400, v16
	v_lshl_add_u64 v[12:13], v[2:3], 0, v[12:13]
	global_load_dwordx4 v[20:23], v[8:9], off
	global_load_dwordx4 v[24:27], v[12:13], off
	v_ashrrev_i32_e32 v8, 4, v0
	v_add_u32_e32 v0, 0x600, v16
	v_ashrrev_i32_e32 v36, 4, v0
	v_ashrrev_i32_e32 v9, 31, v8
	v_ashrrev_i32_e32 v37, 31, v36
	v_and_b32_e32 v18, 0x7f, v16
	v_lshlrev_b64 v[12:13], 8, v[8:9]
	v_lshlrev_b64 v[14:15], 8, v[36:37]
	v_or_b32_e32 v0, s52, v18
	v_lshl_add_u64 v[12:13], v[2:3], 0, v[12:13]
	v_lshl_add_u64 v[2:3], v[2:3], 0, v[14:15]
	v_mul_u32_u24_e32 v0, 0x3200, v0
	v_ashrrev_i32_e32 v17, 2, v16
	global_load_dwordx4 v[28:31], v[12:13], off
	global_load_dwordx4 v[32:35], v[2:3], off
	v_lshl_add_u64 v[2:3], s[44:45], 0, v[0:1]
	s_lshl_b32 s20, s34, 8
	v_and_b32_e32 v14, 0xffffffe0, v17
	v_lshl_add_u64 v[2:3], v[2:3], 0, s[20:21]
	v_ashrrev_i32_e32 v15, 31, v14
	v_lshl_add_u64 v[2:3], v[14:15], 1, v[2:3]
	v_add_co_u32_e32 v12, vcc, s56, v2
	v_mad_u64_u32 v[38:39], s[48:49], v6, s65, v[4:5]
	s_nop 0
	v_addc_co_u32_e32 v13, vcc, 0, v3, vcc
	global_load_dwordx4 v[40:43], v[12:13], off offset:3584
	v_mad_u64_u32 v[44:45], s[48:49], v10, s65, v[4:5]
	v_mad_u64_u32 v[46:47], s[48:49], v8, s65, v[4:5]
	v_mad_u64_u32 v[36:37], s[48:49], v36, s65, v[4:5]
	s_mov_b64 s[48:49], 0x2e00
	s_nop 0
	v_lshl_add_u64 v[10:11], v[2:3], 0, s[48:49]
	global_load_dwordx4 v[2:5], v[10:11], off offset:48
	global_load_dwordx4 v[6:9], v[10:11], off offset:32
	s_nop 0
	global_load_dwordx4 v[10:13], v[10:11], off offset:16
	s_lshl_b32 s41, s34, 9
	s_add_u32 s22, s22, s41
	s_addc_u32 s23, s23, 0
	s_mov_b32 s53, s21
	s_waitcnt vmcnt(0)
	ds_write_b128 v38, v[20:23]
	s_waitcnt vmcnt(6)
	ds_write_b128 v44, v[24:27]
	s_waitcnt vmcnt(5)
	ds_write_b128 v46, v[28:31]
	s_waitcnt vmcnt(4)
	ds_write_b128 v36, v[32:35]
	s_waitcnt vmcnt(3)
	v_and_b32_e32 v26, 0xffff0000, v40
	v_lshlrev_b32_e32 v25, 16, v40
	v_and_b32_e32 v31, 0xffff0000, v41
	v_mul_f32_e32 v19, 0x3d372713, v26
	v_lshlrev_b32_e32 v28, 16, v41
	v_mul_f32_e32 v0, 0x3d372713, v25
	v_mul_f32_e32 v21, 0x3d372713, v31
	v_mul_f32_e32 v19, v19, v26
	v_mul_f32_e32 v20, 0x3d372713, v28
	v_mul_f32_e32 v0, v0, v25
	v_mul_f32_e32 v21, v21, v31
	v_fma_f32 v19, v19, v26, v26
	v_mul_f32_e32 v20, v20, v28
	v_fma_f32 v0, v0, v25, v25
	v_fma_f32 v21, v21, v31, v31
	v_mul_f32_e32 v19, 0x3f4c422a, v19
	v_fma_f32 v20, v20, v28, v28
	v_mul_f32_e32 v0, 0x3f4c422a, v0
	v_mul_f32_e32 v21, 0x3f4c422a, v21
	v_mul_f32_e32 v19, 0xc038aa3b, v19
	v_mul_f32_e32 v20, 0x3f4c422a, v20
	v_mul_f32_e32 v0, 0xc038aa3b, v0
	v_mul_f32_e32 v21, 0xc038aa3b, v21
	v_exp_f32_e32 v19, v19
	v_mul_f32_e32 v20, 0xc038aa3b, v20
	v_exp_f32_e32 v0, v0
	v_exp_f32_e32 v21, v21
	v_exp_f32_e32 v20, v20
	v_add_f32_e32 v19, 1.0, v19
	v_add_f32_e32 v0, 1.0, v0
	v_add_f32_e32 v21, 1.0, v21
	v_rcp_f32_e32 v40, v19
	v_add_f32_e32 v20, 1.0, v20
	v_rcp_f32_e32 v41, v0
	v_rcp_f32_e32 v35, v21
	v_rcp_f32_e32 v38, v20
	v_mul_f32_e32 v19, v40, v26
	v_mul_f32_e32 v0, v41, v25
	v_mul_f32_e32 v21, v35, v31
	v_fma_f32 v20, v41, v25, v19
	v_mul_f32_e32 v24, v19, v19
	v_add_f32_e32 v19, 0, v20
	v_fmac_f32_e32 v24, v0, v0
	v_fma_f32 v0, v38, v28, v21
	v_add_f32_e32 v0, v0, v19
	v_lshlrev_b32_e32 v19, 16, v42
	v_mul_f32_e32 v20, 0x3d372713, v19
	v_mul_f32_e32 v20, v20, v19
	v_fma_f32 v20, v20, v19, v19
	v_mul_f32_e32 v20, 0x3f4c422a, v20
	v_mul_f32_e32 v20, 0xc038aa3b, v20
	v_exp_f32_e32 v22, v20
	v_and_b32_e32 v20, 0xffff0000, v42
	v_mul_f32_e32 v27, 0x3d372713, v20
	v_mul_f32_e32 v27, v27, v20
	v_fma_f32 v27, v27, v20, v20
	v_mul_f32_e32 v27, 0x3f4c422a, v27
	v_mul_f32_e32 v27, 0xc038aa3b, v27
	v_exp_f32_e32 v27, v27
	v_mul_f32_e32 v29, v21, v21
	v_add_f32_e32 v21, 1.0, v22
	v_rcp_f32_e32 v22, v21
	v_add_f32_e32 v21, 1.0, v27
	v_rcp_f32_e32 v21, v21
	v_mul_f32_e32 v23, v38, v28
	v_fmac_f32_e32 v29, v23, v23
	v_add_f32_e32 v30, v24, v29
	v_mul_f32_e32 v27, v21, v20
	v_fma_f32 v23, v22, v19, v27
	v_add_f32_e32 v0, v23, v0
	v_lshlrev_b32_e32 v23, 16, v43
	v_mul_f32_e32 v24, 0x3d372713, v23
	v_mul_f32_e32 v24, v24, v23
	v_fma_f32 v24, v24, v23, v23
	v_mul_f32_e32 v24, 0x3f4c422a, v24
	v_mul_f32_e32 v24, 0xc038aa3b, v24
	v_exp_f32_e32 v29, v24
	v_and_b32_e32 v24, 0xffff0000, v43
	v_mul_f32_e32 v33, 0x3d372713, v24
	v_mul_f32_e32 v33, v33, v24
	v_fma_f32 v33, v33, v24, v24
	v_mul_f32_e32 v33, 0x3f4c422a, v33
	v_mul_f32_e32 v33, 0xc038aa3b, v33
	v_exp_f32_e32 v33, v33
	v_mul_f32_e32 v34, v27, v27
	v_add_f32_e32 v27, 1.0, v29
	v_rcp_f32_e32 v29, v27
	v_add_f32_e32 v27, 1.0, v33
	v_rcp_f32_e32 v27, v27
	v_mul_f32_e32 v32, v22, v19
	v_fmac_f32_e32 v34, v32, v32
	v_add_f32_e32 v34, v34, v30
	v_mul_f32_e32 v32, v27, v24
	v_fma_f32 v30, v29, v23, v32
	v_add_f32_e32 v0, v30, v0
	s_waitcnt vmcnt(0)
; __device__ __forceinline__ float gelu_tanh(float x) { const float z = 0.7978845608028654f * (x + 0.044715f * x * x * x); return x * frcp(1.f + fexp2(-2.f * LOG2E * z)); }
; __device__ __forceinline__ void sgu_unit(LAS unsigned char* lds, const bfu* PROJ, const bfu* SW  , const float* ln_g, const float* ln_b, const float* sb, bfu* CAT, int s) {
;     ...
;     for (int k = 0; k < 4; ++k) { const v4u w = *(const v4u*)(vp + 8 * k);
; #pragma unroll
;         for (int j = 0; j < 4; ++j) { const float x0 = gelu_tanh(bflo(w[j])), x1 = gelu_tanh(bfhi(w[j])); v[8 * k + 2 * j] = x0; v[8 * k + 2 * j + 1] = x1; a += x0 + x1; a2 += x0 * x0 + x1 * x1; } }
	v_lshlrev_b32_e32 v30, 16, v10
	v_mul_f32_e32 v33, 0x3d372713, v30
	v_and_b32_e32 v10, 0xffff0000, v10
	v_mul_f32_e32 v33, v33, v30
	v_mul_f32_e32 v37, 0x3d372713, v10
	v_fma_f32 v33, v33, v30, v30
	v_mul_f32_e32 v37, v37, v10
	v_mul_f32_e32 v33, 0x3f4c422a, v33
	v_fma_f32 v37, v37, v10, v10
	v_mul_f32_e32 v33, 0xc038aa3b, v33
	v_mul_f32_e32 v37, 0x3f4c422a, v37
	v_exp_f32_e32 v33, v33
	v_mul_f32_e32 v37, 0xc038aa3b, v37
	v_exp_f32_e32 v37, v37
	v_mul_f32_e32 v39, v32, v32
	v_add_f32_e32 v32, 1.0, v33
	v_rcp_f32_e32 v33, v32
	v_add_f32_e32 v32, 1.0, v37
	v_rcp_f32_e32 v32, v32
	v_mul_f32_e32 v36, v29, v23
	v_fmac_f32_e32 v39, v36, v36
	v_add_f32_e32 v37, v39, v34
	v_mul_f32_e32 v36, v32, v10
	v_fma_f32 v34, v33, v30, v36
	v_add_f32_e32 v0, v34, v0
	v_lshlrev_b32_e32 v34, 16, v11
	v_mul_f32_e32 v39, 0x3d372713, v34
	v_and_b32_e32 v11, 0xffff0000, v11
	v_mul_f32_e32 v39, v39, v34
	v_mul_f32_e32 v43, 0x3d372713, v11
	v_fma_f32 v39, v39, v34, v34
	v_mul_f32_e32 v43, v43, v11
	v_mul_f32_e32 v39, 0x3f4c422a, v39
	v_fma_f32 v43, v43, v11, v11
	v_mul_f32_e32 v39, 0xc038aa3b, v39
	v_mul_f32_e32 v43, 0x3f4c422a, v43
	v_exp_f32_e32 v39, v39
	v_mul_f32_e32 v43, 0xc038aa3b, v43
	v_exp_f32_e32 v43, v43
	v_mul_f32_e32 v44, v36, v36
	v_add_f32_e32 v36, 1.0, v39
	v_rcp_f32_e32 v39, v36
	v_add_f32_e32 v36, 1.0, v43
	v_rcp_f32_e32 v36, v36
	v_mul_f32_e32 v42, v33, v30
	v_fmac_f32_e32 v44, v42, v42
	v_add_f32_e32 v44, v44, v37
	v_mul_f32_e32 v42, v36, v11
	v_fma_f32 v37, v39, v34, v42
	v_add_f32_e32 v0, v37, v0
	v_lshlrev_b32_e32 v37, 16, v12
	v_mul_f32_e32 v43, 0x3d372713, v37
	v_and_b32_e32 v12, 0xffff0000, v12
	v_mul_f32_e32 v43, v43, v37
	v_mul_f32_e32 v46, 0x3d372713, v12
	v_fma_f32 v43, v43, v37, v37
	v_mul_f32_e32 v46, v46, v12
	v_mul_f32_e32 v43, 0x3f4c422a, v43
	v_fma_f32 v46, v46, v12, v12
	v_mul_f32_e32 v43, 0xc038aa3b, v43
	v_mul_f32_e32 v46, 0x3f4c422a, v46
	v_exp_f32_e32 v43, v43
	v_mul_f32_e32 v46, 0xc038aa3b, v46
	v_exp_f32_e32 v46, v46
	v_mul_f32_e32 v47, v42, v42
	v_add_f32_e32 v42, 1.0, v43
	v_rcp_f32_e32 v43, v42
	v_add_f32_e32 v42, 1.0, v46
	v_rcp_f32_e32 v42, v42
	v_mul_f32_e32 v45, v39, v34
	v_fmac_f32_e32 v47, v45, v45
	v_add_f32_e32 v47, v47, v44
	v_mul_f32_e32 v45, v42, v12
	v_fma_f32 v44, v43, v37, v45
	v_add_f32_e32 v0, v44, v0
	v_lshlrev_b32_e32 v44, 16, v13
	v_mul_f32_e32 v46, 0x3d372713, v44
	v_and_b32_e32 v13, 0xffff0000, v13
	v_mul_f32_e32 v46, v46, v44
	v_mul_f32_e32 v49, 0x3d372713, v13
	v_fma_f32 v46, v46, v44, v44
	v_mul_f32_e32 v49, v49, v13
	v_mul_f32_e32 v46, 0x3f4c422a, v46
	v_fma_f32 v49, v49, v13, v13
	v_mul_f32_e32 v46, 0xc038aa3b, v46
	v_mul_f32_e32 v49, 0x3f4c422a, v49
	v_exp_f32_e32 v46, v46
	v_mul_f32_e32 v49, 0xc038aa3b, v49
	v_exp_f32_e32 v49, v49
	v_mul_f32_e32 v50, v45, v45
	v_add_f32_e32 v45, 1.0, v46
	v_rcp_f32_e32 v46, v45
	v_add_f32_e32 v45, 1.0, v49
	v_rcp_f32_e32 v45, v45
	v_mul_f32_e32 v48, v43, v37
	v_fmac_f32_e32 v50, v48, v48
	v_add_f32_e32 v50, v50, v47
	v_mul_f32_e32 v48, v45, v13
	v_fma_f32 v47, v46, v44, v48
	v_add_f32_e32 v0, v47, v0
	v_lshlrev_b32_e32 v47, 16, v6
	v_mul_f32_e32 v49, 0x3d372713, v47
	v_and_b32_e32 v6, 0xffff0000, v6
	v_mul_f32_e32 v49, v49, v47
	v_mul_f32_e32 v52, 0x3d372713, v6
	v_fma_f32 v49, v49, v47, v47
	v_mul_f32_e32 v52, v52, v6
	v_mul_f32_e32 v49, 0x3f4c422a, v49
	v_fma_f32 v52, v52, v6, v6
	v_mul_f32_e32 v49, 0xc038aa3b, v49
	v_mul_f32_e32 v52, 0x3f4c422a, v52
	v_exp_f32_e32 v49, v49
	v_mul_f32_e32 v52, 0xc038aa3b, v52
	v_exp_f32_e32 v52, v52
	v_mul_f32_e32 v53, v48, v48
	v_add_f32_e32 v48, 1.0, v49
	v_rcp_f32_e32 v49, v48
	v_add_f32_e32 v48, 1.0, v52
	v_rcp_f32_e32 v48, v48
	v_mul_f32_e32 v51, v46, v44
	v_fmac_f32_e32 v53, v51, v51
	v_add_f32_e32 v53, v53, v50
	v_mul_f32_e32 v51, v48, v6
	v_fma_f32 v50, v49, v47, v51
	v_add_f32_e32 v0, v50, v0
	v_lshlrev_b32_e32 v50, 16, v7
	v_mul_f32_e32 v52, 0x3d372713, v50
	v_and_b32_e32 v7, 0xffff0000, v7
	v_mul_f32_e32 v52, v52, v50
	v_mul_f32_e32 v55, 0x3d372713, v7
	v_fma_f32 v52, v52, v50, v50
	v_mul_f32_e32 v55, v55, v7
	v_mul_f32_e32 v52, 0x3f4c422a, v52
	v_fma_f32 v55, v55, v7, v7
	v_mul_f32_e32 v52, 0xc038aa3b, v52
	v_mul_f32_e32 v55, 0x3f4c422a, v55
	v_exp_f32_e32 v52, v52
	v_mul_f32_e32 v55, 0xc038aa3b, v55
	v_exp_f32_e32 v55, v55
	v_mul_f32_e32 v56, v51, v51
	v_add_f32_e32 v51, 1.0, v52
	v_rcp_f32_e32 v52, v51
	v_add_f32_e32 v51, 1.0, v55
	v_rcp_f32_e32 v51, v51
	v_mul_f32_e32 v54, v49, v47
	v_fmac_f32_e32 v56, v54, v54
	v_add_f32_e32 v56, v56, v53
	v_mul_f32_e32 v54, v51, v7
	v_fma_f32 v53, v52, v50, v54
	v_add_f32_e32 v0, v53, v0
	v_lshlrev_b32_e32 v53, 16, v8
	v_mul_f32_e32 v55, 0x3d372713, v53
	v_and_b32_e32 v8, 0xffff0000, v8
	v_mul_f32_e32 v55, v55, v53
	v_mul_f32_e32 v58, 0x3d372713, v8
	v_fma_f32 v55, v55, v53, v53
	v_mul_f32_e32 v58, v58, v8
	v_mul_f32_e32 v55, 0x3f4c422a, v55
	v_fma_f32 v58, v58, v8, v8
	v_mul_f32_e32 v55, 0xc038aa3b, v55
	v_mul_f32_e32 v58, 0x3f4c422a, v58
	v_exp_f32_e32 v55, v55
	v_mul_f32_e32 v58, 0xc038aa3b, v58
	v_exp_f32_e32 v58, v58
	v_mul_f32_e32 v59, v54, v54
	v_add_f32_e32 v54, 1.0, v55
	v_rcp_f32_e32 v55, v54
	v_add_f32_e32 v54, 1.0, v58
	v_rcp_f32_e32 v54, v54
	v_mul_f32_e32 v57, v52, v50
	v_fmac_f32_e32 v59, v57, v57
	v_add_f32_e32 v57, v59, v56
	v_mul_f32_e32 v59, v54, v8
	v_fma_f32 v56, v55, v53, v59
	v_add_f32_e32 v0, v56, v0
	v_lshlrev_b32_e32 v56, 16, v9
	v_mul_f32_e32 v60, 0x3d372713, v56
	v_and_b32_e32 v9, 0xffff0000, v9
	v_mul_f32_e32 v60, v60, v56
	v_mul_f32_e32 v61, 0x3d372713, v9
	v_fma_f32 v60, v60, v56, v56
	v_mul_f32_e32 v61, v61, v9
	v_mul_f32_e32 v60, 0x3f4c422a, v60
	v_fma_f32 v61, v61, v9, v9
	v_mul_f32_e32 v60, 0xc038aa3b, v60
	v_mul_f32_e32 v61, 0x3f4c422a, v61
; __device__ __forceinline__ float gelu_tanh(float x) { const float z = 0.7978845608028654f * (x + 0.044715f * x * x * x); return x * frcp(1.f + fexp2(-2.f * LOG2E * z)); }
; __device__ __forceinline__ void sgu_unit(LAS unsigned char* lds, const bfu* PROJ, const bfu* SW  , const float* ln_g, const float* ln_b, const float* sb, bfu* CAT, int s) {
;     ...
;         for (int j = 0; j < 4; ++j) { const float x0 = gelu_tanh(bflo(w[j])), x1 = gelu_tanh(bfhi(w[j])); v[8 * k + 2 * j] = x0; v[8 * k + 2 * j + 1] = x1; a += x0 + x1; a2 += x0 * x0 + x1 * x1; } }
;     red[qd * 128 + sr] = a; red[512 + qd * 128 + sr] = a2;
;     __syncthreads();
;     { const float sm = (red[sr] + red[128 + sr]) + (red[256 + sr] + red[384 + sr]), sq = (red[512 + sr] + red[640 + sr]) + (red[768 + sr] + red[896 + sr]);
;       const float mu = sm * (1.f / 128.f), var = fmaxf(sq * (1.f / 128.f) - mu * mu, 0.f), rstd = 1.f / sqrtf(var + EPS);
;       const float* lg_ = ln_g + g * 128 + qd * 32; const float* lb_ = ln_b + g * 128 + qd * 32;
; #pragma unroll
	v_exp_f32_e32 v60, v60
	v_mul_f32_e32 v61, 0xc038aa3b, v61
	v_exp_f32_e32 v61, v61
	v_mul_f32_e32 v58, v55, v53
	v_add_f32_e32 v60, 1.0, v60
	v_rcp_f32_e32 v69, v60
	v_add_f32_e32 v60, 1.0, v61
	v_rcp_f32_e32 v102, v60
	v_mul_f32_e32 v59, v59, v59
	v_fmac_f32_e32 v59, v58, v58
	v_add_f32_e32 v57, v59, v57
	v_mul_f32_e32 v59, v102, v9
	v_and_b32_e32 v104, 0xffff0000, v2
	v_fma_f32 v60, v69, v56, v59
	v_lshlrev_b32_e32 v103, 16, v2
	v_mul_f32_e32 v2, 0x3d372713, v104
	v_add_f32_e32 v0, v60, v0
	v_mul_f32_e32 v60, 0x3d372713, v103
	v_mul_f32_e32 v2, v2, v104
	v_mul_f32_e32 v60, v60, v103
	v_fma_f32 v2, v2, v104, v104
	v_fma_f32 v60, v60, v103, v103
	v_mul_f32_e32 v2, 0x3f4c422a, v2
	v_mul_f32_e32 v60, 0x3f4c422a, v60
	v_mul_f32_e32 v2, 0xc038aa3b, v2
	v_mul_f32_e32 v60, 0xc038aa3b, v60
	v_exp_f32_e32 v2, v2
	v_exp_f32_e32 v60, v60
	v_mul_f32_e32 v58, v69, v56
	v_mul_f32_e32 v59, v59, v59
	v_add_f32_e32 v2, 1.0, v2
	v_add_f32_e32 v60, 1.0, v60
	v_rcp_f32_e32 v106, v2
	v_rcp_f32_e32 v105, v60
	v_fmac_f32_e32 v59, v58, v58
	v_and_b32_e32 v108, 0xffff0000, v3
	v_mul_f32_e32 v58, v106, v104
	v_add_f32_e32 v2, v59, v57
	v_fma_f32 v59, v105, v103, v58
	v_lshlrev_b32_e32 v107, 16, v3
	v_mul_f32_e32 v3, 0x3d372713, v108
	v_add_f32_e32 v0, v59, v0
	v_mul_f32_e32 v59, 0x3d372713, v107
	v_mul_f32_e32 v3, v3, v108
	v_mul_f32_e32 v59, v59, v107
	v_fma_f32 v3, v3, v108, v108
	v_fma_f32 v59, v59, v107, v107
	v_mul_f32_e32 v3, 0x3f4c422a, v3
	v_mul_f32_e32 v59, 0x3f4c422a, v59
	v_mul_f32_e32 v3, 0xc038aa3b, v3
	v_mul_f32_e32 v59, 0xc038aa3b, v59
	v_exp_f32_e32 v3, v3
	v_exp_f32_e32 v59, v59
	v_mul_f32_e32 v57, v105, v103
	v_mul_f32_e32 v58, v58, v58
	v_add_f32_e32 v3, 1.0, v3
	v_add_f32_e32 v59, 1.0, v59
	v_rcp_f32_e32 v110, v3
	v_rcp_f32_e32 v109, v59
	v_fmac_f32_e32 v58, v57, v57
	v_and_b32_e32 v112, 0xffff0000, v4
	v_mul_f32_e32 v57, v110, v108
	v_add_f32_e32 v2, v58, v2
	v_fma_f32 v58, v109, v107, v57
	v_lshlrev_b32_e32 v111, 16, v4
	v_mul_f32_e32 v4, 0x3d372713, v112
	v_add_f32_e32 v0, v58, v0
	v_mul_f32_e32 v58, 0x3d372713, v111
	v_mul_f32_e32 v4, v4, v112
	v_mul_f32_e32 v58, v58, v111
	v_fma_f32 v4, v4, v112, v112
	v_fma_f32 v58, v58, v111, v111
	v_mul_f32_e32 v4, 0x3f4c422a, v4
	v_mul_f32_e32 v58, 0x3f4c422a, v58
	v_mul_f32_e32 v4, 0xc038aa3b, v4
	v_mul_f32_e32 v58, 0xc038aa3b, v58
	v_exp_f32_e32 v4, v4
	v_exp_f32_e32 v58, v58
	v_mul_f32_e32 v3, v109, v107
	v_mul_f32_e32 v57, v57, v57
	v_add_f32_e32 v4, 1.0, v4
	v_add_f32_e32 v58, 1.0, v58
	v_rcp_f32_e32 v114, v4
	v_rcp_f32_e32 v113, v58
	v_fmac_f32_e32 v57, v3, v3
	v_add_f32_e32 v2, v57, v2
	v_mul_f32_e32 v4, v114, v112
	v_fma_f32 v57, v113, v111, v4
	v_and_b32_e32 v115, 0xffff0000, v5
	v_add_f32_e32 v0, v57, v0
	v_lshlrev_b32_e32 v57, 16, v5
	v_mul_f32_e32 v5, 0x3d372713, v115
	v_mul_f32_e32 v58, 0x3d372713, v57
	v_mul_f32_e32 v5, v5, v115
	v_mul_f32_e32 v58, v58, v57
	v_fma_f32 v5, v5, v115, v115
	v_fma_f32 v58, v58, v57, v57
	v_mul_f32_e32 v5, 0x3f4c422a, v5
	v_mul_f32_e32 v58, 0x3f4c422a, v58
	v_mul_f32_e32 v5, 0xc038aa3b, v5
	v_mul_f32_e32 v58, 0xc038aa3b, v58
	v_exp_f32_e32 v5, v5
	v_exp_f32_e32 v58, v58
	v_mul_f32_e32 v3, v113, v111
	v_mul_f32_e32 v4, v4, v4
	v_add_f32_e32 v5, 1.0, v5
	v_add_f32_e32 v58, 1.0, v58
	v_rcp_f32_e32 v117, v5
	v_rcp_f32_e32 v116, v58
	v_fmac_f32_e32 v4, v3, v3
	v_add_f32_e32 v2, v4, v2
	v_mul_f32_e32 v4, v117, v115
	v_mul_f32_e32 v3, v116, v57
	v_fma_f32 v5, v116, v57, v4
	v_mul_f32_e32 v4, v4, v4
	v_fmac_f32_e32 v4, v3, v3
	v_add_f32_e32 v0, v5, v0
	v_add_f32_e32 v2, v4, v2
	v_lshl_add_u32 v4, v16, 2, s70
	v_and_b32_e32 v3, 0x3fffff80, v16
	ds_write_b32 v4, v0
	v_lshl_add_u32 v0, v18, 2, s70
	v_lshl_add_u32 v3, v3, 2, v0
	ds_write_b32 v3, v2 offset:2048
	v_lshlrev_b64 v[2:3], 2, v[14:15]
	v_lshl_add_u64 v[4:5], s[22:23], 0, v[2:3]
	s_add_u32 s22, s35, s41
	s_addc_u32 s23, s40, 0
	v_lshl_add_u64 v[66:67], s[22:23], 0, v[2:3]
	s_waitcnt lgkmcnt(0)
	s_barrier
	global_load_dwordx4 v[58:61], v[66:67], off
	global_load_dwordx4 v[62:65], v[4:5], off
	global_load_dwordx4 v[70:73], v[4:5], off offset:16
	ds_read2st64_b32 v[2:3], v0 offset1:2
	ds_read2st64_b32 v[78:79], v0 offset0:4 offset1:6
	global_load_dwordx4 v[74:77], v[66:67], off offset:16
	ds_read2st64_b32 v[80:81], v0 offset0:8 offset1:10
	ds_read2st64_b32 v[82:83], v0 offset0:12 offset1:14
	s_brev_b32 s22, 60
	s_waitcnt lgkmcnt(3)
	v_add_f32_e32 v0, v2, v3
	s_waitcnt lgkmcnt(2)
	v_add_f32_e32 v2, v78, v79
	v_add_f32_e32 v0, v0, v2
	s_waitcnt lgkmcnt(1)
	v_add_f32_e32 v2, v80, v81
	s_waitcnt lgkmcnt(0)
	v_add_f32_e32 v3, v82, v83
	v_mul_f32_e32 v15, 0x3c000000, v0
	v_add_f32_e32 v2, v2, v3
	v_mul_f32_e32 v0, v15, v15
	v_fma_f32 v0, v2, s22, -v0
	v_max_f32_e32 v0, 0, v0
	v_add_f32_e32 v0, 0x358637bd, v0
	v_mul_f32_e32 v2, 0x4f800000, v0
	v_cmp_gt_f32_e32 vcc, s68, v0
	s_nop 1
	v_cndmask_b32_e32 v0, v0, v2, vcc
	v_sqrt_f32_e32 v2, v0
	s_nop 0
	v_add_u32_e32 v3, -1, v2
	v_fma_f32 v78, -v3, v2, v0
	v_cmp_ge_f32_e64 s[40:41], 0, v78
	global_load_dwordx4 v[78:81], v[4:5], off offset:32
	global_load_dwordx4 v[82:85], v[66:67], off offset:32
	v_add_u32_e32 v86, 1, v2
	v_cndmask_b32_e64 v3, v2, v3, s[40:41]
	v_fma_f32 v2, -v86, v2, v0
	v_cmp_lt_f32_e64 s[40:41], 0, v2
	s_nop 1
	v_cndmask_b32_e64 v2, v3, v86, s[40:41]
	v_mul_f32_e32 v3, 0x37800000, v2
	v_cndmask_b32_e32 v2, v2, v3, vcc
	v_cmp_class_f32_e32 vcc, v0, v234
	global_load_dwordx4 v[86:89], v[4:5], off offset:48
	global_load_dwordx4 v[90:93], v[66:67], off offset:48
	v_cndmask_b32_e32 v0, v2, v0, vcc
	v_div_scale_f32 v2, s[22:23], v0, v0, 1.0
	v_rcp_f32_e32 v3, v2
	v_readfirstlane_b32 s22, v16
	s_ashr_i32 s22, s22, 2
	v_fma_f32 v94, -v2, v3, 1.0
	v_fmac_f32_e32 v3, v94, v3
	v_div_scale_f32 v94, vcc, 1.0, v0, 1.0
	v_mul_f32_e32 v95, v94, v3
	v_fma_f32 v96, -v2, v95, v94
	v_fmac_f32_e32 v95, v96, v3
	v_fma_f32 v2, -v2, v95, v94
	v_div_fmas_f32 v2, v2, v3, v95
	v_div_fixup_f32 v118, v2, v0, 1.0
	v_fma_f32 v2, v41, v25, -v15
	v_mul_f32_e32 v2, v2, v118
	v_lshl_add_u32 v0, v18, 1, 0
	s_waitcnt vmcnt(6)
; __device__ __forceinline__ unsigned f2bf(float f) { unsigned u = __builtin_bit_cast(unsigned, f); return (u + 0x7fffu + ((u >> 16) & 1u)) >> 16; }
; __device__ __forceinline__ void sgu_unit(LAS unsigned char* lds, const bfu* PROJ, const bfu* SW  , const float* ln_g, const float* ln_b, const float* sb, bfu* CAT, int s) {
;     ...
;     { const float sm = (red[sr] + red[128 + sr]) + (red[256 + sr] + red[384 + sr]), sq = (red[512 + sr] + red[640 + sr]) + (red[768 + sr] + red[896 + sr]);
;       const float mu = sm * (1.f / 128.f), var = fmaxf(sq * (1.f / 128.f) - mu * mu, 0.f), rstd = 1.f / sqrtf(var + EPS);
;       const float* lg_ = ln_g + g * 128 + qd * 32; const float* lb_ = ln_b + g * 128 + qd * 32;
; #pragma unroll
;       for (int k = 0; k < 32; ++k) Vt[(qd * 32 + k) * TS + sr] = (bfu)f2bf((v[k] - mu) * rstd * lg_[k] + lb_[k]); }
;     __syncthreads();
	v_fma_f32 v2, v62, v2, v58
	v_bfe_u32 v3, v2, 16, 1
	v_add3_u32 v18, v2, v3, s71
	v_mad_u64_u32 v[2:3], s[40:41], v14, s65, v[0:1]
	v_fma_f32 v3, v40, v26, -v15
	v_mul_f32_e32 v3, v3, v118
	v_fma_f32 v3, v63, v3, v59
	v_bfe_u32 v14, v3, 16, 1
	v_add3_u32 v3, v3, v14, s71
	ds_write_b16_d16_hi v2, v3 offset:35088
	v_fma_f32 v3, v38, v28, -v15
	v_mul_f32_e32 v3, v3, v118
	v_fma_f32 v3, v64, v3, v60
	v_bfe_u32 v14, v3, 16, 1
	v_add3_u32 v3, v3, v14, s71
	ds_write_b16_d16_hi v2, v3 offset:35360
	v_fma_f32 v3, v35, v31, -v15
	v_mul_f32_e32 v3, v3, v118
	v_fmac_f32_e32 v61, v3, v65
	ds_write_b16_d16_hi v2, v18 offset:34816
	v_bfe_u32 v3, v61, 16, 1
	v_add3_u32 v3, v61, v3, s71
	global_load_dwordx4 v[58:61], v[4:5], off offset:80
	global_load_dwordx4 v[62:65], v[4:5], off offset:64
	global_load_dwordx4 v[94:97], v[66:67], off offset:80
	global_load_dwordx4 v[98:101], v[66:67], off offset:64
	ds_write_b16_d16_hi v2, v3 offset:35632
	v_fma_f32 v3, v22, v19, -v15
	v_mul_f32_e32 v3, v3, v118
	s_waitcnt vmcnt(8)
	v_fma_f32 v3, v3, v70, v74
	v_bfe_u32 v14, v3, 16, 1
	v_add3_u32 v3, v3, v14, s71
	ds_write_b16_d16_hi v2, v3 offset:35904
	v_fma_f32 v3, v21, v20, -v15
	v_mul_f32_e32 v3, v3, v118
	v_fma_f32 v3, v3, v71, v75
	v_bfe_u32 v14, v3, 16, 1
	v_add3_u32 v3, v3, v14, s71
	ds_write_b16_d16_hi v2, v3 offset:36176
	v_fma_f32 v3, v29, v23, -v15
	v_mul_f32_e32 v3, v3, v118
	v_fma_f32 v3, v3, v72, v76
	v_bfe_u32 v14, v3, 16, 1
	v_add3_u32 v3, v3, v14, s71
	ds_write_b16_d16_hi v2, v3 offset:36448
	v_fma_f32 v3, v27, v24, -v15
	v_mul_f32_e32 v3, v3, v118
	v_fmac_f32_e32 v77, v3, v73
	v_bfe_u32 v3, v77, 16, 1
	v_add3_u32 v3, v77, v3, s71
	ds_write_b16_d16_hi v2, v3 offset:36720
	v_fma_f32 v3, v33, v30, -v15
	v_mul_f32_e32 v3, v3, v118
	s_waitcnt vmcnt(6)
	v_fma_f32 v3, v3, v78, v82
	v_bfe_u32 v14, v3, 16, 1
	v_add3_u32 v3, v3, v14, s71
	ds_write_b16_d16_hi v2, v3 offset:36992
	v_fma_f32 v3, v32, v10, -v15
	v_mul_f32_e32 v3, v3, v118
	v_fma_f32 v3, v3, v79, v83
	v_bfe_u32 v10, v3, 16, 1
	v_add3_u32 v3, v3, v10, s71
	ds_write_b16_d16_hi v2, v3 offset:37264
	v_fma_f32 v3, v39, v34, -v15
	v_mul_f32_e32 v3, v3, v118
	v_fma_f32 v3, v3, v80, v84
	v_bfe_u32 v10, v3, 16, 1
	v_add3_u32 v3, v3, v10, s71
	ds_write_b16_d16_hi v2, v3 offset:37536
	global_load_dwordx4 v[18:21], v[4:5], off offset:112
	global_load_dwordx4 v[22:25], v[4:5], off offset:96
	global_load_dwordx4 v[26:29], v[66:67], off offset:112
	global_load_dwordx4 v[30:33], v[66:67], off offset:96
	v_fma_f32 v3, v36, v11, -v15
	v_mul_f32_e32 v3, v3, v118
	v_fmac_f32_e32 v85, v3, v81
	v_bfe_u32 v3, v85, 16, 1
	v_add3_u32 v3, v85, v3, s71
	ds_write_b16_d16_hi v2, v3 offset:37808
	v_fma_f32 v3, v43, v37, -v15
	v_mul_f32_e32 v3, v3, v118
	s_waitcnt vmcnt(8)
	v_fma_f32 v3, v3, v86, v90
	v_bfe_u32 v4, v3, 16, 1
	v_add3_u32 v3, v3, v4, s71
	ds_write_b16_d16_hi v2, v3 offset:38080
	v_fma_f32 v3, v42, v12, -v15
	v_mul_f32_e32 v3, v3, v118
	v_fma_f32 v3, v3, v87, v91
	v_bfe_u32 v4, v3, 16, 1
	v_add3_u32 v3, v3, v4, s71
	ds_write_b16_d16_hi v2, v3 offset:38352
	v_fma_f32 v3, v46, v44, -v15
	v_mul_f32_e32 v3, v3, v118
	v_fma_f32 v3, v3, v88, v92
	v_bfe_u32 v4, v3, 16, 1
	v_add3_u32 v3, v3, v4, s71
	ds_write_b16_d16_hi v2, v3 offset:38624
	v_fma_f32 v3, v45, v13, -v15
	v_mul_f32_e32 v3, v3, v118
	v_fmac_f32_e32 v93, v3, v89
	v_bfe_u32 v3, v93, 16, 1
	v_add3_u32 v3, v93, v3, s71
	ds_write_b16_d16_hi v2, v3 offset:38896
	v_fma_f32 v3, v49, v47, -v15
	v_mul_f32_e32 v3, v3, v118
	v_bfi_b32 v14, -16, s22, v16
	s_waitcnt vmcnt(4)
	v_fma_f32 v3, v3, v62, v98
	v_bfe_u32 v4, v3, 16, 1
	v_add3_u32 v3, v3, v4, s71
	ds_write_b16_d16_hi v2, v3 offset:39168
	v_fma_f32 v3, v48, v6, -v15
	v_mul_f32_e32 v3, v3, v118
	v_fma_f32 v3, v3, v63, v99
	v_bfe_u32 v4, v3, 16, 1
	v_add3_u32 v3, v3, v4, s71
	ds_write_b16_d16_hi v2, v3 offset:39440
	v_fma_f32 v3, v52, v50, -v15
	v_mul_f32_e32 v3, v3, v118
	v_fma_f32 v3, v3, v64, v100
	v_bfe_u32 v4, v3, 16, 1
	v_add3_u32 v3, v3, v4, s71
	ds_write_b16_d16_hi v2, v3 offset:39712
	v_fma_f32 v3, v51, v7, -v15
	v_mul_f32_e32 v3, v3, v118
	v_fmac_f32_e32 v101, v3, v65
	v_bfe_u32 v3, v101, 16, 1
	v_add3_u32 v3, v101, v3, s71
	ds_write_b16_d16_hi v2, v3 offset:39984
	v_fma_f32 v3, v55, v53, -v15
	v_mul_f32_e32 v3, v3, v118
	v_fma_f32 v3, v3, v58, v94
	v_bfe_u32 v4, v3, 16, 1
	v_add3_u32 v3, v3, v4, s71
	ds_write_b16_d16_hi v2, v3 offset:40256
	v_fma_f32 v3, v54, v8, -v15
	v_mul_f32_e32 v3, v3, v118
	v_fma_f32 v3, v3, v59, v95
	v_bfe_u32 v4, v3, 16, 1
	v_add3_u32 v3, v3, v4, s71
	ds_write_b16_d16_hi v2, v3 offset:40528
	v_fma_f32 v3, v69, v56, -v15
	v_mul_f32_e32 v3, v3, v118
	v_fma_f32 v3, v3, v60, v96
	v_bfe_u32 v4, v3, 16, 1
	v_add3_u32 v3, v3, v4, s71
	ds_write_b16_d16_hi v2, v3 offset:40800
	v_fma_f32 v3, v102, v9, -v15
	v_mul_f32_e32 v3, v3, v118
	v_fmac_f32_e32 v97, v3, v61
	v_bfe_u32 v3, v97, 16, 1
	v_add3_u32 v3, v97, v3, s71
	ds_write_b16_d16_hi v2, v3 offset:41072
	v_fma_f32 v3, v105, v103, -v15
	v_mul_f32_e32 v3, v3, v118
	s_waitcnt vmcnt(0)
	v_fma_f32 v3, v3, v22, v30
	v_bfe_u32 v4, v3, 16, 1
	v_add3_u32 v3, v3, v4, s71
	ds_write_b16_d16_hi v2, v3 offset:41344
	v_fma_f32 v3, v106, v104, -v15
	v_mul_f32_e32 v3, v3, v118
	v_fma_f32 v3, v3, v23, v31
	v_bfe_u32 v4, v3, 16, 1
	v_add3_u32 v3, v3, v4, s71
	ds_write_b16_d16_hi v2, v3 offset:41616
	v_fma_f32 v3, v109, v107, -v15
	v_mul_f32_e32 v3, v3, v118
	v_fma_f32 v3, v3, v24, v32
	v_bfe_u32 v4, v3, 16, 1
	v_add3_u32 v3, v3, v4, s71
	ds_write_b16_d16_hi v2, v3 offset:41888
	v_fma_f32 v3, v110, v108, -v15
	v_mul_f32_e32 v3, v3, v118
	v_fmac_f32_e32 v33, v3, v25
	v_bfe_u32 v3, v33, 16, 1
	v_add3_u32 v3, v33, v3, s71
	ds_write_b16_d16_hi v2, v3 offset:42160
	v_fma_f32 v3, v113, v111, -v15
	v_mul_f32_e32 v3, v3, v118
	v_fma_f32 v3, v3, v18, v26
	v_bfe_u32 v4, v3, 16, 1
	v_add3_u32 v3, v3, v4, s71
	ds_write_b16_d16_hi v2, v3 offset:42432
	v_fma_f32 v3, v114, v112, -v15
	v_mul_f32_e32 v3, v3, v118
	v_fma_f32 v3, v3, v19, v27
	v_bfe_u32 v4, v3, 16, 1
	v_add3_u32 v3, v3, v4, s71
	ds_write_b16_d16_hi v2, v3 offset:42704
	v_fma_f32 v3, v116, v57, -v15
	v_mul_f32_e32 v3, v3, v118
	v_fma_f32 v3, v3, v20, v28
	v_bfe_u32 v4, v3, 16, 1
	v_add3_u32 v3, v3, v4, s71
	ds_write_b16_d16_hi v2, v3 offset:42976
	v_fma_f32 v2, v117, v115, -v15
	v_mul_f32_e32 v2, v2, v118
	v_fmac_f32_e32 v29, v2, v21
	v_bfe_u32 v2, v29, 16, 1
	v_add3_u32 v4, v29, v2, s71
	v_or_b32_e32 v2, 31, v17
	v_mad_u64_u32 v[2:3], s[40:41], v2, s65, v[0:1]
	v_ashrrev_i32_e32 v15, 31, v14
	ds_write_b16_d16_hi v2, v4 offset:34816
	v_lshl_add_u64 v[32:33], v[14:15], 0, s[52:53]
	v_mov_b64_e32 v[2:3], s[44:45]
	v_bfe_u32 v4, v16, 4, 2
	v_mad_i64_i32 v[2:3], s[22:23], v32, s61, v[2:3]
	v_lshlrev_b32_e32 v0, 3, v4
	v_lshl_add_u64 v[2:3], v[2:3], 0, s[20:21]
	v_lshl_add_u64 v[34:35], v[2:3], 0, v[0:1]
	v_add_co_u32_e32 v2, vcc, s56, v34
	s_waitcnt lgkmcnt(0)
	s_nop 0
	v_addc_co_u32_e32 v3, vcc, 0, v35, vcc
	s_barrier
; #define LAS __attribute__((address_space(3)))
; __device__ __forceinline__ unsigned pk2(float lo, float hi) { return pg8::cvt_pk_bf16(lo, hi); }
; __device__ __forceinline__ float gelu_tanh(float x) { const float z = 0.7978845608028654f * (x + 0.044715f * x * x * x); return x * frcp(1.f + fexp2(-2.f * LOG2E * z)); }
; #define ZERO8(a) do { _Pragma("unroll") for (int t_ = 0; t_ < 8; ++t_) a[t_] = (f32x4){0.f, 0.f, 0.f, 0.f}; } while (0)
; __device__ __forceinline__ void wave_mma(f32x4 (&acc)[8], const LAS bfu* As, const LAS bfu* Bs, int m0, int fr, int fq) {
;     ...
;     for (int ks = 0; ks < 4; ++ks) { const bf16x8 a = *(const LAS bf16x8*)(As + (m0 + fr) * TS + ks * 32 + fq * 8);
; #pragma unroll
;         for (int t = 0; t < 8; ++t) { const bf16x8 b = *(const LAS bf16x8*)(Bs + (t * 16 + fr) * TS + ks * 32 + fq * 8); acc[t] = __builtin_amdgcn_mfma_f32_16x16x32_bf16(b, a, acc[t], 0, 0, 0); } }
; __device__ __forceinline__ void sgu_unit(LAS unsigned char* lds, const bfu* PROJ, const bfu* SW  , const float* ln_g, const float* ln_b, const float* sb, bfu* CAT, int s) {
;     ...
;     const int fr = lane & 15, fq = lane >> 4, m0 = wid * 16, t_ = m0 + fr; f32x4 acc[8]; ZERO8(acc);
;     wave_mma(acc, Ws, Vt, m0, fr, fq);
;     const float bias = sb[g * 128 + t_];
;     const bfu* up = PROJ + (row0 + t_) * INW + C_SU + g * 128 + 4 * fq; bfu* op = CAT + (row0 + t_) * DM + 1536 + g * 128 + 4 * fq;
; #pragma unroll
;     for (int t = 0; t < 8; ++t) { const v2u uw = *(const v2u*)(up + 16 * t);
;         v2u w; w.x = pk2(gelu_tanh(bflo(uw.x)) * (acc[t][0] + bias), gelu_tanh(bfhi(uw.x)) * (acc[t][1] + bias)); w.y = pk2(gelu_tanh(bflo(uw.y)) * (acc[t][2] + bias), gelu_tanh(bfhi(uw.y)) * (acc[t][3] + bias));
;         *(v2u*)(op + 16 * t) = w; }
	global_load_dwordx2 v[170:171], v[2:3], off offset:2560
	s_waitcnt lgkmcnt(0)
	v_and_b32_e32 v2, 15, v16
	v_lshl_add_u32 v6, v4, 4, 0
	v_mad_u32_u24 v19, v2, s65, v6
	ds_read_b128 v[44:47], v19 offset:34816
	ds_read_b128 v[48:51], v19 offset:34880
	v_mad_u64_u32 v[38:39], s[22:23], v14, s65, v[6:7]
	ds_read_b128 v[52:55], v38
	ds_read_b128 v[56:59], v38 offset:64
	ds_read_b128 v[60:63], v19 offset:34944
	ds_read_b128 v[64:67], v38 offset:128
	ds_read_b128 v[72:75], v19 offset:35008
	ds_read_b128 v[76:79], v38 offset:192
	ds_read_b128 v[80:83], v19 offset:39168
	ds_read_b128 v[84:87], v19 offset:39232
	ds_read_b128 v[88:91], v19 offset:39296
	ds_read_b128 v[92:95], v19 offset:39360
	ds_read_b128 v[96:99], v19 offset:43520
	s_waitcnt lgkmcnt(10)
	v_mfma_f32_16x16x32_bf16 v[2:5], v[44:47], v[52:55], 0
	v_lshl_add_u32 v28, s34, 7, v14
	v_ashrrev_i32_e32 v29, 31, v28
	v_lshl_add_u64 v[40:41], v[28:29], 2, s[50:51]
	ds_read_b128 v[44:47], v19 offset:43584
	s_waitcnt lgkmcnt(10)
	v_mfma_f32_16x16x32_bf16 v[20:23], v[48:51], v[56:59], v[2:5]
	s_nop 1
	global_load_dword v18, v[40:41], off
	s_mov_b64 s[22:23], 0x2a00
	ds_read_b128 v[48:51], v19 offset:43648
	ds_read_b128 v[100:103], v19 offset:43712
	s_waitcnt lgkmcnt(10)
	v_mfma_f32_16x16x32_bf16 v[20:23], v[60:63], v[64:67], v[20:23]
	v_lshlrev_b64 v[26:27], 12, v[32:33]
	v_lshl_add_u64 v[26:27], s[46:47], 0, v[26:27]
	v_lshl_add_u64 v[26:27], v[26:27], 0, s[20:21]
	ds_read_b128 v[60:63], v19 offset:47872
	s_waitcnt lgkmcnt(9)
	v_mfma_f32_16x16x32_bf16 v[22:25], v[72:75], v[76:79], v[20:23]
	ds_read_b128 v[72:75], v19 offset:47936
	s_mov_b32 s20, 0x29600000
	s_waitcnt vmcnt(1)
	v_lshlrev_b32_e32 v28, 16, v170
	v_mul_f32_e32 v30, 0x3d372713, v28
	v_mul_f32_e32 v30, v30, v28
	v_mov_b32_e32 v31, v28
	v_and_b32_e32 v29, 0xffff0000, v170
	v_fmac_f32_e32 v31, v30, v31
	v_mul_f32_e32 v30, 0x3f4c422a, v31
	v_mul_f32_e32 v31, 0x3d372713, v29
	v_mul_f32_e32 v31, v31, v29
	v_mov_b32_e32 v32, v29
	v_fmac_f32_e32 v32, v31, v32
	v_mul_f32_e32 v30, 0xc038aa3b, v30
	v_mul_f32_e32 v31, 0x3f4c422a, v32
	v_exp_f32_e32 v30, v30
	v_mul_f32_e32 v31, 0xc038aa3b, v31
	v_exp_f32_e32 v31, v31
	v_lshl_add_u64 v[20:21], v[34:35], 0, s[22:23]
	global_load_dwordx2 v[172:173], v[20:21], off offset:32
	global_load_dwordx2 v[174:175], v[20:21], off offset:64
	global_load_dwordx2 v[176:177], v[20:21], off offset:96
	global_load_dwordx2 v[178:179], v[20:21], off offset:128
	global_load_dwordx2 v[180:181], v[20:21], off offset:160
	global_load_dwordx2 v[182:183], v[20:21], off offset:192
	global_load_dwordx2 v[184:185], v[20:21], off offset:224
	v_lshl_add_u64 v[34:35], v[26:27], 0, v[0:1]
	v_add_f32_e32 v0, 1.0, v30
	v_rcp_f32_e32 v26, v0
	v_add_f32_e32 v0, 1.0, v31
	v_lshlrev_b32_e32 v36, 16, v171
	v_rcp_f32_e32 v27, v0
	v_mul_f32_e32 v0, 0x3d372713, v36
	v_mul_f32_e32 v0, v0, v36
	v_mov_b32_e32 v30, v36
	v_and_b32_e32 v37, 0xffff0000, v171
	v_fmac_f32_e32 v30, v0, v30
	v_mul_f32_e32 v0, 0x3f4c422a, v30
	v_mul_f32_e32 v30, 0x3d372713, v37
	v_mul_f32_e32 v30, v30, v37
	v_mov_b32_e32 v31, v37
	v_fmac_f32_e32 v31, v30, v31
	v_mul_f32_e32 v0, 0xc038aa3b, v0
	v_mul_f32_e32 v30, 0x3f4c422a, v31
	v_exp_f32_e32 v0, v0
	v_mul_f32_e32 v30, 0xc038aa3b, v30
	v_exp_f32_e32 v30, v30
	v_pk_mul_f32 v[38:39], v[26:27], v[28:29]
	v_add_f32_e32 v0, 1.0, v0
	v_rcp_f32_e32 v40, v0
	v_add_f32_e32 v0, 1.0, v30
	v_rcp_f32_e32 v41, v0
	s_waitcnt vmcnt(0)
	v_pk_add_f32 v[22:23], v[22:23], v[18:19] op_sel_hi:[1,0]
	s_mov_b64 s[22:23], 0x29600c00
	v_pk_mul_f32 v[22:23], v[22:23], v[38:39]
	v_pk_mul_f32 v[36:37], v[40:41], v[36:37]
	v_cvt_pk_bf16_f32 v38, v22, v23
	v_pk_add_f32 v[40:41], v[24:25], v[18:19] op_sel_hi:[1,0]
	s_waitcnt lgkmcnt(9)
	v_mfma_f32_16x16x32_bf16 v[22:25], v[80:83], v[52:55], 0
	ds_read_b128 v[80:83], v19 offset:48000
	v_pk_mul_f32 v[36:37], v[40:41], v[36:37]
	s_waitcnt lgkmcnt(9)
	v_mfma_f32_16x16x32_bf16 v[22:25], v[84:87], v[56:59], v[22:25]
	ds_read_b128 v[84:87], v19 offset:48064
	v_add_co_u32_e32 v30, vcc, s20, v34
	v_cvt_pk_bf16_f32 v39, v36, v37
	s_nop 0
	v_addc_co_u32_e32 v31, vcc, 0, v35, vcc
	global_store_dwordx2 v[30:31], v[38:39], off offset:3072
	s_waitcnt lgkmcnt(9)
	v_mfma_f32_16x16x32_bf16 v[22:25], v[88:91], v[64:67], v[22:25]
	ds_read_b128 v[88:91], v19 offset:52224
	s_waitcnt lgkmcnt(9)
	v_mfma_f32_16x16x32_bf16 v[24:27], v[92:95], v[76:79], v[22:25]
	ds_read_b128 v[92:95], v19 offset:52288
	s_waitcnt vmcnt(0)
	v_lshlrev_b32_e32 v30, 16, v172
	v_mul_f32_e32 v0, 0x3d372713, v30
	v_mul_f32_e32 v0, v0, v30
	s_nop 0
	v_mov_b32_e32 v22, v30
	v_and_b32_e32 v31, 0xffff0000, v172
	v_fmac_f32_e32 v22, v0, v22
	v_mul_f32_e32 v0, 0x3f4c422a, v22
	v_mul_f32_e32 v22, 0x3d372713, v31
	v_mul_f32_e32 v22, v22, v31
	v_mov_b32_e32 v23, v31
	v_fmac_f32_e32 v23, v22, v23
	v_mul_f32_e32 v0, 0xc038aa3b, v0
	v_mul_f32_e32 v22, 0x3f4c422a, v23
	v_exp_f32_e32 v0, v0
	v_mul_f32_e32 v22, 0xc038aa3b, v22
	v_exp_f32_e32 v28, v22
	v_lshl_add_u64 v[22:23], v[34:35], 0, s[22:23]
	v_add_f32_e32 v0, 1.0, v0
	v_rcp_f32_e32 v32, v0
	v_add_f32_e32 v0, 1.0, v28
	v_lshlrev_b32_e32 v34, 16, v173
	v_rcp_f32_e32 v33, v0
	v_mul_f32_e32 v0, 0x3d372713, v34
	v_mul_f32_e32 v0, v0, v34
	v_mov_b32_e32 v28, v34
	v_and_b32_e32 v35, 0xffff0000, v173
	v_fmac_f32_e32 v28, v0, v28
	v_mul_f32_e32 v0, 0x3f4c422a, v28
	v_mul_f32_e32 v28, 0x3d372713, v35
	v_mul_f32_e32 v28, v28, v35
	v_mov_b32_e32 v29, v35
	v_fmac_f32_e32 v29, v28, v29
	v_mul_f32_e32 v0, 0xc038aa3b, v0
	v_mul_f32_e32 v28, 0x3f4c422a, v29
	v_exp_f32_e32 v0, v0
	v_mul_f32_e32 v28, 0xc038aa3b, v28
	v_exp_f32_e32 v28, v28
	v_pk_mul_f32 v[32:33], v[32:33], v[30:31]
	v_add_f32_e32 v0, 1.0, v0
	v_rcp_f32_e32 v36, v0
	v_add_f32_e32 v0, 1.0, v28
	v_rcp_f32_e32 v37, v0
	v_pk_add_f32 v[24:25], v[24:25], v[18:19] op_sel_hi:[1,0]
	v_pk_add_f32 v[26:27], v[26:27], v[18:19] op_sel_hi:[1,0]
	v_pk_mul_f32 v[24:25], v[24:25], v[32:33]
	v_pk_mul_f32 v[32:33], v[36:37], v[34:35]
	v_cvt_pk_bf16_f32 v24, v24, v25
	v_pk_mul_f32 v[26:27], v[26:27], v[32:33]
	v_cvt_pk_bf16_f32 v25, v26, v27
	global_store_dwordx2 v[22:23], v[24:25], off offset:32
	s_waitcnt lgkmcnt(9)
; #define LAS __attribute__((address_space(3)))
; __device__ __forceinline__ unsigned pk2(float lo, float hi) { return pg8::cvt_pk_bf16(lo, hi); }
; __device__ __forceinline__ float gelu_tanh(float x) { const float z = 0.7978845608028654f * (x + 0.044715f * x * x * x); return x * frcp(1.f + fexp2(-2.f * LOG2E * z)); }
; #define ZERO8(a) do { _Pragma("unroll") for (int t_ = 0; t_ < 8; ++t_) a[t_] = (f32x4){0.f, 0.f, 0.f, 0.f}; } while (0)
; __device__ __forceinline__ void wave_mma(f32x4 (&acc)[8], const LAS bfu* As, const LAS bfu* Bs, int m0, int fr, int fq) {
;     ...
;     for (int ks = 0; ks < 4; ++ks) { const bf16x8 a = *(const LAS bf16x8*)(As + (m0 + fr) * TS + ks * 32 + fq * 8);
; #pragma unroll
;         for (int t = 0; t < 8; ++t) { const bf16x8 b = *(const LAS bf16x8*)(Bs + (t * 16 + fr) * TS + ks * 32 + fq * 8); acc[t] = __builtin_amdgcn_mfma_f32_16x16x32_bf16(b, a, acc[t], 0, 0, 0); } }
; __device__ __forceinline__ void sgu_unit(LAS unsigned char* lds, const bfu* PROJ, const bfu* SW  , const float* ln_g, const float* ln_b, const float* sb, bfu* CAT, int s) {
;     ...
;     const int fr = lane & 15, fq = lane >> 4, m0 = wid * 16, t_ = m0 + fr; f32x4 acc[8]; ZERO8(acc);
;     wave_mma(acc, Ws, Vt, m0, fr, fq);
;     const float bias = sb[g * 128 + t_];
;     const bfu* up = PROJ + (row0 + t_) * INW + C_SU + g * 128 + 4 * fq; bfu* op = CAT + (row0 + t_) * DM + 1536 + g * 128 + 4 * fq;
; #pragma unroll
;     for (int t = 0; t < 8; ++t) { const v2u uw = *(const v2u*)(up + 16 * t);
;         v2u w; w.x = pk2(gelu_tanh(bflo(uw.x)) * (acc[t][0] + bias), gelu_tanh(bfhi(uw.x)) * (acc[t][1] + bias)); w.y = pk2(gelu_tanh(bflo(uw.y)) * (acc[t][2] + bias), gelu_tanh(bfhi(uw.y)) * (acc[t][3] + bias));
;         *(v2u*)(op + 16 * t) = w; }
	v_mfma_f32_16x16x32_bf16 v[28:31], v[96:99], v[52:55], 0
	ds_read_b128 v[96:99], v19 offset:52352
	s_waitcnt lgkmcnt(9)
	v_mfma_f32_16x16x32_bf16 v[24:27], v[44:47], v[56:59], v[28:31]
	ds_read_b128 v[44:47], v19 offset:52416
	s_nop 5
	s_waitcnt lgkmcnt(9)
	v_mfma_f32_16x16x32_bf16 v[24:27], v[48:51], v[64:67], v[24:27]
	ds_read_b128 v[48:51], v19 offset:56576
	s_waitcnt vmcnt(0)
	v_lshlrev_b32_e32 v28, 16, v174
	v_mul_f32_e32 v0, 0x3d372713, v28
	v_mul_f32_e32 v0, v0, v28
	v_mov_b32_e32 v30, v28
	v_and_b32_e32 v29, 0xffff0000, v174
	v_fmac_f32_e32 v30, v0, v30
	v_mul_f32_e32 v0, 0x3f4c422a, v30
	v_mul_f32_e32 v30, 0x3d372713, v29
	v_mul_f32_e32 v30, v30, v29
	v_mov_b32_e32 v31, v29
	v_fmac_f32_e32 v31, v30, v31
	v_mul_f32_e32 v0, 0xc038aa3b, v0
	v_mul_f32_e32 v30, 0x3f4c422a, v31
	v_exp_f32_e32 v0, v0
	v_mul_f32_e32 v30, 0xc038aa3b, v30
	v_exp_f32_e32 v31, v30
	s_waitcnt lgkmcnt(9)
	v_mfma_f32_16x16x32_bf16 v[24:27], v[100:103], v[76:79], v[24:27]
	ds_read_b128 v[100:103], v19 offset:56640
	v_add_f32_e32 v0, 1.0, v0
	v_rcp_f32_e32 v30, v0
	v_add_f32_e32 v0, 1.0, v31
	v_lshlrev_b32_e32 v32, 16, v175
	v_rcp_f32_e32 v31, v0
	v_mul_f32_e32 v0, 0x3d372713, v32
	v_mul_f32_e32 v0, v0, v32
	v_mov_b32_e32 v34, v32
	v_and_b32_e32 v33, 0xffff0000, v175
	v_fmac_f32_e32 v34, v0, v34
	v_mul_f32_e32 v0, 0x3f4c422a, v34
	v_mul_f32_e32 v34, 0x3d372713, v33
	v_mul_f32_e32 v34, v34, v33
	v_mov_b32_e32 v35, v33
	v_fmac_f32_e32 v35, v34, v35
	v_mul_f32_e32 v0, 0xc038aa3b, v0
	v_mul_f32_e32 v34, 0x3f4c422a, v35
	v_exp_f32_e32 v0, v0
	v_mul_f32_e32 v34, 0xc038aa3b, v34
	v_exp_f32_e32 v37, v34
	v_pk_mul_f32 v[34:35], v[30:31], v[28:29]
	v_add_f32_e32 v0, 1.0, v0
	v_rcp_f32_e32 v36, v0
	v_add_f32_e32 v0, 1.0, v37
	v_rcp_f32_e32 v37, v0
	v_pk_add_f32 v[24:25], v[24:25], v[18:19] op_sel_hi:[1,0]
	v_pk_add_f32 v[26:27], v[26:27], v[18:19] op_sel_hi:[1,0]
	v_pk_mul_f32 v[24:25], v[24:25], v[34:35]
	v_pk_mul_f32 v[32:33], v[36:37], v[32:33]
	v_cvt_pk_bf16_f32 v24, v24, v25
	v_pk_mul_f32 v[26:27], v[26:27], v[32:33]
	v_cvt_pk_bf16_f32 v25, v26, v27
	global_store_dwordx2 v[22:23], v[24:25], off offset:64
	s_waitcnt lgkmcnt(9)
	v_mfma_f32_16x16x32_bf16 v[28:31], v[60:63], v[52:55], 0
	ds_read_b128 v[60:63], v19 offset:56704
	s_waitcnt lgkmcnt(9)
	v_mfma_f32_16x16x32_bf16 v[24:27], v[72:75], v[56:59], v[28:31]
	ds_read_b128 v[72:75], v19 offset:56768
	s_nop 5
	s_waitcnt lgkmcnt(9)
	v_mfma_f32_16x16x32_bf16 v[24:27], v[80:83], v[64:67], v[24:27]
	ds_read_b128 v[80:83], v19 offset:60928
	s_waitcnt vmcnt(0)
	v_lshlrev_b32_e32 v28, 16, v176
	v_mul_f32_e32 v0, 0x3d372713, v28
	v_mul_f32_e32 v0, v0, v28
	v_mov_b32_e32 v30, v28
	v_and_b32_e32 v29, 0xffff0000, v176
	v_fmac_f32_e32 v30, v0, v30
	v_mul_f32_e32 v0, 0x3f4c422a, v30
	v_mul_f32_e32 v30, 0x3d372713, v29
	v_mul_f32_e32 v30, v30, v29
	v_mov_b32_e32 v31, v29
	v_fmac_f32_e32 v31, v30, v31
	v_mul_f32_e32 v0, 0xc038aa3b, v0
	v_mul_f32_e32 v30, 0x3f4c422a, v31
	v_exp_f32_e32 v0, v0
	v_mul_f32_e32 v30, 0xc038aa3b, v30
	v_exp_f32_e32 v31, v30
	s_waitcnt lgkmcnt(9)
	v_mfma_f32_16x16x32_bf16 v[24:27], v[84:87], v[76:79], v[24:27]
	ds_read_b128 v[84:87], v19 offset:60992
	v_add_f32_e32 v0, 1.0, v0
	v_rcp_f32_e32 v30, v0
	v_add_f32_e32 v0, 1.0, v31
	v_lshlrev_b32_e32 v32, 16, v177
	v_rcp_f32_e32 v31, v0
	v_mul_f32_e32 v0, 0x3d372713, v32
	v_mul_f32_e32 v0, v0, v32
	v_mov_b32_e32 v34, v32
	v_and_b32_e32 v33, 0xffff0000, v177
	v_fmac_f32_e32 v34, v0, v34
	v_mul_f32_e32 v0, 0x3f4c422a, v34
	v_mul_f32_e32 v34, 0x3d372713, v33
	v_mul_f32_e32 v34, v34, v33
	v_mov_b32_e32 v35, v33
	v_fmac_f32_e32 v35, v34, v35
	v_mul_f32_e32 v0, 0xc038aa3b, v0
	v_mul_f32_e32 v34, 0x3f4c422a, v35
	v_exp_f32_e32 v0, v0
	v_mul_f32_e32 v34, 0xc038aa3b, v34
	v_exp_f32_e32 v37, v34
	v_pk_mul_f32 v[34:35], v[30:31], v[28:29]
	v_add_f32_e32 v0, 1.0, v0
	v_rcp_f32_e32 v36, v0
	v_add_f32_e32 v0, 1.0, v37
	v_rcp_f32_e32 v37, v0
	v_pk_add_f32 v[24:25], v[24:25], v[18:19] op_sel_hi:[1,0]
	v_pk_add_f32 v[26:27], v[26:27], v[18:19] op_sel_hi:[1,0]
	v_pk_mul_f32 v[24:25], v[24:25], v[34:35]
	v_pk_mul_f32 v[32:33], v[36:37], v[32:33]
	v_cvt_pk_bf16_f32 v24, v24, v25
	v_pk_mul_f32 v[26:27], v[26:27], v[32:33]
	v_cvt_pk_bf16_f32 v25, v26, v27
	global_store_dwordx2 v[22:23], v[24:25], off offset:96
	s_waitcnt lgkmcnt(9)
	v_mfma_f32_16x16x32_bf16 v[28:31], v[88:91], v[52:55], 0
	ds_read_b128 v[88:91], v19 offset:61056
	s_waitcnt lgkmcnt(9)
	v_mfma_f32_16x16x32_bf16 v[24:27], v[92:95], v[56:59], v[28:31]
	ds_read_b128 v[92:95], v19 offset:61120
	s_nop 5
	s_waitcnt lgkmcnt(9)
	v_mfma_f32_16x16x32_bf16 v[24:27], v[96:99], v[64:67], v[24:27]
	ds_read_b128 v[96:99], v19 offset:65280
	s_waitcnt vmcnt(0)
	v_lshlrev_b32_e32 v28, 16, v178
	v_mul_f32_e32 v0, 0x3d372713, v28
	v_mul_f32_e32 v0, v0, v28
	v_mov_b32_e32 v30, v28
	v_and_b32_e32 v29, 0xffff0000, v178
	v_fmac_f32_e32 v30, v0, v30
	v_mul_f32_e32 v0, 0x3f4c422a, v30
	v_mul_f32_e32 v30, 0x3d372713, v29
	v_mul_f32_e32 v30, v30, v29
	v_mov_b32_e32 v31, v29
	v_fmac_f32_e32 v31, v30, v31
	v_mul_f32_e32 v0, 0xc038aa3b, v0
	v_mul_f32_e32 v30, 0x3f4c422a, v31
	v_exp_f32_e32 v0, v0
	v_mul_f32_e32 v30, 0xc038aa3b, v30
	v_exp_f32_e32 v31, v30
	s_waitcnt lgkmcnt(9)
; #define LAS __attribute__((address_space(3)))
; __device__ __forceinline__ unsigned pk2(float lo, float hi) { return pg8::cvt_pk_bf16(lo, hi); }
; __device__ __forceinline__ float gelu_tanh(float x) { const float z = 0.7978845608028654f * (x + 0.044715f * x * x * x); return x * frcp(1.f + fexp2(-2.f * LOG2E * z)); }
; #define ZERO8(a) do { _Pragma("unroll") for (int t_ = 0; t_ < 8; ++t_) a[t_] = (f32x4){0.f, 0.f, 0.f, 0.f}; } while (0)
; __device__ __forceinline__ void wave_mma(f32x4 (&acc)[8], const LAS bfu* As, const LAS bfu* Bs, int m0, int fr, int fq) {
;     ...
;     for (int ks = 0; ks < 4; ++ks) { const bf16x8 a = *(const LAS bf16x8*)(As + (m0 + fr) * TS + ks * 32 + fq * 8);
; #pragma unroll
;         for (int t = 0; t < 8; ++t) { const bf16x8 b = *(const LAS bf16x8*)(Bs + (t * 16 + fr) * TS + ks * 32 + fq * 8); acc[t] = __builtin_amdgcn_mfma_f32_16x16x32_bf16(b, a, acc[t], 0, 0, 0); } }
; __device__ __forceinline__ void sgu_unit(LAS unsigned char* lds, const bfu* PROJ, const bfu* SW  , const float* ln_g, const float* ln_b, const float* sb, bfu* CAT, int s) {
;     ...
;     const int fr = lane & 15, fq = lane >> 4, m0 = wid * 16, t_ = m0 + fr; f32x4 acc[8]; ZERO8(acc);
;     wave_mma(acc, Ws, Vt, m0, fr, fq);
;     const float bias = sb[g * 128 + t_];
;     const bfu* up = PROJ + (row0 + t_) * INW + C_SU + g * 128 + 4 * fq; bfu* op = CAT + (row0 + t_) * DM + 1536 + g * 128 + 4 * fq;
; #pragma unroll
;     for (int t = 0; t < 8; ++t) { const v2u uw = *(const v2u*)(up + 16 * t);
;         v2u w; w.x = pk2(gelu_tanh(bflo(uw.x)) * (acc[t][0] + bias), gelu_tanh(bfhi(uw.x)) * (acc[t][1] + bias)); w.y = pk2(gelu_tanh(bflo(uw.y)) * (acc[t][2] + bias), gelu_tanh(bfhi(uw.y)) * (acc[t][3] + bias));
;         *(v2u*)(op + 16 * t) = w; }
	v_mfma_f32_16x16x32_bf16 v[24:27], v[44:47], v[76:79], v[24:27]
	ds_read_b128 v[44:47], v19 offset:65344
	v_add_f32_e32 v0, 1.0, v0
	v_rcp_f32_e32 v30, v0
	v_add_f32_e32 v0, 1.0, v31
	v_lshlrev_b32_e32 v32, 16, v179
	v_rcp_f32_e32 v31, v0
	v_mul_f32_e32 v0, 0x3d372713, v32
	v_mul_f32_e32 v0, v0, v32
	v_mov_b32_e32 v34, v32
	v_and_b32_e32 v33, 0xffff0000, v179
	v_fmac_f32_e32 v34, v0, v34
	v_mul_f32_e32 v0, 0x3f4c422a, v34
	v_mul_f32_e32 v34, 0x3d372713, v33
	v_mul_f32_e32 v34, v34, v33
	v_mov_b32_e32 v35, v33
	v_fmac_f32_e32 v35, v34, v35
	v_mul_f32_e32 v0, 0xc038aa3b, v0
	v_mul_f32_e32 v34, 0x3f4c422a, v35
	v_exp_f32_e32 v0, v0
	v_mul_f32_e32 v34, 0xc038aa3b, v34
	v_exp_f32_e32 v37, v34
	v_pk_mul_f32 v[34:35], v[30:31], v[28:29]
	v_add_f32_e32 v0, 1.0, v0
	v_rcp_f32_e32 v36, v0
	v_add_f32_e32 v0, 1.0, v37
	v_rcp_f32_e32 v37, v0
	v_pk_add_f32 v[24:25], v[24:25], v[18:19] op_sel_hi:[1,0]
	v_pk_add_f32 v[26:27], v[26:27], v[18:19] op_sel_hi:[1,0]
	v_pk_mul_f32 v[24:25], v[24:25], v[34:35]
	v_pk_mul_f32 v[32:33], v[36:37], v[32:33]
	v_cvt_pk_bf16_f32 v24, v24, v25
	v_pk_mul_f32 v[26:27], v[26:27], v[32:33]
	v_cvt_pk_bf16_f32 v25, v26, v27
	global_store_dwordx2 v[22:23], v[24:25], off offset:128
	s_waitcnt lgkmcnt(9)
	v_mfma_f32_16x16x32_bf16 v[28:31], v[48:51], v[52:55], 0
	ds_read_b128 v[48:51], v19 offset:65408
	s_waitcnt lgkmcnt(9)
	v_mfma_f32_16x16x32_bf16 v[24:27], v[100:103], v[56:59], v[28:31]
	ds_read_b128 v[100:103], v19 offset:65472
	s_nop 5
	s_waitcnt lgkmcnt(9)
	v_mfma_f32_16x16x32_bf16 v[24:27], v[60:63], v[64:67], v[24:27]
	s_waitcnt vmcnt(0)
	v_lshlrev_b32_e32 v28, 16, v180
	v_mul_f32_e32 v0, 0x3d372713, v28
	v_mul_f32_e32 v0, v0, v28
	v_mov_b32_e32 v30, v28
	v_and_b32_e32 v29, 0xffff0000, v180
	v_fmac_f32_e32 v30, v0, v30
	v_mul_f32_e32 v0, 0x3f4c422a, v30
	v_mul_f32_e32 v30, 0x3d372713, v29
	v_mul_f32_e32 v30, v30, v29
	v_mov_b32_e32 v31, v29
	v_fmac_f32_e32 v31, v30, v31
	v_mul_f32_e32 v0, 0xc038aa3b, v0
	v_mul_f32_e32 v30, 0x3f4c422a, v31
	v_exp_f32_e32 v0, v0
	v_mul_f32_e32 v30, 0xc038aa3b, v30
	v_exp_f32_e32 v31, v30
	s_waitcnt lgkmcnt(8)
	v_mfma_f32_16x16x32_bf16 v[24:27], v[72:75], v[76:79], v[24:27]
	v_add_f32_e32 v0, 1.0, v0
	v_rcp_f32_e32 v30, v0
	v_add_f32_e32 v0, 1.0, v31
	v_lshlrev_b32_e32 v32, 16, v181
	v_rcp_f32_e32 v31, v0
	v_mul_f32_e32 v0, 0x3d372713, v32
	v_mul_f32_e32 v0, v0, v32
	v_mov_b32_e32 v34, v32
	v_and_b32_e32 v33, 0xffff0000, v181
	v_fmac_f32_e32 v34, v0, v34
	v_mul_f32_e32 v0, 0x3f4c422a, v34
	v_mul_f32_e32 v34, 0x3d372713, v33
	v_mul_f32_e32 v34, v34, v33
	v_mov_b32_e32 v35, v33
	v_fmac_f32_e32 v35, v34, v35
	v_mul_f32_e32 v0, 0xc038aa3b, v0
	v_mul_f32_e32 v34, 0x3f4c422a, v35
	v_exp_f32_e32 v0, v0
	v_mul_f32_e32 v34, 0xc038aa3b, v34
	v_exp_f32_e32 v37, v34
	v_pk_mul_f32 v[34:35], v[30:31], v[28:29]
	v_add_f32_e32 v0, 1.0, v0
	v_rcp_f32_e32 v36, v0
	v_add_f32_e32 v0, 1.0, v37
	v_rcp_f32_e32 v37, v0
	v_pk_add_f32 v[24:25], v[24:25], v[18:19] op_sel_hi:[1,0]
	v_pk_add_f32 v[26:27], v[26:27], v[18:19] op_sel_hi:[1,0]
	v_pk_mul_f32 v[24:25], v[24:25], v[34:35]
	v_pk_mul_f32 v[32:33], v[36:37], v[32:33]
	v_cvt_pk_bf16_f32 v24, v24, v25
	v_pk_mul_f32 v[26:27], v[26:27], v[32:33]
	v_cvt_pk_bf16_f32 v25, v26, v27
	global_store_dwordx2 v[22:23], v[24:25], off offset:160
	s_waitcnt lgkmcnt(7)
	v_mfma_f32_16x16x32_bf16 v[28:31], v[80:83], v[52:55], 0
	s_waitcnt lgkmcnt(6)
	v_mfma_f32_16x16x32_bf16 v[24:27], v[84:87], v[56:59], v[28:31]
	s_nop 5
	s_waitcnt lgkmcnt(5)
	v_mfma_f32_16x16x32_bf16 v[24:27], v[88:91], v[64:67], v[24:27]
	s_waitcnt vmcnt(0)
; __device__ __forceinline__ unsigned pk2(float lo, float hi) { return pg8::cvt_pk_bf16(lo, hi); }
; __device__ __forceinline__ float gelu_tanh(float x) { const float z = 0.7978845608028654f * (x + 0.044715f * x * x * x); return x * frcp(1.f + fexp2(-2.f * LOG2E * z)); }
; #define ZERO8(a) do { _Pragma("unroll") for (int t_ = 0; t_ < 8; ++t_) a[t_] = (f32x4){0.f, 0.f, 0.f, 0.f}; } while (0)
; __device__ __forceinline__ void sgu_unit(LAS unsigned char* lds, const bfu* PROJ, const bfu* SW  , const float* ln_g, const float* ln_b, const float* sb, bfu* CAT, int s) {
;     ...
;     const int fr = lane & 15, fq = lane >> 4, m0 = wid * 16, t_ = m0 + fr; f32x4 acc[8]; ZERO8(acc);
;     wave_mma(acc, Ws, Vt, m0, fr, fq);
;     const float bias = sb[g * 128 + t_];
;     const bfu* up = PROJ + (row0 + t_) * INW + C_SU + g * 128 + 4 * fq; bfu* op = CAT + (row0 + t_) * DM + 1536 + g * 128 + 4 * fq;
; #pragma unroll
;     for (int t = 0; t < 8; ++t) { const v2u uw = *(const v2u*)(up + 16 * t);
;         v2u w; w.x = pk2(gelu_tanh(bflo(uw.x)) * (acc[t][0] + bias), gelu_tanh(bfhi(uw.x)) * (acc[t][1] + bias)); w.y = pk2(gelu_tanh(bflo(uw.y)) * (acc[t][2] + bias), gelu_tanh(bfhi(uw.y)) * (acc[t][3] + bias));
;         *(v2u*)(op + 16 * t) = w; }
;     __syncthreads();
	v_lshlrev_b32_e32 v28, 16, v182
	v_mul_f32_e32 v0, 0x3d372713, v28
	v_mul_f32_e32 v0, v0, v28
	v_mov_b32_e32 v30, v28
	v_and_b32_e32 v29, 0xffff0000, v182
	v_fmac_f32_e32 v30, v0, v30
	v_mul_f32_e32 v0, 0x3f4c422a, v30
	v_mul_f32_e32 v30, 0x3d372713, v29
	v_mul_f32_e32 v30, v30, v29
	v_mov_b32_e32 v31, v29
	v_fmac_f32_e32 v31, v30, v31
	v_mul_f32_e32 v0, 0xc038aa3b, v0
	v_mul_f32_e32 v30, 0x3f4c422a, v31
	v_exp_f32_e32 v0, v0
	v_mul_f32_e32 v30, 0xc038aa3b, v30
	v_exp_f32_e32 v31, v30
	s_waitcnt lgkmcnt(4)
	v_mfma_f32_16x16x32_bf16 v[24:27], v[92:95], v[76:79], v[24:27]
	v_add_f32_e32 v0, 1.0, v0
	v_rcp_f32_e32 v30, v0
	v_add_f32_e32 v0, 1.0, v31
	v_lshlrev_b32_e32 v32, 16, v183
	v_rcp_f32_e32 v31, v0
	v_mul_f32_e32 v0, 0x3d372713, v32
	v_mul_f32_e32 v0, v0, v32
	v_mov_b32_e32 v34, v32
	v_and_b32_e32 v33, 0xffff0000, v183
	v_fmac_f32_e32 v34, v0, v34
	v_mul_f32_e32 v0, 0x3f4c422a, v34
	v_mul_f32_e32 v34, 0x3d372713, v33
	v_mul_f32_e32 v34, v34, v33
	v_mov_b32_e32 v35, v33
	v_fmac_f32_e32 v35, v34, v35
	v_mul_f32_e32 v0, 0xc038aa3b, v0
	v_mul_f32_e32 v34, 0x3f4c422a, v35
	v_exp_f32_e32 v0, v0
	v_mul_f32_e32 v34, 0xc038aa3b, v34
	v_exp_f32_e32 v37, v34
	v_pk_mul_f32 v[34:35], v[30:31], v[28:29]
	v_add_f32_e32 v0, 1.0, v0
	v_rcp_f32_e32 v36, v0
	v_add_f32_e32 v0, 1.0, v37
	v_rcp_f32_e32 v37, v0
	v_pk_add_f32 v[24:25], v[24:25], v[18:19] op_sel_hi:[1,0]
	v_pk_add_f32 v[26:27], v[26:27], v[18:19] op_sel_hi:[1,0]
	v_pk_mul_f32 v[24:25], v[24:25], v[34:35]
	v_pk_mul_f32 v[32:33], v[36:37], v[32:33]
	v_cvt_pk_bf16_f32 v24, v24, v25
	v_pk_mul_f32 v[26:27], v[26:27], v[32:33]
	v_cvt_pk_bf16_f32 v25, v26, v27
	global_store_dwordx2 v[22:23], v[24:25], off offset:192
	s_waitcnt lgkmcnt(3)
	v_mfma_f32_16x16x32_bf16 v[10:13], v[96:99], v[52:55], 0
	s_waitcnt lgkmcnt(2)
	v_mfma_f32_16x16x32_bf16 v[6:9], v[44:47], v[56:59], v[10:13]
	s_nop 5
	s_waitcnt lgkmcnt(1)
	v_mfma_f32_16x16x32_bf16 v[6:9], v[48:51], v[64:67], v[6:9]
	s_waitcnt vmcnt(0)
	v_lshlrev_b32_e32 v10, 16, v184
	v_mul_f32_e32 v0, 0x3d372713, v10
	v_mul_f32_e32 v0, v0, v10
	v_mov_b32_e32 v12, v10
	v_and_b32_e32 v11, 0xffff0000, v184
	v_fmac_f32_e32 v12, v0, v12
	v_mul_f32_e32 v0, 0x3f4c422a, v12
	v_mul_f32_e32 v12, 0x3d372713, v11
	v_mul_f32_e32 v12, v12, v11
	v_mov_b32_e32 v13, v11
	v_fmac_f32_e32 v13, v12, v13
	v_mul_f32_e32 v0, 0xc038aa3b, v0
	v_mul_f32_e32 v12, 0x3f4c422a, v13
	v_exp_f32_e32 v0, v0
	v_mul_f32_e32 v12, 0xc038aa3b, v12
	v_exp_f32_e32 v12, v12
	s_waitcnt lgkmcnt(0)
	v_mfma_f32_16x16x32_bf16 v[2:5], v[100:103], v[76:79], v[6:9]
	v_add_f32_e32 v0, 1.0, v0
	s_waitcnt lgkmcnt(0)
	s_nop 1
	v_rcp_f32_e32 v6, v0
	v_add_f32_e32 v0, 1.0, v12
	v_lshlrev_b32_e32 v8, 16, v185
	v_rcp_f32_e32 v7, v0
	v_mul_f32_e32 v0, 0x3d372713, v8
	v_mul_f32_e32 v0, v0, v8
	v_mov_b32_e32 v12, v8
	v_and_b32_e32 v9, 0xffff0000, v185
	v_fmac_f32_e32 v12, v0, v12
	v_mul_f32_e32 v0, 0x3f4c422a, v12
	v_mul_f32_e32 v12, 0x3d372713, v9
	v_mul_f32_e32 v12, v12, v9
	v_mov_b32_e32 v13, v9
	v_fmac_f32_e32 v13, v12, v13
	v_mul_f32_e32 v0, 0xc038aa3b, v0
	v_mul_f32_e32 v12, 0x3f4c422a, v13
	v_exp_f32_e32 v0, v0
	v_mul_f32_e32 v12, 0xc038aa3b, v12
	v_exp_f32_e32 v12, v12
	v_pk_mul_f32 v[6:7], v[6:7], v[10:11]
	v_add_f32_e32 v0, 1.0, v0
	v_rcp_f32_e32 v10, v0
	v_add_f32_e32 v0, 1.0, v12
	v_rcp_f32_e32 v11, v0
	v_pk_add_f32 v[2:3], v[18:19], v[2:3] op_sel_hi:[0,1]
	v_pk_mul_f32 v[2:3], v[2:3], v[6:7]
	v_pk_add_f32 v[4:5], v[18:19], v[4:5] op_sel_hi:[0,1]
	v_pk_mul_f32 v[6:7], v[10:11], v[8:9]
	v_cvt_pk_bf16_f32 v2, v2, v3
	v_pk_mul_f32 v[4:5], v[4:5], v[6:7]
	s_nop 0
	v_cvt_pk_bf16_f32 v3, v4, v5
	global_store_dwordx2 v[22:23], v[2:3], off offset:224
	s_barrier
	s_cbranch_execnz .LBB0_411
